# v23: v22 + merged vmcnt/lgkmcnt waits in GEMM load segments
# speedup vs baseline: 1.0021x; 1.0021x over previous
; #define PG8_STAGE(bufoff, gbase, voff) do { _Pragma("unroll") for (int _i = 0; _i < 2; ++_i) \
;         __builtin_amdgcn_global_load_lds((const unsigned*)((const char*)(gbase) + (voff)[_i]), (LAS unsigned*)(lds + (bufoff) + ldsw + _i * 8192), 16, 0, 0); } while (0)
; #define PG8_LDA(dst, b, h) do { _Pragma("unroll") for (int m = 0; m < 4; ++m) _Pragma("unroll") for (int k = 0; k < 2; ++k) dst[m][k] = *(const LAS f16x8*)(lds + PG8_SA(b, h) + aoff + m * 2048 + k * 1024); } while (0)
; #define PG8_LDB(dst, b, h) do { _Pragma("unroll") for (int n = 0; n < 2; ++n) _Pragma("unroll") for (int k = 0; k < 2; ++k) dst[n][k] = *(const LAS f16x8*)(lds + PG8_SB(b, h) + boff + n * 2048 + k * 1024); } while (0)
; #define PG8_MMA(ai, bj, At, Bt) do { __builtin_amdgcn_s_setprio(1); _Pragma("unroll") for (int m = 0; m < 4; ++m) _Pragma("unroll") for (int n = 0; n < 2; ++n) _Pragma("unroll") for (int k = 0; k < 2; ++k) \
;         acc[ai][bj][m][n] = mma16_<Epi::BF16>(Bt[n][k], At[m][k], acc[ai][bj][m][n]); __builtin_amdgcn_s_setprio(0); } while (0)
; #define PG8_WAIT_V(n) asm volatile("s_waitcnt vmcnt(" #n ")" ::: "memory")
; #define PG8_WAIT_L(n) asm volatile("s_waitcnt lgkmcnt(" #n ")" ::: "memory")
; #define PG8_BAR __builtin_amdgcn_s_barrier()
; #define PG8_SCHED __builtin_amdgcn_sched_barrier(0)
;     ...
;             const char* a1 = cA + (size_t)(t + 1) * kstep;
;             const char* a2 = last ? nA : cA + (size_t)(t + 2) * kstep; const char* b2 = last ? nB : cB + (size_t)(t + 2) * kstep;
;             const char* a3 = a2 + kstep; const char* b3 = b2 + kstep;
;             if constexpr (SP2) {
;             PG8_LDB(B0, 0, 0); PG8_LDB(B1, 0, 1); PG8_SCHED; PG8_LDA(At, 0, 0); PG8_STAGE(PG8_SA(1, 1), a1 + hA, voffA);
;             PG8_WAIT_V(8); PG8_WAIT_L(0); PG8_BAR; PG8_MMA(0, 0, At, B0); PG8_MMA(0, 1, At, B1); PG8_BAR; PG8_SCHED;
;             PG8_LDA(At, 0, 1); PG8_STAGE(PG8_SB(0, 0), b2, voffB); PG8_STAGE(PG8_SB(0, 1), b2 + hB, voffB); PG8_STAGE(PG8_SA(0, 0), a2, voffA);
;             PG8_WAIT_V(8); PG8_WAIT_L(0); PG8_BAR; if (!cur.half) { PG8_MMA(1, 0, At, B0); PG8_MMA(1, 1, At, B1); } PG8_BAR; PG8_SCHED;
.LBB0_157:
	s_add_u32 s28, s26, 0xfffc0080
	s_addc_u32 s29, s27, -1
	s_add_i32 s50, 0, 0x10000
	s_cmp_eq_u32 s49, 12
	s_cselect_b32 s31, s2, s29
	s_cselect_b32 s30, s3, s28
	s_cselect_b32 s29, s11, s48
	s_cselect_b32 s28, s19, s47
	s_add_i32 s52, 0, 0x14000
	v_add_u32_e32 v156, s50, v141
	v_add_u32_e32 v172, s52, v141
	ds_read_b128 v[144:147], v156
	ds_read_b128 v[148:151], v156 offset:1024
	ds_read_b128 v[152:155], v156 offset:2048
	ds_read_b128 v[156:159], v156 offset:3072
	ds_read_b128 v[160:163], v172
	ds_read_b128 v[164:167], v172 offset:1024
	ds_read_b128 v[168:171], v172 offset:2048
	ds_read_b128 v[172:175], v172 offset:3072
	s_add_i32 m0, s25, 0xc000
	ds_read_b128 v[176:179], v143
	ds_read_b128 v[180:183], v143 offset:1024
	ds_read_b128 v[184:187], v143 offset:2048
	ds_read_b128 v[188:191], v143 offset:3072
	ds_read_b128 v[192:195], v143 offset:4096
	ds_read_b128 v[214:217], v143 offset:5120
	ds_read_b128 v[218:221], v143 offset:6144
	ds_read_b128 v[222:225], v143 offset:7168
	global_load_lds_dwordx4 v136, s[26:27]
	s_add_i32 m0, s25, 0xe000
	s_nop 0
	global_load_lds_dwordx4 v138, s[26:27]
	s_waitcnt vmcnt(8) lgkmcnt(0)
	s_barrier
	s_setprio 1
	v_mfma_f32_16x16x32_bf16 v[126:129], v[144:147], v[176:179], v[126:129]
	v_mfma_f32_16x16x32_bf16 v[118:121], v[152:155], v[176:179], v[118:121]
	v_mfma_f32_16x16x32_bf16 v[110:113], v[144:147], v[184:187], v[110:113]
	v_mfma_f32_16x16x32_bf16 v[102:105], v[152:155], v[184:187], v[102:105]
	v_mfma_f32_16x16x32_bf16 v[94:97], v[144:147], v[192:195], v[94:97]
	v_mfma_f32_16x16x32_bf16 v[86:89], v[152:155], v[192:195], v[86:89]
	v_mfma_f32_16x16x32_bf16 v[78:81], v[144:147], v[218:221], v[78:81]
	v_mfma_f32_16x16x32_bf16 v[70:73], v[152:155], v[218:221], v[70:73]
	v_mfma_f32_16x16x32_bf16 v[126:129], v[148:151], v[180:183], v[126:129]
	v_mfma_f32_16x16x32_bf16 v[118:121], v[156:159], v[180:183], v[118:121]
	v_mfma_f32_16x16x32_bf16 v[110:113], v[148:151], v[188:191], v[110:113]
	v_mfma_f32_16x16x32_bf16 v[102:105], v[156:159], v[188:191], v[102:105]
	v_mfma_f32_16x16x32_bf16 v[94:97], v[148:151], v[214:217], v[94:97]
	v_mfma_f32_16x16x32_bf16 v[86:89], v[156:159], v[214:217], v[86:89]
	v_mfma_f32_16x16x32_bf16 v[78:81], v[148:151], v[222:225], v[78:81]
	v_mfma_f32_16x16x32_bf16 v[70:73], v[156:159], v[222:225], v[70:73]
	s_setprio 0
	s_setprio 1
	v_mfma_f32_16x16x32_bf16 v[122:125], v[160:163], v[176:179], v[122:125]
	v_mfma_f32_16x16x32_bf16 v[114:117], v[168:171], v[176:179], v[114:117]
	v_mfma_f32_16x16x32_bf16 v[106:109], v[160:163], v[184:187], v[106:109]
	v_mfma_f32_16x16x32_bf16 v[98:101], v[168:171], v[184:187], v[98:101]
	v_mfma_f32_16x16x32_bf16 v[90:93], v[160:163], v[192:195], v[90:93]
	v_mfma_f32_16x16x32_bf16 v[82:85], v[168:171], v[192:195], v[82:85]
	v_mfma_f32_16x16x32_bf16 v[74:77], v[160:163], v[218:221], v[74:77]
	v_mfma_f32_16x16x32_bf16 v[66:69], v[168:171], v[218:221], v[66:69]
	v_mfma_f32_16x16x32_bf16 v[122:125], v[164:167], v[180:183], v[122:125]
	v_mfma_f32_16x16x32_bf16 v[114:117], v[172:175], v[180:183], v[114:117]
	v_mfma_f32_16x16x32_bf16 v[106:109], v[164:167], v[188:191], v[106:109]
	v_mfma_f32_16x16x32_bf16 v[98:101], v[172:175], v[188:191], v[98:101]
	v_mfma_f32_16x16x32_bf16 v[90:93], v[164:167], v[214:217], v[90:93]
	v_mfma_f32_16x16x32_bf16 v[82:85], v[172:175], v[214:217], v[82:85]
	v_mfma_f32_16x16x32_bf16 v[74:77], v[164:167], v[222:225], v[74:77]
	v_mfma_f32_16x16x32_bf16 v[66:69], v[172:175], v[222:225], v[66:69]
	s_setprio 0
	s_barrier
	s_add_i32 s50, s50, s34
	s_mov_b32 m0, s50
	ds_read_b128 v[176:179], v143 offset:16384
	ds_read_b128 v[180:183], v143 offset:17408
	ds_read_b128 v[184:187], v143 offset:18432
	ds_read_b128 v[188:191], v143 offset:19456
	ds_read_b128 v[192:195], v143 offset:20480
	ds_read_b128 v[214:217], v143 offset:21504
	ds_read_b128 v[218:221], v143 offset:22528
	ds_read_b128 v[222:225], v143 offset:23552
	global_load_lds_dwordx4 v0, s[28:29]
	s_add_i32 m0, s50, 0x2000
	s_add_u32 s50, s28, 0x40000
	s_addc_u32 s51, s29, 0
	s_add_i32 s52, s52, s34
	global_load_lds_dwordx4 v130, s[28:29]
	s_mov_b32 m0, s52
	s_nop 0
	global_load_lds_dwordx4 v0, s[50:51]
	s_add_i32 m0, s52, 0x2000
	s_nop 0
	global_load_lds_dwordx4 v130, s[50:51]
	s_mov_b32 m0, s25
	s_nop 0
	global_load_lds_dwordx4 v134, s[30:31]
	s_mov_b32 m0, s36
	s_nop 0
	global_load_lds_dwordx4 v132, s[30:31]
	s_waitcnt vmcnt(8) lgkmcnt(0)
	s_barrier
	s_setprio 1
	v_mfma_f32_16x16x32_bf16 v[62:65], v[144:147], v[176:179], v[62:65]
	v_mfma_f32_16x16x32_bf16 v[54:57], v[152:155], v[176:179], v[54:57]
	v_mfma_f32_16x16x32_bf16 v[46:49], v[144:147], v[184:187], v[46:49]
	v_mfma_f32_16x16x32_bf16 v[38:41], v[152:155], v[184:187], v[38:41]
	v_mfma_f32_16x16x32_bf16 v[30:33], v[144:147], v[192:195], v[30:33]
	v_mfma_f32_16x16x32_bf16 v[22:25], v[152:155], v[192:195], v[22:25]
	v_mfma_f32_16x16x32_bf16 v[14:17], v[144:147], v[218:221], v[14:17]
	v_mfma_f32_16x16x32_bf16 v[6:9], v[152:155], v[218:221], v[6:9]
	v_mfma_f32_16x16x32_bf16 v[62:65], v[148:151], v[180:183], v[62:65]
	v_mfma_f32_16x16x32_bf16 v[54:57], v[156:159], v[180:183], v[54:57]
	v_mfma_f32_16x16x32_bf16 v[46:49], v[148:151], v[188:191], v[46:49]
	v_mfma_f32_16x16x32_bf16 v[38:41], v[156:159], v[188:191], v[38:41]
	v_mfma_f32_16x16x32_bf16 v[30:33], v[148:151], v[214:217], v[30:33]
	v_mfma_f32_16x16x32_bf16 v[22:25], v[156:159], v[214:217], v[22:25]
	v_mfma_f32_16x16x32_bf16 v[14:17], v[148:151], v[222:225], v[14:17]
	v_mfma_f32_16x16x32_bf16 v[6:9], v[156:159], v[222:225], v[6:9]
	s_setprio 0
	s_setprio 1
	v_mfma_f32_16x16x32_bf16 v[58:61], v[160:163], v[176:179], v[58:61]
	v_mfma_f32_16x16x32_bf16 v[50:53], v[168:171], v[176:179], v[50:53]
	v_mfma_f32_16x16x32_bf16 v[42:45], v[160:163], v[184:187], v[42:45]
	v_mfma_f32_16x16x32_bf16 v[34:37], v[168:171], v[184:187], v[34:37]
	v_mfma_f32_16x16x32_bf16 v[26:29], v[160:163], v[192:195], v[26:29]
	v_mfma_f32_16x16x32_bf16 v[18:21], v[168:171], v[192:195], v[18:21]
	v_mfma_f32_16x16x32_bf16 v[10:13], v[160:163], v[218:221], v[10:13]
	v_mfma_f32_16x16x32_bf16 v[2:5], v[168:171], v[218:221], v[2:5]
	v_mfma_f32_16x16x32_bf16 v[58:61], v[164:167], v[180:183], v[58:61]
	v_mfma_f32_16x16x32_bf16 v[50:53], v[172:175], v[180:183], v[50:53]
	v_mfma_f32_16x16x32_bf16 v[42:45], v[164:167], v[188:191], v[42:45]
	v_mfma_f32_16x16x32_bf16 v[34:37], v[172:175], v[188:191], v[34:37]
	v_mfma_f32_16x16x32_bf16 v[26:29], v[164:167], v[214:217], v[26:29]
	v_mfma_f32_16x16x32_bf16 v[18:21], v[172:175], v[214:217], v[18:21]
	v_mfma_f32_16x16x32_bf16 v[10:13], v[164:167], v[222:225], v[10:13]
	v_mfma_f32_16x16x32_bf16 v[2:5], v[172:175], v[222:225], v[2:5]
	s_setprio 0
	s_barrier
; #define PG8_STAGE(bufoff, gbase, voff) do { _Pragma("unroll") for (int _i = 0; _i < 2; ++_i) \
;         __builtin_amdgcn_global_load_lds((const unsigned*)((const char*)(gbase) + (voff)[_i]), (LAS unsigned*)(lds + (bufoff) + ldsw + _i * 8192), 16, 0, 0); } while (0)
; #define PG8_LDA(dst, b, h) do { _Pragma("unroll") for (int m = 0; m < 4; ++m) _Pragma("unroll") for (int k = 0; k < 2; ++k) dst[m][k] = *(const LAS f16x8*)(lds + PG8_SA(b, h) + aoff + m * 2048 + k * 1024); } while (0)
; #define PG8_LDB(dst, b, h) do { _Pragma("unroll") for (int n = 0; n < 2; ++n) _Pragma("unroll") for (int k = 0; k < 2; ++k) dst[n][k] = *(const LAS f16x8*)(lds + PG8_SB(b, h) + boff + n * 2048 + k * 1024); } while (0)
; #define PG8_MMA(ai, bj, At, Bt) do { __builtin_amdgcn_s_setprio(1); _Pragma("unroll") for (int m = 0; m < 4; ++m) _Pragma("unroll") for (int n = 0; n < 2; ++n) _Pragma("unroll") for (int k = 0; k < 2; ++k) \
;         acc[ai][bj][m][n] = mma16_<Epi::BF16>(Bt[n][k], At[m][k], acc[ai][bj][m][n]); __builtin_amdgcn_s_setprio(0); } while (0)
; #define PG8_WAIT_V(n) asm volatile("s_waitcnt vmcnt(" #n ")" ::: "memory")
; #define PG8_WAIT_L(n) asm volatile("s_waitcnt lgkmcnt(" #n ")" ::: "memory")
; #define PG8_BAR __builtin_amdgcn_s_barrier()
; #define PG8_SCHED __builtin_amdgcn_sched_barrier(0)
;     ...
;             PG8_LDB(B0, 1, 0); PG8_LDB(B1, 1, 1); PG8_SCHED; PG8_LDA(At, 1, 0); PG8_STAGE(PG8_SA(0, 1), a2 + hA, voffA);
;             PG8_WAIT_V(8); PG8_WAIT_L(0); PG8_BAR; PG8_MMA(0, 0, At, B0); PG8_MMA(0, 1, At, B1); PG8_BAR; PG8_SCHED;
;             PG8_LDA(At, 1, 1); PG8_STAGE(PG8_SB(1, 0), b3, voffB); PG8_STAGE(PG8_SB(1, 1), b3 + hB, voffB); PG8_STAGE(PG8_SA(1, 0), a3, voffA);
;             PG8_WAIT_V(8); PG8_WAIT_L(0); PG8_BAR; if (!cur.half) { PG8_MMA(1, 0, At, B0); PG8_MMA(1, 1, At, B1); } PG8_BAR; PG8_SCHED;
;     ...
;         if constexpr (ALIGN_EPI) { if (wr == 0) PG8_BAR; }
	s_add_i32 s50, 0, 0x18000
	s_add_i32 s51, 0, 0x1c000
	v_add_u32_e32 v156, s50, v141
	v_add_u32_e32 v172, s51, v141
	ds_read_b128 v[144:147], v156
	ds_read_b128 v[148:151], v156 offset:1024
	ds_read_b128 v[152:155], v156 offset:2048
	ds_read_b128 v[156:159], v156 offset:3072
	ds_read_b128 v[160:163], v172
	ds_read_b128 v[164:167], v172 offset:1024
	ds_read_b128 v[168:171], v172 offset:2048
	ds_read_b128 v[172:175], v172 offset:3072
	s_add_u32 s30, s30, 0x40000
	s_addc_u32 s31, s31, 0
	s_add_u32 s98, s30, 0xfffc0080
	s_addc_u32 s99, s31, -1
	s_mov_b32 m0, s37
	ds_read_b128 v[176:179], v143 offset:32768
	ds_read_b128 v[180:183], v143 offset:33792
	ds_read_b128 v[184:187], v143 offset:34816
	ds_read_b128 v[188:191], v143 offset:35840
	ds_read_b128 v[192:195], v143 offset:36864
	ds_read_b128 v[214:217], v143 offset:37888
	ds_read_b128 v[218:221], v143 offset:38912
	ds_read_b128 v[222:225], v143 offset:39936
	global_load_lds_dwordx4 v134, s[30:31]
	s_mov_b32 m0, s40
	s_nop 0
	global_load_lds_dwordx4 v132, s[30:31]
	s_waitcnt vmcnt(8) lgkmcnt(0)
	s_barrier
	s_setprio 1
	v_mfma_f32_16x16x32_bf16 v[126:129], v[144:147], v[176:179], v[126:129]
	v_mfma_f32_16x16x32_bf16 v[118:121], v[152:155], v[176:179], v[118:121]
	v_mfma_f32_16x16x32_bf16 v[110:113], v[144:147], v[184:187], v[110:113]
	v_mfma_f32_16x16x32_bf16 v[102:105], v[152:155], v[184:187], v[102:105]
	v_mfma_f32_16x16x32_bf16 v[94:97], v[144:147], v[192:195], v[94:97]
	v_mfma_f32_16x16x32_bf16 v[86:89], v[152:155], v[192:195], v[86:89]
	v_mfma_f32_16x16x32_bf16 v[78:81], v[144:147], v[218:221], v[78:81]
	v_mfma_f32_16x16x32_bf16 v[70:73], v[152:155], v[218:221], v[70:73]
	v_mfma_f32_16x16x32_bf16 v[126:129], v[148:151], v[180:183], v[126:129]
	v_mfma_f32_16x16x32_bf16 v[118:121], v[156:159], v[180:183], v[118:121]
	v_mfma_f32_16x16x32_bf16 v[110:113], v[148:151], v[188:191], v[110:113]
	v_mfma_f32_16x16x32_bf16 v[102:105], v[156:159], v[188:191], v[102:105]
	v_mfma_f32_16x16x32_bf16 v[94:97], v[148:151], v[214:217], v[94:97]
	v_mfma_f32_16x16x32_bf16 v[86:89], v[156:159], v[214:217], v[86:89]
	v_mfma_f32_16x16x32_bf16 v[78:81], v[148:151], v[222:225], v[78:81]
	v_mfma_f32_16x16x32_bf16 v[70:73], v[156:159], v[222:225], v[70:73]
	s_setprio 0
	s_setprio 1
	v_mfma_f32_16x16x32_bf16 v[122:125], v[160:163], v[176:179], v[122:125]
	v_mfma_f32_16x16x32_bf16 v[114:117], v[168:171], v[176:179], v[114:117]
	v_mfma_f32_16x16x32_bf16 v[106:109], v[160:163], v[184:187], v[106:109]
	v_mfma_f32_16x16x32_bf16 v[98:101], v[168:171], v[184:187], v[98:101]
	v_mfma_f32_16x16x32_bf16 v[90:93], v[160:163], v[192:195], v[90:93]
	v_mfma_f32_16x16x32_bf16 v[82:85], v[168:171], v[192:195], v[82:85]
	v_mfma_f32_16x16x32_bf16 v[74:77], v[160:163], v[218:221], v[74:77]
	v_mfma_f32_16x16x32_bf16 v[66:69], v[168:171], v[218:221], v[66:69]
	v_mfma_f32_16x16x32_bf16 v[122:125], v[164:167], v[180:183], v[122:125]
	v_mfma_f32_16x16x32_bf16 v[114:117], v[172:175], v[180:183], v[114:117]
	v_mfma_f32_16x16x32_bf16 v[106:109], v[164:167], v[188:191], v[106:109]
	v_mfma_f32_16x16x32_bf16 v[98:101], v[172:175], v[188:191], v[98:101]
	v_mfma_f32_16x16x32_bf16 v[90:93], v[164:167], v[214:217], v[90:93]
	v_mfma_f32_16x16x32_bf16 v[82:85], v[172:175], v[214:217], v[82:85]
	v_mfma_f32_16x16x32_bf16 v[74:77], v[164:167], v[222:225], v[74:77]
	v_mfma_f32_16x16x32_bf16 v[66:69], v[172:175], v[222:225], v[66:69]
	s_setprio 0
	s_barrier
	s_add_i32 s30, s50, s34
	s_add_u32 s28, s28, 0x80
	s_addc_u32 s29, s29, 0
	s_mov_b32 m0, s30
	ds_read_b128 v[176:179], v143 offset:49152
	ds_read_b128 v[180:183], v143 offset:50176
	ds_read_b128 v[184:187], v143 offset:51200
	ds_read_b128 v[188:191], v143 offset:52224
	ds_read_b128 v[192:195], v143 offset:53248
	ds_read_b128 v[214:217], v143 offset:54272
	ds_read_b128 v[218:221], v143 offset:55296
	ds_read_b128 v[222:225], v143 offset:56320
	global_load_lds_dwordx4 v0, s[28:29]
	s_add_i32 m0, s30, 0x2000
	s_add_i32 s30, s51, s34
	global_load_lds_dwordx4 v130, s[28:29]
	s_add_u32 s28, s28, 0x40000
	s_addc_u32 s29, s29, 0
	s_mov_b32 m0, s30
	s_nop 0
	global_load_lds_dwordx4 v0, s[28:29]
	s_add_i32 m0, s30, 0x2000
	s_nop 0
	global_load_lds_dwordx4 v130, s[28:29]
	s_mov_b32 m0, s41
	s_nop 0
	global_load_lds_dwordx4 v134, s[98:99]
	s_mov_b32 m0, s42
	s_nop 0
	global_load_lds_dwordx4 v132, s[98:99]
	s_waitcnt vmcnt(8) lgkmcnt(0)
	s_barrier
	s_setprio 1
	v_mfma_f32_16x16x32_bf16 v[62:65], v[144:147], v[176:179], v[62:65]
	v_mfma_f32_16x16x32_bf16 v[54:57], v[152:155], v[176:179], v[54:57]
	v_mfma_f32_16x16x32_bf16 v[46:49], v[144:147], v[184:187], v[46:49]
	v_mfma_f32_16x16x32_bf16 v[38:41], v[152:155], v[184:187], v[38:41]
	v_mfma_f32_16x16x32_bf16 v[30:33], v[144:147], v[192:195], v[30:33]
	v_mfma_f32_16x16x32_bf16 v[22:25], v[152:155], v[192:195], v[22:25]
	v_mfma_f32_16x16x32_bf16 v[14:17], v[144:147], v[218:221], v[14:17]
	v_mfma_f32_16x16x32_bf16 v[6:9], v[152:155], v[218:221], v[6:9]
	v_mfma_f32_16x16x32_bf16 v[62:65], v[148:151], v[180:183], v[62:65]
	v_mfma_f32_16x16x32_bf16 v[54:57], v[156:159], v[180:183], v[54:57]
	v_mfma_f32_16x16x32_bf16 v[46:49], v[148:151], v[188:191], v[46:49]
	v_mfma_f32_16x16x32_bf16 v[38:41], v[156:159], v[188:191], v[38:41]
	v_mfma_f32_16x16x32_bf16 v[30:33], v[148:151], v[214:217], v[30:33]
	v_mfma_f32_16x16x32_bf16 v[22:25], v[156:159], v[214:217], v[22:25]
	v_mfma_f32_16x16x32_bf16 v[14:17], v[148:151], v[222:225], v[14:17]
	v_mfma_f32_16x16x32_bf16 v[6:9], v[156:159], v[222:225], v[6:9]
	s_setprio 0
	s_setprio 1
	v_mfma_f32_16x16x32_bf16 v[58:61], v[160:163], v[176:179], v[58:61]
	v_mfma_f32_16x16x32_bf16 v[50:53], v[168:171], v[176:179], v[50:53]
	v_mfma_f32_16x16x32_bf16 v[42:45], v[160:163], v[184:187], v[42:45]
	v_mfma_f32_16x16x32_bf16 v[34:37], v[168:171], v[184:187], v[34:37]
	v_mfma_f32_16x16x32_bf16 v[26:29], v[160:163], v[192:195], v[26:29]
	v_mfma_f32_16x16x32_bf16 v[18:21], v[168:171], v[192:195], v[18:21]
	v_mfma_f32_16x16x32_bf16 v[10:13], v[160:163], v[218:221], v[10:13]
	v_mfma_f32_16x16x32_bf16 v[2:5], v[168:171], v[218:221], v[2:5]
	v_mfma_f32_16x16x32_bf16 v[58:61], v[164:167], v[180:183], v[58:61]
	v_mfma_f32_16x16x32_bf16 v[50:53], v[172:175], v[180:183], v[50:53]
	v_mfma_f32_16x16x32_bf16 v[42:45], v[164:167], v[188:191], v[42:45]
	v_mfma_f32_16x16x32_bf16 v[34:37], v[172:175], v[188:191], v[34:37]
	v_mfma_f32_16x16x32_bf16 v[26:29], v[164:167], v[214:217], v[26:29]
	v_mfma_f32_16x16x32_bf16 v[18:21], v[172:175], v[214:217], v[18:21]
	v_mfma_f32_16x16x32_bf16 v[10:13], v[164:167], v[222:225], v[10:13]
	v_mfma_f32_16x16x32_bf16 v[2:5], v[172:175], v[222:225], v[2:5]
	s_setprio 0
	s_barrier
	s_add_i32 s49, s49, 2
	s_add_u32 s26, s26, 0x100
	s_addc_u32 s27, s27, 0
	s_add_u32 s47, s47, 0x100
	s_addc_u32 s48, s48, 0
	s_cmp_gt_u32 s49, 13
	s_cbranch_scc0 .LBB0_157
	s_and_b64 vcc, exec, s[8:9]
	s_cbranch_vccz .LBB0_160
	s_barrier

; #define PG8_STAGE(bufoff, gbase, voff) do { _Pragma("unroll") for (int _i = 0; _i < 2; ++_i) \
;         __builtin_amdgcn_global_load_lds((const unsigned*)((const char*)(gbase) + (voff)[_i]), (LAS unsigned*)(lds + (bufoff) + ldsw + _i * 8192), 16, 0, 0); } while (0)
; #define PG8_LDA(dst, b, h) do { _Pragma("unroll") for (int m = 0; m < 4; ++m) _Pragma("unroll") for (int k = 0; k < 2; ++k) dst[m][k] = *(const LAS f16x8*)(lds + PG8_SA(b, h) + aoff + m * 2048 + k * 1024); } while (0)
; #define PG8_LDB(dst, b, h) do { _Pragma("unroll") for (int n = 0; n < 2; ++n) _Pragma("unroll") for (int k = 0; k < 2; ++k) dst[n][k] = *(const LAS f16x8*)(lds + PG8_SB(b, h) + boff + n * 2048 + k * 1024); } while (0)
; #define PG8_MMA(ai, bj, At, Bt) do { __builtin_amdgcn_s_setprio(1); _Pragma("unroll") for (int m = 0; m < 4; ++m) _Pragma("unroll") for (int n = 0; n < 2; ++n) _Pragma("unroll") for (int k = 0; k < 2; ++k) \
;         acc[ai][bj][m][n] = mma16_<Epi::BF16>(Bt[n][k], At[m][k], acc[ai][bj][m][n]); __builtin_amdgcn_s_setprio(0); } while (0)
; #define PG8_WAIT_V(n) asm volatile("s_waitcnt vmcnt(" #n ")" ::: "memory")
; #define PG8_WAIT_L(n) asm volatile("s_waitcnt lgkmcnt(" #n ")" ::: "memory")
; #define PG8_BAR __builtin_amdgcn_s_barrier()
; #define PG8_SCHED __builtin_amdgcn_sched_barrier(0)
;     ...
;             const char* a1 = cA + (size_t)(t + 1) * kstep;
;             const char* a2 = last ? nA : cA + (size_t)(t + 2) * kstep; const char* b2 = last ? nB : cB + (size_t)(t + 2) * kstep;
;             const char* a3 = a2 + kstep; const char* b3 = b2 + kstep;
;             if constexpr (SP2) {
;             PG8_LDB(B0, 0, 0); PG8_LDB(B1, 0, 1); PG8_SCHED; PG8_LDA(At, 0, 0); PG8_STAGE(PG8_SA(1, 1), a1 + hA, voffA);
;             PG8_WAIT_V(8); PG8_WAIT_L(0); PG8_BAR; PG8_MMA(0, 0, At, B0); PG8_MMA(0, 1, At, B1); PG8_BAR; PG8_SCHED;
;             PG8_LDA(At, 0, 1); PG8_STAGE(PG8_SB(0, 0), b2, voffB); PG8_STAGE(PG8_SB(0, 1), b2 + hB, voffB); PG8_STAGE(PG8_SA(0, 0), a2, voffA);
;             PG8_WAIT_V(8); PG8_WAIT_L(0); PG8_BAR; if (!cur.half) { PG8_MMA(1, 0, At, B0); PG8_MMA(1, 1, At, B1); } PG8_BAR; PG8_SCHED;
.LBB0_242:
	s_mov_b64 s[42:43], s[44:45]
	s_add_u32 s44, s42, 0x100
	s_addc_u32 s45, s43, 0
	s_add_i32 s37, 0, 0x10000
	s_cmp_eq_u32 s14, 40
	s_cselect_b32 s55, s9, s45
	s_cselect_b32 s54, s8, s44
	s_cselect_b32 s53, s11, s3
	s_cselect_b32 s52, s10, s2
	s_add_i32 s78, 0, 0x14000
	v_add_u32_e32 v130, s37, v243
	v_add_u32_e32 v142, s78, v243
	ds_read_b128 v[146:149], v130
	ds_read_b128 v[150:153], v130 offset:1024
	ds_read_b128 v[154:157], v130 offset:2048
	ds_read_b128 v[158:161], v130 offset:3072
	ds_read_b128 v[130:133], v142
	ds_read_b128 v[134:137], v142 offset:1024
	ds_read_b128 v[138:141], v142 offset:2048
	ds_read_b128 v[142:145], v142 offset:3072
	s_add_i32 m0, s63, 0xc000
	s_waitcnt lgkmcnt(0)
	ds_read_b128 v[162:165], v244
	ds_read_b128 v[166:169], v244 offset:1024
	ds_read_b128 v[170:173], v244 offset:2048
	ds_read_b128 v[174:177], v244 offset:3072
	ds_read_b128 v[178:181], v244 offset:4096
	ds_read_b128 v[182:185], v244 offset:5120
	ds_read_b128 v[186:189], v244 offset:6144
	ds_read_b128 v[190:193], v244 offset:7168
	global_load_lds_dwordx4 v222, s[42:43]
	s_add_i32 m0, s63, 0xe000
	s_nop 0
	global_load_lds_dwordx4 v224, s[42:43]
	s_waitcnt vmcnt(8) lgkmcnt(0)
	s_barrier
	s_setprio 1
	v_mfma_f32_16x16x32_bf16 v[126:129], v[146:149], v[162:165], v[126:129]
	v_mfma_f32_16x16x32_bf16 v[122:125], v[154:157], v[162:165], v[122:125]
	v_mfma_f32_16x16x32_bf16 v[118:121], v[146:149], v[170:173], v[118:121]
	v_mfma_f32_16x16x32_bf16 v[114:117], v[154:157], v[170:173], v[114:117]
	v_mfma_f32_16x16x32_bf16 v[110:113], v[146:149], v[178:181], v[110:113]
	v_mfma_f32_16x16x32_bf16 v[106:109], v[154:157], v[178:181], v[106:109]
	v_mfma_f32_16x16x32_bf16 v[102:105], v[146:149], v[186:189], v[102:105]
	v_mfma_f32_16x16x32_bf16 v[98:101], v[154:157], v[186:189], v[98:101]
	v_mfma_f32_16x16x32_bf16 v[126:129], v[150:153], v[166:169], v[126:129]
	v_mfma_f32_16x16x32_bf16 v[122:125], v[158:161], v[166:169], v[122:125]
	v_mfma_f32_16x16x32_bf16 v[118:121], v[150:153], v[174:177], v[118:121]
	v_mfma_f32_16x16x32_bf16 v[114:117], v[158:161], v[174:177], v[114:117]
	v_mfma_f32_16x16x32_bf16 v[110:113], v[150:153], v[182:185], v[110:113]
	v_mfma_f32_16x16x32_bf16 v[106:109], v[158:161], v[182:185], v[106:109]
	v_mfma_f32_16x16x32_bf16 v[102:105], v[150:153], v[190:193], v[102:105]
	v_mfma_f32_16x16x32_bf16 v[98:101], v[158:161], v[190:193], v[98:101]
	s_setprio 0
	s_setprio 1
	v_mfma_f32_16x16x32_bf16 v[70:73], v[130:133], v[162:165], v[70:73]
	v_mfma_f32_16x16x32_bf16 v[66:69], v[138:141], v[162:165], v[66:69]
	v_mfma_f32_16x16x32_bf16 v[54:57], v[130:133], v[170:173], v[54:57]
	v_mfma_f32_16x16x32_bf16 v[50:53], v[138:141], v[170:173], v[50:53]
	v_mfma_f32_16x16x32_bf16 v[46:49], v[130:133], v[178:181], v[46:49]
	v_mfma_f32_16x16x32_bf16 v[42:45], v[138:141], v[178:181], v[42:45]
	v_mfma_f32_16x16x32_bf16 v[38:41], v[130:133], v[186:189], v[38:41]
	v_mfma_f32_16x16x32_bf16 v[34:37], v[138:141], v[186:189], v[34:37]
	v_mfma_f32_16x16x32_bf16 v[70:73], v[134:137], v[166:169], v[70:73]
	v_mfma_f32_16x16x32_bf16 v[66:69], v[142:145], v[166:169], v[66:69]
	v_mfma_f32_16x16x32_bf16 v[54:57], v[134:137], v[174:177], v[54:57]
	v_mfma_f32_16x16x32_bf16 v[50:53], v[142:145], v[174:177], v[50:53]
	v_mfma_f32_16x16x32_bf16 v[46:49], v[134:137], v[182:185], v[46:49]
	v_mfma_f32_16x16x32_bf16 v[42:45], v[142:145], v[182:185], v[42:45]
	v_mfma_f32_16x16x32_bf16 v[38:41], v[134:137], v[190:193], v[38:41]
	v_mfma_f32_16x16x32_bf16 v[34:37], v[142:145], v[190:193], v[34:37]
	s_setprio 0
	s_barrier
	s_add_i32 s37, s37, s62
	s_mov_b32 m0, s37
	ds_read_b128 v[186:189], v244 offset:16384
	ds_read_b128 v[190:193], v244 offset:17408
	ds_read_b128 v[178:181], v244 offset:18432
	ds_read_b128 v[182:185], v244 offset:19456
	ds_read_b128 v[170:173], v244 offset:20480
	ds_read_b128 v[174:177], v244 offset:21504
	ds_read_b128 v[162:165], v244 offset:22528
	ds_read_b128 v[166:169], v244 offset:23552
	global_load_lds_dwordx4 v214, s[52:53]
	s_add_i32 m0, s37, 0x2000
	s_add_u32 s42, s52, 0xb0000
	s_addc_u32 s43, s53, 0
	s_add_i32 s37, s78, s62
	global_load_lds_dwordx4 v218, s[52:53]
	s_mov_b32 m0, s37
	s_nop 0
	global_load_lds_dwordx4 v214, s[42:43]
	s_add_i32 m0, s37, 0x2000
	s_nop 0
	global_load_lds_dwordx4 v218, s[42:43]
	s_mov_b32 m0, s63
	v_cndmask_b32_e64 v200, 0, 1, s[50:51]
	global_load_lds_dwordx4 v194, s[54:55]
	s_mov_b32 m0, s64
	v_cmp_ne_u32_e64 s[42:43], 1, v200
	global_load_lds_dwordx4 v216, s[54:55]
	s_waitcnt vmcnt(8) lgkmcnt(0)
	s_andn2_b64 vcc, exec, s[50:51]
	s_barrier
	s_cbranch_vccnz .LBB0_244
	s_setprio 1
	v_mfma_f32_16x16x32_bf16 v[94:97], v[146:149], v[186:189], v[94:97]
	v_mfma_f32_16x16x32_bf16 v[90:93], v[154:157], v[186:189], v[90:93]
	v_mfma_f32_16x16x32_bf16 v[86:89], v[146:149], v[178:181], v[86:89]
	v_mfma_f32_16x16x32_bf16 v[82:85], v[154:157], v[178:181], v[82:85]
	v_mfma_f32_16x16x32_bf16 v[78:81], v[146:149], v[170:173], v[78:81]
	v_mfma_f32_16x16x32_bf16 v[74:77], v[154:157], v[170:173], v[74:77]
	v_mfma_f32_16x16x32_bf16 v[62:65], v[146:149], v[162:165], v[62:65]
	v_mfma_f32_16x16x32_bf16 v[58:61], v[154:157], v[162:165], v[58:61]
	v_mfma_f32_16x16x32_bf16 v[94:97], v[150:153], v[190:193], v[94:97]
	v_mfma_f32_16x16x32_bf16 v[90:93], v[158:161], v[190:193], v[90:93]
	v_mfma_f32_16x16x32_bf16 v[86:89], v[150:153], v[182:185], v[86:89]
	v_mfma_f32_16x16x32_bf16 v[82:85], v[158:161], v[182:185], v[82:85]
	v_mfma_f32_16x16x32_bf16 v[78:81], v[150:153], v[174:177], v[78:81]
	v_mfma_f32_16x16x32_bf16 v[74:77], v[158:161], v[174:177], v[74:77]
	v_mfma_f32_16x16x32_bf16 v[62:65], v[150:153], v[166:169], v[62:65]
	v_mfma_f32_16x16x32_bf16 v[58:61], v[158:161], v[166:169], v[58:61]
	s_setprio 0
	s_setprio 1
	v_mfma_f32_16x16x32_bf16 v[30:33], v[130:133], v[186:189], v[30:33]
	v_mfma_f32_16x16x32_bf16 v[26:29], v[138:141], v[186:189], v[26:29]
	v_mfma_f32_16x16x32_bf16 v[22:25], v[130:133], v[178:181], v[22:25]
	v_mfma_f32_16x16x32_bf16 v[18:21], v[138:141], v[178:181], v[18:21]
	v_mfma_f32_16x16x32_bf16 v[14:17], v[130:133], v[170:173], v[14:17]
	v_mfma_f32_16x16x32_bf16 v[10:13], v[138:141], v[170:173], v[10:13]
	v_mfma_f32_16x16x32_bf16 v[6:9], v[130:133], v[162:165], v[6:9]
	v_mfma_f32_16x16x32_bf16 v[2:5], v[138:141], v[162:165], v[2:5]
	v_mfma_f32_16x16x32_bf16 v[30:33], v[134:137], v[190:193], v[30:33]
	v_mfma_f32_16x16x32_bf16 v[26:29], v[142:145], v[190:193], v[26:29]
	v_mfma_f32_16x16x32_bf16 v[22:25], v[134:137], v[182:185], v[22:25]
	v_mfma_f32_16x16x32_bf16 v[18:21], v[142:145], v[182:185], v[18:21]
	v_mfma_f32_16x16x32_bf16 v[14:17], v[134:137], v[174:177], v[14:17]
	v_mfma_f32_16x16x32_bf16 v[10:13], v[142:145], v[174:177], v[10:13]
	v_mfma_f32_16x16x32_bf16 v[6:9], v[134:137], v[166:169], v[6:9]
	v_mfma_f32_16x16x32_bf16 v[2:5], v[142:145], v[166:169], v[2:5]
	s_setprio 0
; #define PG8_STAGE(bufoff, gbase, voff) do { _Pragma("unroll") for (int _i = 0; _i < 2; ++_i) \
;         __builtin_amdgcn_global_load_lds((const unsigned*)((const char*)(gbase) + (voff)[_i]), (LAS unsigned*)(lds + (bufoff) + ldsw + _i * 8192), 16, 0, 0); } while (0)
; #define PG8_LDA(dst, b, h) do { _Pragma("unroll") for (int m = 0; m < 4; ++m) _Pragma("unroll") for (int k = 0; k < 2; ++k) dst[m][k] = *(const LAS f16x8*)(lds + PG8_SA(b, h) + aoff + m * 2048 + k * 1024); } while (0)
; #define PG8_LDB(dst, b, h) do { _Pragma("unroll") for (int n = 0; n < 2; ++n) _Pragma("unroll") for (int k = 0; k < 2; ++k) dst[n][k] = *(const LAS f16x8*)(lds + PG8_SB(b, h) + boff + n * 2048 + k * 1024); } while (0)
; #define PG8_MMA(ai, bj, At, Bt) do { __builtin_amdgcn_s_setprio(1); _Pragma("unroll") for (int m = 0; m < 4; ++m) _Pragma("unroll") for (int n = 0; n < 2; ++n) _Pragma("unroll") for (int k = 0; k < 2; ++k) \
;         acc[ai][bj][m][n] = mma16_<Epi::BF16>(Bt[n][k], At[m][k], acc[ai][bj][m][n]); __builtin_amdgcn_s_setprio(0); } while (0)
; #define PG8_WAIT_V(n) asm volatile("s_waitcnt vmcnt(" #n ")" ::: "memory")
; #define PG8_WAIT_L(n) asm volatile("s_waitcnt lgkmcnt(" #n ")" ::: "memory")
; #define PG8_BAR __builtin_amdgcn_s_barrier()
; #define PG8_SCHED __builtin_amdgcn_sched_barrier(0)
;     ...
;             PG8_LDB(B0, 1, 0); PG8_LDB(B1, 1, 1); PG8_SCHED; PG8_LDA(At, 1, 0); PG8_STAGE(PG8_SA(0, 1), a2 + hA, voffA);
;             PG8_WAIT_V(8); PG8_WAIT_L(0); PG8_BAR; PG8_MMA(0, 0, At, B0); PG8_MMA(0, 1, At, B1); PG8_BAR; PG8_SCHED;
;             PG8_LDA(At, 1, 1); PG8_STAGE(PG8_SB(1, 0), b3, voffB); PG8_STAGE(PG8_SB(1, 1), b3 + hB, voffB); PG8_STAGE(PG8_SA(1, 0), a3, voffA);
;             PG8_WAIT_V(8); PG8_WAIT_L(0); PG8_BAR; if (!cur.half) { PG8_MMA(1, 0, At, B0); PG8_MMA(1, 1, At, B1); } PG8_BAR; PG8_SCHED;
.LBB0_244:
	s_barrier
	s_add_i32 s37, 0, 0x18000
	s_add_i32 s78, 0, 0x1c000
	v_add_u32_e32 v130, s37, v243
	v_add_u32_e32 v142, s78, v243
	ds_read_b128 v[146:149], v130
	ds_read_b128 v[150:153], v130 offset:1024
	ds_read_b128 v[154:157], v130 offset:2048
	ds_read_b128 v[158:161], v130 offset:3072
	ds_read_b128 v[130:133], v142
	ds_read_b128 v[134:137], v142 offset:1024
	ds_read_b128 v[138:141], v142 offset:2048
	ds_read_b128 v[142:145], v142 offset:3072
	s_add_u32 s54, s54, 0xb0000
	s_addc_u32 s55, s55, 0
	s_add_u32 s98, s54, 0xfff50080
	s_addc_u32 s99, s55, -1
	s_mov_b32 m0, s65
	s_waitcnt lgkmcnt(0)
	ds_read_b128 v[162:165], v244 offset:32768
	ds_read_b128 v[166:169], v244 offset:33792
	ds_read_b128 v[170:173], v244 offset:34816
	ds_read_b128 v[174:177], v244 offset:35840
	ds_read_b128 v[178:181], v244 offset:36864
	ds_read_b128 v[182:185], v244 offset:37888
	ds_read_b128 v[186:189], v244 offset:38912
	ds_read_b128 v[190:193], v244 offset:39936
	global_load_lds_dwordx4 v194, s[54:55]
	s_mov_b32 m0, s66
	s_nop 0
	global_load_lds_dwordx4 v216, s[54:55]
	s_waitcnt vmcnt(8) lgkmcnt(0)
	s_barrier
	s_setprio 1
	v_mfma_f32_16x16x32_bf16 v[126:129], v[146:149], v[162:165], v[126:129]
	v_mfma_f32_16x16x32_bf16 v[122:125], v[154:157], v[162:165], v[122:125]
	v_mfma_f32_16x16x32_bf16 v[118:121], v[146:149], v[170:173], v[118:121]
	v_mfma_f32_16x16x32_bf16 v[114:117], v[154:157], v[170:173], v[114:117]
	v_mfma_f32_16x16x32_bf16 v[110:113], v[146:149], v[178:181], v[110:113]
	v_mfma_f32_16x16x32_bf16 v[106:109], v[154:157], v[178:181], v[106:109]
	v_mfma_f32_16x16x32_bf16 v[102:105], v[146:149], v[186:189], v[102:105]
	v_mfma_f32_16x16x32_bf16 v[98:101], v[154:157], v[186:189], v[98:101]
	v_mfma_f32_16x16x32_bf16 v[126:129], v[150:153], v[166:169], v[126:129]
	v_mfma_f32_16x16x32_bf16 v[122:125], v[158:161], v[166:169], v[122:125]
	v_mfma_f32_16x16x32_bf16 v[118:121], v[150:153], v[174:177], v[118:121]
	v_mfma_f32_16x16x32_bf16 v[114:117], v[158:161], v[174:177], v[114:117]
	v_mfma_f32_16x16x32_bf16 v[110:113], v[150:153], v[182:185], v[110:113]
	v_mfma_f32_16x16x32_bf16 v[106:109], v[158:161], v[182:185], v[106:109]
	v_mfma_f32_16x16x32_bf16 v[102:105], v[150:153], v[190:193], v[102:105]
	v_mfma_f32_16x16x32_bf16 v[98:101], v[158:161], v[190:193], v[98:101]
	s_setprio 0
	s_setprio 1
	v_mfma_f32_16x16x32_bf16 v[70:73], v[130:133], v[162:165], v[70:73]
	v_mfma_f32_16x16x32_bf16 v[66:69], v[138:141], v[162:165], v[66:69]
	v_mfma_f32_16x16x32_bf16 v[54:57], v[130:133], v[170:173], v[54:57]
	v_mfma_f32_16x16x32_bf16 v[50:53], v[138:141], v[170:173], v[50:53]
	v_mfma_f32_16x16x32_bf16 v[46:49], v[130:133], v[178:181], v[46:49]
	v_mfma_f32_16x16x32_bf16 v[42:45], v[138:141], v[178:181], v[42:45]
	v_mfma_f32_16x16x32_bf16 v[38:41], v[130:133], v[186:189], v[38:41]
	v_mfma_f32_16x16x32_bf16 v[34:37], v[138:141], v[186:189], v[34:37]
	v_mfma_f32_16x16x32_bf16 v[70:73], v[134:137], v[166:169], v[70:73]
	v_mfma_f32_16x16x32_bf16 v[66:69], v[142:145], v[166:169], v[66:69]
	v_mfma_f32_16x16x32_bf16 v[54:57], v[134:137], v[174:177], v[54:57]
	v_mfma_f32_16x16x32_bf16 v[50:53], v[142:145], v[174:177], v[50:53]
	v_mfma_f32_16x16x32_bf16 v[46:49], v[134:137], v[182:185], v[46:49]
	v_mfma_f32_16x16x32_bf16 v[42:45], v[142:145], v[182:185], v[42:45]
	v_mfma_f32_16x16x32_bf16 v[38:41], v[134:137], v[190:193], v[38:41]
	v_mfma_f32_16x16x32_bf16 v[34:37], v[142:145], v[190:193], v[34:37]
	s_setprio 0
	s_barrier
	s_add_i32 s37, s37, s62
	s_add_u32 s52, s52, 0x80
	s_addc_u32 s53, s53, 0
	s_mov_b32 m0, s37
	ds_read_b128 v[186:189], v244 offset:49152
	ds_read_b128 v[190:193], v244 offset:50176
	ds_read_b128 v[178:181], v244 offset:51200
	ds_read_b128 v[182:185], v244 offset:52224
	ds_read_b128 v[170:173], v244 offset:53248
	ds_read_b128 v[174:177], v244 offset:54272
	ds_read_b128 v[162:165], v244 offset:55296
	ds_read_b128 v[166:169], v244 offset:56320
	global_load_lds_dwordx4 v214, s[52:53]
	s_add_i32 m0, s37, 0x2000
	s_add_i32 s37, s78, s62
	global_load_lds_dwordx4 v218, s[52:53]
	s_add_u32 s52, s52, 0xb0000
	s_addc_u32 s53, s53, 0
	s_mov_b32 m0, s37
	s_and_b64 vcc, exec, s[42:43]
	global_load_lds_dwordx4 v214, s[52:53]
	s_add_i32 m0, s37, 0x2000
	s_nop 0
	global_load_lds_dwordx4 v218, s[52:53]
	s_mov_b32 m0, s0
	s_nop 0
	global_load_lds_dwordx4 v194, s[98:99]
	s_mov_b32 m0, s69
	s_nop 0
	global_load_lds_dwordx4 v216, s[98:99]
	s_waitcnt vmcnt(8) lgkmcnt(0)
	s_barrier
	s_cbranch_vccnz .LBB0_241
	s_setprio 1
	v_mfma_f32_16x16x32_bf16 v[94:97], v[146:149], v[186:189], v[94:97]
	v_mfma_f32_16x16x32_bf16 v[90:93], v[154:157], v[186:189], v[90:93]
	v_mfma_f32_16x16x32_bf16 v[86:89], v[146:149], v[178:181], v[86:89]
	v_mfma_f32_16x16x32_bf16 v[82:85], v[154:157], v[178:181], v[82:85]
	v_mfma_f32_16x16x32_bf16 v[78:81], v[146:149], v[170:173], v[78:81]
	v_mfma_f32_16x16x32_bf16 v[74:77], v[154:157], v[170:173], v[74:77]
	v_mfma_f32_16x16x32_bf16 v[62:65], v[146:149], v[162:165], v[62:65]
	v_mfma_f32_16x16x32_bf16 v[58:61], v[154:157], v[162:165], v[58:61]
	v_mfma_f32_16x16x32_bf16 v[94:97], v[150:153], v[190:193], v[94:97]
	v_mfma_f32_16x16x32_bf16 v[90:93], v[158:161], v[190:193], v[90:93]
	v_mfma_f32_16x16x32_bf16 v[86:89], v[150:153], v[182:185], v[86:89]
	v_mfma_f32_16x16x32_bf16 v[82:85], v[158:161], v[182:185], v[82:85]
	v_mfma_f32_16x16x32_bf16 v[78:81], v[150:153], v[174:177], v[78:81]
	v_mfma_f32_16x16x32_bf16 v[74:77], v[158:161], v[174:177], v[74:77]
	v_mfma_f32_16x16x32_bf16 v[62:65], v[150:153], v[166:169], v[62:65]
	v_mfma_f32_16x16x32_bf16 v[58:61], v[158:161], v[166:169], v[58:61]
	s_setprio 0
	s_setprio 1
	v_mfma_f32_16x16x32_bf16 v[30:33], v[130:133], v[186:189], v[30:33]
	v_mfma_f32_16x16x32_bf16 v[26:29], v[138:141], v[186:189], v[26:29]
	v_mfma_f32_16x16x32_bf16 v[22:25], v[130:133], v[178:181], v[22:25]
	v_mfma_f32_16x16x32_bf16 v[18:21], v[138:141], v[178:181], v[18:21]
	v_mfma_f32_16x16x32_bf16 v[14:17], v[130:133], v[170:173], v[14:17]
	v_mfma_f32_16x16x32_bf16 v[10:13], v[138:141], v[170:173], v[10:13]
	v_mfma_f32_16x16x32_bf16 v[6:9], v[130:133], v[162:165], v[6:9]
	v_mfma_f32_16x16x32_bf16 v[2:5], v[138:141], v[162:165], v[2:5]
	v_mfma_f32_16x16x32_bf16 v[30:33], v[134:137], v[190:193], v[30:33]
	v_mfma_f32_16x16x32_bf16 v[26:29], v[142:145], v[190:193], v[26:29]
	v_mfma_f32_16x16x32_bf16 v[22:25], v[134:137], v[182:185], v[22:25]
	v_mfma_f32_16x16x32_bf16 v[18:21], v[142:145], v[182:185], v[18:21]
	v_mfma_f32_16x16x32_bf16 v[14:17], v[134:137], v[174:177], v[14:17]
	v_mfma_f32_16x16x32_bf16 v[10:13], v[142:145], v[174:177], v[10:13]
	v_mfma_f32_16x16x32_bf16 v[6:9], v[134:137], v[166:169], v[6:9]
	v_mfma_f32_16x16x32_bf16 v[2:5], v[142:145], v[166:169], v[2:5]
	s_setprio 0
	s_branch .LBB0_241

; #define PG8_STAGE(bufoff, gbase, voff) do { _Pragma("unroll") for (int _i = 0; _i < 2; ++_i) \
;         __builtin_amdgcn_global_load_lds((const unsigned*)((const char*)(gbase) + (voff)[_i]), (LAS unsigned*)(lds + (bufoff) + ldsw + _i * 8192), 16, 0, 0); } while (0)
; #define PG8_LDA(dst, b, h) do { _Pragma("unroll") for (int m = 0; m < 4; ++m) _Pragma("unroll") for (int k = 0; k < 2; ++k) dst[m][k] = *(const LAS f16x8*)(lds + PG8_SA(b, h) + aoff + m * 2048 + k * 1024); } while (0)
; #define PG8_LDB(dst, b, h) do { _Pragma("unroll") for (int n = 0; n < 2; ++n) _Pragma("unroll") for (int k = 0; k < 2; ++k) dst[n][k] = *(const LAS f16x8*)(lds + PG8_SB(b, h) + boff + n * 2048 + k * 1024); } while (0)
; #define PG8_MMA(ai, bj, At, Bt) do { __builtin_amdgcn_s_setprio(1); _Pragma("unroll") for (int m = 0; m < 4; ++m) _Pragma("unroll") for (int n = 0; n < 2; ++n) _Pragma("unroll") for (int k = 0; k < 2; ++k) \
;         acc[ai][bj][m][n] = mma16_<Epi::BF16>(Bt[n][k], At[m][k], acc[ai][bj][m][n]); __builtin_amdgcn_s_setprio(0); } while (0)
; #define PG8_WAIT_V(n) asm volatile("s_waitcnt vmcnt(" #n ")" ::: "memory")
; #define PG8_WAIT_L(n) asm volatile("s_waitcnt lgkmcnt(" #n ")" ::: "memory")
; #define PG8_BAR __builtin_amdgcn_s_barrier()
; #define PG8_SCHED __builtin_amdgcn_sched_barrier(0)
;     ...
;             const char* a1 = cA + (size_t)(t + 1) * kstep;
;             const char* a2 = last ? nA : cA + (size_t)(t + 2) * kstep; const char* b2 = last ? nB : cB + (size_t)(t + 2) * kstep;
;             const char* a3 = a2 + kstep; const char* b3 = b2 + kstep;
;             if constexpr (SP2) {
;             PG8_LDB(B0, 0, 0); PG8_LDB(B1, 0, 1); PG8_SCHED; PG8_LDA(At, 0, 0); PG8_STAGE(PG8_SA(1, 1), a1 + hA, voffA);
;             PG8_WAIT_V(8); PG8_WAIT_L(0); PG8_BAR; PG8_MMA(0, 0, At, B0); PG8_MMA(0, 1, At, B1); PG8_BAR; PG8_SCHED;
;             PG8_LDA(At, 0, 1); PG8_STAGE(PG8_SB(0, 0), b2, voffB); PG8_STAGE(PG8_SB(0, 1), b2 + hB, voffB); PG8_STAGE(PG8_SA(0, 0), a2, voffA);
;             PG8_WAIT_V(8); PG8_WAIT_L(0); PG8_BAR; if (!cur.half) { PG8_MMA(1, 0, At, B0); PG8_MMA(1, 1, At, B1); } PG8_BAR; PG8_SCHED;
.LBB0_516:
	s_add_u32 s28, s26, 0xfffc0080
	s_addc_u32 s29, s27, -1
	s_add_i32 s50, 0, 0x10000
	s_cmp_eq_u32 s49, 12
	s_cselect_b32 s31, s2, s29
	s_cselect_b32 s30, s3, s28
	v_add_u32_e32 v142, s50, v145
	s_cselect_b32 s29, s19, s48
	s_cselect_b32 s28, s21, s47
	s_add_i32 s52, 0, 0x14000
	ds_read_b128 v[148:151], v142
	ds_read_b128 v[152:155], v142 offset:1024
	ds_read_b128 v[156:159], v142 offset:2048
	ds_read_b128 v[160:163], v142 offset:3072
	v_add_u32_e32 v142, s52, v145
	ds_read_b128 v[164:167], v142
	ds_read_b128 v[168:171], v142 offset:1024
	ds_read_b128 v[172:175], v142 offset:2048
	ds_read_b128 v[176:179], v142 offset:3072
	s_add_i32 m0, s17, 0xc000
	ds_read_b128 v[180:183], v147
	ds_read_b128 v[184:187], v147 offset:1024
	ds_read_b128 v[188:191], v147 offset:2048
	ds_read_b128 v[192:195], v147 offset:3072
	ds_read_b128 v[214:217], v147 offset:4096
	ds_read_b128 v[218:221], v147 offset:5120
	ds_read_b128 v[222:225], v147 offset:6144
	ds_read_b128 v[226:229], v147 offset:7168
	global_load_lds_dwordx4 v138, s[26:27]
	s_add_i32 m0, s17, 0xe000
	s_nop 0
	global_load_lds_dwordx4 v140, s[26:27]
	s_waitcnt vmcnt(8) lgkmcnt(0)
	s_barrier
	s_setprio 1
	v_mfma_f32_16x16x32_bf16 v[126:129], v[148:151], v[180:183], v[126:129]
	v_mfma_f32_16x16x32_bf16 v[122:125], v[156:159], v[180:183], v[122:125]
	v_mfma_f32_16x16x32_bf16 v[118:121], v[148:151], v[188:191], v[118:121]
	v_mfma_f32_16x16x32_bf16 v[114:117], v[156:159], v[188:191], v[114:117]
	v_mfma_f32_16x16x32_bf16 v[102:105], v[148:151], v[214:217], v[102:105]
	v_mfma_f32_16x16x32_bf16 v[98:101], v[156:159], v[214:217], v[98:101]
	v_mfma_f32_16x16x32_bf16 v[86:89], v[148:151], v[222:225], v[86:89]
	v_mfma_f32_16x16x32_bf16 v[82:85], v[156:159], v[222:225], v[82:85]
	v_mfma_f32_16x16x32_bf16 v[126:129], v[152:155], v[184:187], v[126:129]
	v_mfma_f32_16x16x32_bf16 v[122:125], v[160:163], v[184:187], v[122:125]
	v_mfma_f32_16x16x32_bf16 v[118:121], v[152:155], v[192:195], v[118:121]
	v_mfma_f32_16x16x32_bf16 v[114:117], v[160:163], v[192:195], v[114:117]
	v_mfma_f32_16x16x32_bf16 v[102:105], v[152:155], v[218:221], v[102:105]
	v_mfma_f32_16x16x32_bf16 v[98:101], v[160:163], v[218:221], v[98:101]
	v_mfma_f32_16x16x32_bf16 v[86:89], v[152:155], v[226:229], v[86:89]
	v_mfma_f32_16x16x32_bf16 v[82:85], v[160:163], v[226:229], v[82:85]
	s_setprio 0
	s_setprio 1
	v_mfma_f32_16x16x32_bf16 v[110:113], v[164:167], v[180:183], v[110:113]
	v_mfma_f32_16x16x32_bf16 v[106:109], v[172:175], v[180:183], v[106:109]
	v_mfma_f32_16x16x32_bf16 v[94:97], v[164:167], v[188:191], v[94:97]
	v_mfma_f32_16x16x32_bf16 v[90:93], v[172:175], v[188:191], v[90:93]
	v_mfma_f32_16x16x32_bf16 v[78:81], v[164:167], v[214:217], v[78:81]
	v_mfma_f32_16x16x32_bf16 v[74:77], v[172:175], v[214:217], v[74:77]
	v_mfma_f32_16x16x32_bf16 v[70:73], v[164:167], v[222:225], v[70:73]
	v_mfma_f32_16x16x32_bf16 v[66:69], v[172:175], v[222:225], v[66:69]
	v_mfma_f32_16x16x32_bf16 v[110:113], v[168:171], v[184:187], v[110:113]
	v_mfma_f32_16x16x32_bf16 v[106:109], v[176:179], v[184:187], v[106:109]
	v_mfma_f32_16x16x32_bf16 v[94:97], v[168:171], v[192:195], v[94:97]
	v_mfma_f32_16x16x32_bf16 v[90:93], v[176:179], v[192:195], v[90:93]
	v_mfma_f32_16x16x32_bf16 v[78:81], v[168:171], v[218:221], v[78:81]
	v_mfma_f32_16x16x32_bf16 v[74:77], v[176:179], v[218:221], v[74:77]
	v_mfma_f32_16x16x32_bf16 v[70:73], v[168:171], v[226:229], v[70:73]
	v_mfma_f32_16x16x32_bf16 v[66:69], v[176:179], v[226:229], v[66:69]
	s_setprio 0
	s_barrier
	s_add_i32 s50, s50, s34
	s_mov_b32 m0, s50
	ds_read_b128 v[180:183], v147 offset:16384
	ds_read_b128 v[184:187], v147 offset:17408
	ds_read_b128 v[188:191], v147 offset:18432
	ds_read_b128 v[192:195], v147 offset:19456
	ds_read_b128 v[214:217], v147 offset:20480
	ds_read_b128 v[218:221], v147 offset:21504
	ds_read_b128 v[222:225], v147 offset:22528
	ds_read_b128 v[226:229], v147 offset:23552
	global_load_lds_dwordx4 v0, s[28:29]
	s_add_i32 m0, s50, 0x2000
	s_add_u32 s50, s28, 0x40000
	s_addc_u32 s51, s29, 0
	s_add_i32 s52, s52, s34
	global_load_lds_dwordx4 v130, s[28:29]
	s_mov_b32 m0, s52
	s_nop 0
	global_load_lds_dwordx4 v0, s[50:51]
	s_add_i32 m0, s52, 0x2000
	s_nop 0
	global_load_lds_dwordx4 v130, s[50:51]
	s_mov_b32 m0, s17
	s_nop 0
	global_load_lds_dwordx4 v134, s[30:31]
	s_mov_b32 m0, s36
	s_nop 0
	global_load_lds_dwordx4 v132, s[30:31]
	s_waitcnt vmcnt(8) lgkmcnt(0)
	s_barrier
	s_setprio 1
	v_mfma_f32_16x16x32_bf16 v[62:65], v[148:151], v[180:183], v[62:65]
	v_mfma_f32_16x16x32_bf16 v[58:61], v[156:159], v[180:183], v[58:61]
	v_mfma_f32_16x16x32_bf16 v[54:57], v[148:151], v[188:191], v[54:57]
	v_mfma_f32_16x16x32_bf16 v[50:53], v[156:159], v[188:191], v[50:53]
	v_mfma_f32_16x16x32_bf16 v[38:41], v[148:151], v[214:217], v[38:41]
	v_mfma_f32_16x16x32_bf16 v[34:37], v[156:159], v[214:217], v[34:37]
	v_mfma_f32_16x16x32_bf16 v[22:25], v[148:151], v[222:225], v[22:25]
	v_mfma_f32_16x16x32_bf16 v[18:21], v[156:159], v[222:225], v[18:21]
	v_mfma_f32_16x16x32_bf16 v[62:65], v[152:155], v[184:187], v[62:65]
	v_mfma_f32_16x16x32_bf16 v[58:61], v[160:163], v[184:187], v[58:61]
	v_mfma_f32_16x16x32_bf16 v[54:57], v[152:155], v[192:195], v[54:57]
	v_mfma_f32_16x16x32_bf16 v[50:53], v[160:163], v[192:195], v[50:53]
	v_mfma_f32_16x16x32_bf16 v[38:41], v[152:155], v[218:221], v[38:41]
	v_mfma_f32_16x16x32_bf16 v[34:37], v[160:163], v[218:221], v[34:37]
	v_mfma_f32_16x16x32_bf16 v[22:25], v[152:155], v[226:229], v[22:25]
	v_mfma_f32_16x16x32_bf16 v[18:21], v[160:163], v[226:229], v[18:21]
	s_setprio 0
	s_setprio 1
	v_mfma_f32_16x16x32_bf16 v[46:49], v[164:167], v[180:183], v[46:49]
	v_mfma_f32_16x16x32_bf16 v[42:45], v[172:175], v[180:183], v[42:45]
	v_mfma_f32_16x16x32_bf16 v[30:33], v[164:167], v[188:191], v[30:33]
	v_mfma_f32_16x16x32_bf16 v[26:29], v[172:175], v[188:191], v[26:29]
	v_mfma_f32_16x16x32_bf16 v[14:17], v[164:167], v[214:217], v[14:17]
	v_mfma_f32_16x16x32_bf16 v[10:13], v[172:175], v[214:217], v[10:13]
	v_mfma_f32_16x16x32_bf16 v[6:9], v[164:167], v[222:225], v[6:9]
	v_mfma_f32_16x16x32_bf16 v[2:5], v[172:175], v[222:225], v[2:5]
	v_mfma_f32_16x16x32_bf16 v[46:49], v[168:171], v[184:187], v[46:49]
	v_mfma_f32_16x16x32_bf16 v[42:45], v[176:179], v[184:187], v[42:45]
	v_mfma_f32_16x16x32_bf16 v[30:33], v[168:171], v[192:195], v[30:33]
	v_mfma_f32_16x16x32_bf16 v[26:29], v[176:179], v[192:195], v[26:29]
	v_mfma_f32_16x16x32_bf16 v[14:17], v[168:171], v[218:221], v[14:17]
	v_mfma_f32_16x16x32_bf16 v[10:13], v[176:179], v[218:221], v[10:13]
	v_mfma_f32_16x16x32_bf16 v[6:9], v[168:171], v[226:229], v[6:9]
	v_mfma_f32_16x16x32_bf16 v[2:5], v[176:179], v[226:229], v[2:5]
	s_setprio 0
	s_barrier
; #define PG8_STAGE(bufoff, gbase, voff) do { _Pragma("unroll") for (int _i = 0; _i < 2; ++_i) \
;         __builtin_amdgcn_global_load_lds((const unsigned*)((const char*)(gbase) + (voff)[_i]), (LAS unsigned*)(lds + (bufoff) + ldsw + _i * 8192), 16, 0, 0); } while (0)
; #define PG8_LDA(dst, b, h) do { _Pragma("unroll") for (int m = 0; m < 4; ++m) _Pragma("unroll") for (int k = 0; k < 2; ++k) dst[m][k] = *(const LAS f16x8*)(lds + PG8_SA(b, h) + aoff + m * 2048 + k * 1024); } while (0)
; #define PG8_LDB(dst, b, h) do { _Pragma("unroll") for (int n = 0; n < 2; ++n) _Pragma("unroll") for (int k = 0; k < 2; ++k) dst[n][k] = *(const LAS f16x8*)(lds + PG8_SB(b, h) + boff + n * 2048 + k * 1024); } while (0)
; #define PG8_WAIT_V(n) asm volatile("s_waitcnt vmcnt(" #n ")" ::: "memory")
; #define PG8_WAIT_L(n) asm volatile("s_waitcnt lgkmcnt(" #n ")" ::: "memory")
;     ...
;         for (int t = 0; t < nt; t += 2) {
;             const bool last = (t == nt - 2);
;             const char* a1 = cA + (size_t)(t + 1) * kstep;
;             const char* a2 = last ? nA : cA + (size_t)(t + 2) * kstep; const char* b2 = last ? nB : cB + (size_t)(t + 2) * kstep;
;             const char* a3 = a2 + kstep; const char* b3 = b2 + kstep;
;             if constexpr (SP2) {
;             PG8_LDB(B0, 0, 0); PG8_LDB(B1, 0, 1); PG8_SCHED; PG8_LDA(At, 0, 0); PG8_STAGE(PG8_SA(1, 1), a1 + hA, voffA);
;             PG8_WAIT_V(8); PG8_WAIT_L(0); PG8_BAR; PG8_MMA(0, 0, At, B0); PG8_MMA(0, 1, At, B1); PG8_BAR; PG8_SCHED;
;             PG8_LDA(At, 0, 1); PG8_STAGE(PG8_SB(0, 0), b2, voffB); PG8_STAGE(PG8_SB(0, 1), b2 + hB, voffB); PG8_STAGE(PG8_SA(0, 0), a2, voffA);
;             PG8_WAIT_V(8); PG8_WAIT_L(0); PG8_BAR; if (!cur.half) { PG8_MMA(1, 0, At, B0); PG8_MMA(1, 1, At, B1); } PG8_BAR; PG8_SCHED;
;             PG8_LDB(B0, 1, 0); PG8_LDB(B1, 1, 1); PG8_SCHED; PG8_LDA(At, 1, 0); PG8_STAGE(PG8_SA(0, 1), a2 + hA, voffA);
;             PG8_WAIT_V(8); PG8_WAIT_L(0); PG8_BAR; PG8_MMA(0, 0, At, B0); PG8_MMA(0, 1, At, B1); PG8_BAR; PG8_SCHED;
;             PG8_LDA(At, 1, 1); PG8_STAGE(PG8_SB(1, 0), b3, voffB); PG8_STAGE(PG8_SB(1, 1), b3 + hB, voffB); PG8_STAGE(PG8_SA(1, 0), a3, voffA);
;             PG8_WAIT_V(8); PG8_WAIT_L(0); PG8_BAR; if (!cur.half) { PG8_MMA(1, 0, At, B0); PG8_MMA(1, 1, At, B1); } PG8_BAR; PG8_SCHED;
;     ...
;         if constexpr (ALIGN_EPI) { if (wr == 0) PG8_BAR; }
	s_add_i32 s50, 0, 0x18000
	s_add_i32 s51, 0, 0x1c000
	v_add_u32_e32 v160, s50, v145
	v_add_u32_e32 v176, s51, v145
	ds_read_b128 v[148:151], v160
	ds_read_b128 v[152:155], v160 offset:1024
	ds_read_b128 v[156:159], v160 offset:2048
	ds_read_b128 v[160:163], v160 offset:3072
	ds_read_b128 v[164:167], v176
	ds_read_b128 v[168:171], v176 offset:1024
	ds_read_b128 v[172:175], v176 offset:2048
	ds_read_b128 v[176:179], v176 offset:3072
	s_add_u32 s30, s30, 0x40000
	s_addc_u32 s31, s31, 0
	s_add_u32 s98, s30, 0xfffc0080
	s_addc_u32 s99, s31, -1
	s_mov_b32 m0, s37
	ds_read_b128 v[180:183], v147 offset:32768
	ds_read_b128 v[184:187], v147 offset:33792
	ds_read_b128 v[188:191], v147 offset:34816
	ds_read_b128 v[192:195], v147 offset:35840
	ds_read_b128 v[214:217], v147 offset:36864
	ds_read_b128 v[218:221], v147 offset:37888
	ds_read_b128 v[222:225], v147 offset:38912
	ds_read_b128 v[226:229], v147 offset:39936
	global_load_lds_dwordx4 v134, s[30:31]
	s_mov_b32 m0, s40
	s_nop 0
	global_load_lds_dwordx4 v132, s[30:31]
	s_waitcnt vmcnt(8) lgkmcnt(0)
	s_barrier
	s_setprio 1
	v_mfma_f32_16x16x32_bf16 v[126:129], v[148:151], v[180:183], v[126:129]
	v_mfma_f32_16x16x32_bf16 v[122:125], v[156:159], v[180:183], v[122:125]
	v_mfma_f32_16x16x32_bf16 v[118:121], v[148:151], v[188:191], v[118:121]
	v_mfma_f32_16x16x32_bf16 v[114:117], v[156:159], v[188:191], v[114:117]
	v_mfma_f32_16x16x32_bf16 v[102:105], v[148:151], v[214:217], v[102:105]
	v_mfma_f32_16x16x32_bf16 v[98:101], v[156:159], v[214:217], v[98:101]
	v_mfma_f32_16x16x32_bf16 v[86:89], v[148:151], v[222:225], v[86:89]
	v_mfma_f32_16x16x32_bf16 v[82:85], v[156:159], v[222:225], v[82:85]
	v_mfma_f32_16x16x32_bf16 v[126:129], v[152:155], v[184:187], v[126:129]
	v_mfma_f32_16x16x32_bf16 v[122:125], v[160:163], v[184:187], v[122:125]
	v_mfma_f32_16x16x32_bf16 v[118:121], v[152:155], v[192:195], v[118:121]
	v_mfma_f32_16x16x32_bf16 v[114:117], v[160:163], v[192:195], v[114:117]
	v_mfma_f32_16x16x32_bf16 v[102:105], v[152:155], v[218:221], v[102:105]
	v_mfma_f32_16x16x32_bf16 v[98:101], v[160:163], v[218:221], v[98:101]
	v_mfma_f32_16x16x32_bf16 v[86:89], v[152:155], v[226:229], v[86:89]
	v_mfma_f32_16x16x32_bf16 v[82:85], v[160:163], v[226:229], v[82:85]
	s_setprio 0
	s_setprio 1
	v_mfma_f32_16x16x32_bf16 v[110:113], v[164:167], v[180:183], v[110:113]
	v_mfma_f32_16x16x32_bf16 v[106:109], v[172:175], v[180:183], v[106:109]
	v_mfma_f32_16x16x32_bf16 v[94:97], v[164:167], v[188:191], v[94:97]
	v_mfma_f32_16x16x32_bf16 v[90:93], v[172:175], v[188:191], v[90:93]
	v_mfma_f32_16x16x32_bf16 v[78:81], v[164:167], v[214:217], v[78:81]
	v_mfma_f32_16x16x32_bf16 v[74:77], v[172:175], v[214:217], v[74:77]
	v_mfma_f32_16x16x32_bf16 v[70:73], v[164:167], v[222:225], v[70:73]
	v_mfma_f32_16x16x32_bf16 v[66:69], v[172:175], v[222:225], v[66:69]
	v_mfma_f32_16x16x32_bf16 v[110:113], v[168:171], v[184:187], v[110:113]
	v_mfma_f32_16x16x32_bf16 v[106:109], v[176:179], v[184:187], v[106:109]
	v_mfma_f32_16x16x32_bf16 v[94:97], v[168:171], v[192:195], v[94:97]
	v_mfma_f32_16x16x32_bf16 v[90:93], v[176:179], v[192:195], v[90:93]
	v_mfma_f32_16x16x32_bf16 v[78:81], v[168:171], v[218:221], v[78:81]
	v_mfma_f32_16x16x32_bf16 v[74:77], v[176:179], v[218:221], v[74:77]
	v_mfma_f32_16x16x32_bf16 v[70:73], v[168:171], v[226:229], v[70:73]
	v_mfma_f32_16x16x32_bf16 v[66:69], v[176:179], v[226:229], v[66:69]
	s_setprio 0
	s_barrier
	s_add_i32 s30, s50, s34
	s_add_u32 s28, s28, 0x80
	s_addc_u32 s29, s29, 0
	s_mov_b32 m0, s30
	ds_read_b128 v[180:183], v147 offset:49152
	ds_read_b128 v[184:187], v147 offset:50176
	ds_read_b128 v[188:191], v147 offset:51200
	ds_read_b128 v[192:195], v147 offset:52224
	ds_read_b128 v[214:217], v147 offset:53248
	ds_read_b128 v[218:221], v147 offset:54272
	ds_read_b128 v[222:225], v147 offset:55296
	ds_read_b128 v[226:229], v147 offset:56320
	global_load_lds_dwordx4 v0, s[28:29]
	s_add_i32 m0, s30, 0x2000
	s_add_i32 s30, s51, s34
	global_load_lds_dwordx4 v130, s[28:29]
	s_add_u32 s28, s28, 0x40000
	s_addc_u32 s29, s29, 0
	s_mov_b32 m0, s30
	s_nop 0
	global_load_lds_dwordx4 v0, s[28:29]
	s_add_i32 m0, s30, 0x2000
	s_nop 0
	global_load_lds_dwordx4 v130, s[28:29]
	s_mov_b32 m0, s41
	s_nop 0
	global_load_lds_dwordx4 v134, s[98:99]
	s_mov_b32 m0, s42
	s_nop 0
	global_load_lds_dwordx4 v132, s[98:99]
	s_waitcnt vmcnt(8) lgkmcnt(0)
	s_barrier
	s_setprio 1
	v_mfma_f32_16x16x32_bf16 v[62:65], v[148:151], v[180:183], v[62:65]
	v_mfma_f32_16x16x32_bf16 v[58:61], v[156:159], v[180:183], v[58:61]
	v_mfma_f32_16x16x32_bf16 v[54:57], v[148:151], v[188:191], v[54:57]
	v_mfma_f32_16x16x32_bf16 v[50:53], v[156:159], v[188:191], v[50:53]
	v_mfma_f32_16x16x32_bf16 v[38:41], v[148:151], v[214:217], v[38:41]
	v_mfma_f32_16x16x32_bf16 v[34:37], v[156:159], v[214:217], v[34:37]
	v_mfma_f32_16x16x32_bf16 v[22:25], v[148:151], v[222:225], v[22:25]
	v_mfma_f32_16x16x32_bf16 v[18:21], v[156:159], v[222:225], v[18:21]
	v_mfma_f32_16x16x32_bf16 v[62:65], v[152:155], v[184:187], v[62:65]
	v_mfma_f32_16x16x32_bf16 v[58:61], v[160:163], v[184:187], v[58:61]
	v_mfma_f32_16x16x32_bf16 v[54:57], v[152:155], v[192:195], v[54:57]
	v_mfma_f32_16x16x32_bf16 v[50:53], v[160:163], v[192:195], v[50:53]
	v_mfma_f32_16x16x32_bf16 v[38:41], v[152:155], v[218:221], v[38:41]
	v_mfma_f32_16x16x32_bf16 v[34:37], v[160:163], v[218:221], v[34:37]
	v_mfma_f32_16x16x32_bf16 v[22:25], v[152:155], v[226:229], v[22:25]
	v_mfma_f32_16x16x32_bf16 v[18:21], v[160:163], v[226:229], v[18:21]
	s_setprio 0
	s_setprio 1
	v_mfma_f32_16x16x32_bf16 v[46:49], v[164:167], v[180:183], v[46:49]
	v_mfma_f32_16x16x32_bf16 v[42:45], v[172:175], v[180:183], v[42:45]
	v_mfma_f32_16x16x32_bf16 v[30:33], v[164:167], v[188:191], v[30:33]
	v_mfma_f32_16x16x32_bf16 v[26:29], v[172:175], v[188:191], v[26:29]
	v_mfma_f32_16x16x32_bf16 v[14:17], v[164:167], v[214:217], v[14:17]
	v_mfma_f32_16x16x32_bf16 v[10:13], v[172:175], v[214:217], v[10:13]
	v_mfma_f32_16x16x32_bf16 v[6:9], v[164:167], v[222:225], v[6:9]
	v_mfma_f32_16x16x32_bf16 v[2:5], v[172:175], v[222:225], v[2:5]
	v_mfma_f32_16x16x32_bf16 v[46:49], v[168:171], v[184:187], v[46:49]
	v_mfma_f32_16x16x32_bf16 v[42:45], v[176:179], v[184:187], v[42:45]
	v_mfma_f32_16x16x32_bf16 v[30:33], v[168:171], v[192:195], v[30:33]
	v_mfma_f32_16x16x32_bf16 v[26:29], v[176:179], v[192:195], v[26:29]
	v_mfma_f32_16x16x32_bf16 v[14:17], v[168:171], v[218:221], v[14:17]
	v_mfma_f32_16x16x32_bf16 v[10:13], v[176:179], v[218:221], v[10:13]
	v_mfma_f32_16x16x32_bf16 v[6:9], v[168:171], v[226:229], v[6:9]
	v_mfma_f32_16x16x32_bf16 v[2:5], v[176:179], v[226:229], v[2:5]
	s_setprio 0
	s_barrier
	s_add_i32 s49, s49, 2
	s_add_u32 s26, s26, 0x100
	s_addc_u32 s27, s27, 0
	s_add_u32 s47, s47, 0x100
	s_addc_u32 s48, s48, 0
	s_cmp_gt_u32 s49, 13
	s_cbranch_scc0 .LBB0_516
	s_and_b64 vcc, exec, s[8:9]
	s_cbranch_vccnz .LBB0_521
	v_lshl_add_u32 v142, s16, 8, v144
	s_cmp_gt_i32 s46, 25
	s_mov_b64 s[2:3], -1
	s_cbranch_scc1 .LBB0_522

; #define PG8_STAGE(bufoff, gbase, voff) do { _Pragma("unroll") for (int _i = 0; _i < 2; ++_i) \
;         __builtin_amdgcn_global_load_lds((const unsigned*)((const char*)(gbase) + (voff)[_i]), (LAS unsigned*)(lds + (bufoff) + ldsw + _i * 8192), 16, 0, 0); } while (0)
; #define PG8_LDA(dst, b, h) do { _Pragma("unroll") for (int m = 0; m < 4; ++m) _Pragma("unroll") for (int k = 0; k < 2; ++k) dst[m][k] = *(const LAS f16x8*)(lds + PG8_SA(b, h) + aoff + m * 2048 + k * 1024); } while (0)
; #define PG8_LDB(dst, b, h) do { _Pragma("unroll") for (int n = 0; n < 2; ++n) _Pragma("unroll") for (int k = 0; k < 2; ++k) dst[n][k] = *(const LAS f16x8*)(lds + PG8_SB(b, h) + boff + n * 2048 + k * 1024); } while (0)
; #define PG8_MMA(ai, bj, At, Bt) do { __builtin_amdgcn_s_setprio(1); _Pragma("unroll") for (int m = 0; m < 4; ++m) _Pragma("unroll") for (int n = 0; n < 2; ++n) _Pragma("unroll") for (int k = 0; k < 2; ++k) \
;         acc[ai][bj][m][n] = mma16_<Epi::BF16>(Bt[n][k], At[m][k], acc[ai][bj][m][n]); __builtin_amdgcn_s_setprio(0); } while (0)
; #define PG8_WAIT_V(n) asm volatile("s_waitcnt vmcnt(" #n ")" ::: "memory")
; #define PG8_WAIT_L(n) asm volatile("s_waitcnt lgkmcnt(" #n ")" ::: "memory")
; #define PG8_BAR __builtin_amdgcn_s_barrier()
; #define PG8_SCHED __builtin_amdgcn_sched_barrier(0)
;     ...
;             const char* a1 = cA + (size_t)(t + 1) * kstep;
;             const char* a2 = last ? nA : cA + (size_t)(t + 2) * kstep; const char* b2 = last ? nB : cB + (size_t)(t + 2) * kstep;
;             const char* a3 = a2 + kstep; const char* b3 = b2 + kstep;
;             if constexpr (SP2) {
;             PG8_LDB(B0, 0, 0); PG8_LDB(B1, 0, 1); PG8_SCHED; PG8_LDA(At, 0, 0); PG8_STAGE(PG8_SA(1, 1), a1 + hA, voffA);
;             PG8_WAIT_V(8); PG8_WAIT_L(0); PG8_BAR; PG8_MMA(0, 0, At, B0); PG8_MMA(0, 1, At, B1); PG8_BAR; PG8_SCHED;
;             PG8_LDA(At, 0, 1); PG8_STAGE(PG8_SB(0, 0), b2, voffB); PG8_STAGE(PG8_SB(0, 1), b2 + hB, voffB); PG8_STAGE(PG8_SA(0, 0), a2, voffA);
;             PG8_WAIT_V(8); PG8_WAIT_L(0); PG8_BAR; if (!cur.half) { PG8_MMA(1, 0, At, B0); PG8_MMA(1, 1, At, B1); } PG8_BAR; PG8_SCHED;
.LBB0_758:
	s_mov_b64 s[30:31], s[10:11]
	s_add_u32 s10, s30, 0x100
	s_addc_u32 s11, s31, 0
	s_add_i32 s40, 0, 0x10000
	s_cmp_eq_u32 s59, 12
	s_cselect_b32 s29, s43, s11
	s_cselect_b32 s28, s42, s10
	v_add_u32_e32 v0, s40, v233
	s_cselect_b32 s27, s2, s58
	s_cselect_b32 s26, s3, s23
	s_add_i32 s41, 0, 0x14000
	ds_read_b128 v[148:151], v0
	ds_read_b128 v[152:155], v0 offset:1024
	ds_read_b128 v[156:159], v0 offset:2048
	ds_read_b128 v[160:163], v0 offset:3072
	v_add_u32_e32 v0, s41, v233
	ds_read_b128 v[132:135], v0
	ds_read_b128 v[136:139], v0 offset:1024
	ds_read_b128 v[140:143], v0 offset:2048
	ds_read_b128 v[144:147], v0 offset:3072
	s_add_i32 m0, s9, 0xc000
	s_waitcnt lgkmcnt(0)
	ds_read_b128 v[164:167], v243
	ds_read_b128 v[168:171], v243 offset:1024
	ds_read_b128 v[172:175], v243 offset:2048
	ds_read_b128 v[176:179], v243 offset:3072
	ds_read_b128 v[180:183], v243 offset:4096
	ds_read_b128 v[184:187], v243 offset:5120
	ds_read_b128 v[188:191], v243 offset:6144
	ds_read_b128 v[192:195], v243 offset:7168
	global_load_lds_dwordx4 v222, s[30:31]
	s_add_i32 m0, s9, 0xe000
	s_nop 0
	global_load_lds_dwordx4 v224, s[30:31]
	s_waitcnt vmcnt(8) lgkmcnt(0)
	s_barrier
	s_setprio 1
	v_mfma_f32_16x16x32_f16 v[128:131], v[148:151], v[164:167], v[128:131]
	v_mfma_f32_16x16x32_f16 v[124:127], v[156:159], v[164:167], v[124:127]
	v_mfma_f32_16x16x32_f16 v[112:115], v[148:151], v[172:175], v[112:115]
	v_mfma_f32_16x16x32_f16 v[108:111], v[156:159], v[172:175], v[108:111]
	v_mfma_f32_16x16x32_f16 v[96:99], v[148:151], v[180:183], v[96:99]
	v_mfma_f32_16x16x32_f16 v[92:95], v[156:159], v[180:183], v[92:95]
	v_mfma_f32_16x16x32_f16 v[80:83], v[148:151], v[188:191], v[80:83]
	v_mfma_f32_16x16x32_f16 v[76:79], v[156:159], v[188:191], v[76:79]
	v_mfma_f32_16x16x32_f16 v[128:131], v[152:155], v[168:171], v[128:131]
	v_mfma_f32_16x16x32_f16 v[124:127], v[160:163], v[168:171], v[124:127]
	v_mfma_f32_16x16x32_f16 v[112:115], v[152:155], v[176:179], v[112:115]
	v_mfma_f32_16x16x32_f16 v[108:111], v[160:163], v[176:179], v[108:111]
	v_mfma_f32_16x16x32_f16 v[96:99], v[152:155], v[184:187], v[96:99]
	v_mfma_f32_16x16x32_f16 v[92:95], v[160:163], v[184:187], v[92:95]
	v_mfma_f32_16x16x32_f16 v[80:83], v[152:155], v[192:195], v[80:83]
	v_mfma_f32_16x16x32_f16 v[76:79], v[160:163], v[192:195], v[76:79]
	s_setprio 0
	s_setprio 1
	v_mfma_f32_16x16x32_f16 v[120:123], v[132:135], v[164:167], v[120:123]
	v_mfma_f32_16x16x32_f16 v[116:119], v[140:143], v[164:167], v[116:119]
	v_mfma_f32_16x16x32_f16 v[104:107], v[132:135], v[172:175], v[104:107]
	v_mfma_f32_16x16x32_f16 v[100:103], v[140:143], v[172:175], v[100:103]
	v_mfma_f32_16x16x32_f16 v[88:91], v[132:135], v[180:183], v[88:91]
	v_mfma_f32_16x16x32_f16 v[84:87], v[140:143], v[180:183], v[84:87]
	v_mfma_f32_16x16x32_f16 v[72:75], v[132:135], v[188:191], v[72:75]
	v_mfma_f32_16x16x32_f16 v[68:71], v[140:143], v[188:191], v[68:71]
	v_mfma_f32_16x16x32_f16 v[120:123], v[136:139], v[168:171], v[120:123]
	v_mfma_f32_16x16x32_f16 v[116:119], v[144:147], v[168:171], v[116:119]
	v_mfma_f32_16x16x32_f16 v[104:107], v[136:139], v[176:179], v[104:107]
	v_mfma_f32_16x16x32_f16 v[100:103], v[144:147], v[176:179], v[100:103]
	v_mfma_f32_16x16x32_f16 v[88:91], v[136:139], v[184:187], v[88:91]
	v_mfma_f32_16x16x32_f16 v[84:87], v[144:147], v[184:187], v[84:87]
	v_mfma_f32_16x16x32_f16 v[72:75], v[136:139], v[192:195], v[72:75]
	v_mfma_f32_16x16x32_f16 v[68:71], v[144:147], v[192:195], v[68:71]
	s_setprio 0
	s_barrier
	s_add_i32 s30, s40, s35
	s_mov_b32 m0, s30
	ds_read_b128 v[188:191], v243 offset:16384
	ds_read_b128 v[192:195], v243 offset:17408
	ds_read_b128 v[180:183], v243 offset:18432
	ds_read_b128 v[184:187], v243 offset:19456
	ds_read_b128 v[172:175], v243 offset:20480
	ds_read_b128 v[176:179], v243 offset:21504
	ds_read_b128 v[164:167], v243 offset:22528
	ds_read_b128 v[168:171], v243 offset:23552
	global_load_lds_dwordx4 v216, s[26:27]
	s_add_i32 m0, s30, 0x2000
	s_add_u32 s30, s26, 0x40000
	s_addc_u32 s31, s27, 0
	s_add_i32 s40, s41, s35
	global_load_lds_dwordx4 v220, s[26:27]
	s_mov_b32 m0, s40
	s_nop 0
	global_load_lds_dwordx4 v216, s[30:31]
	s_add_i32 m0, s40, 0x2000
	s_nop 0
	global_load_lds_dwordx4 v220, s[30:31]
	s_mov_b32 m0, s9
	v_cndmask_b32_e64 v0, 0, 1, s[24:25]
	global_load_lds_dwordx4 v214, s[28:29]
	s_mov_b32 m0, s36
	v_cmp_ne_u32_e64 s[40:41], 1, v0
	global_load_lds_dwordx4 v218, s[28:29]
	s_waitcnt vmcnt(8) lgkmcnt(0)
	s_andn2_b64 vcc, exec, s[24:25]
	s_barrier
	s_cbranch_vccnz .LBB0_760
	s_setprio 1
	v_mfma_f32_16x16x32_f16 v[64:67], v[148:151], v[188:191], v[64:67]
	v_mfma_f32_16x16x32_f16 v[60:63], v[156:159], v[188:191], v[60:63]
	v_mfma_f32_16x16x32_f16 v[48:51], v[148:151], v[180:183], v[48:51]
	v_mfma_f32_16x16x32_f16 v[44:47], v[156:159], v[180:183], v[44:47]
	v_mfma_f32_16x16x32_f16 v[32:35], v[148:151], v[172:175], v[32:35]
	v_mfma_f32_16x16x32_f16 v[28:31], v[156:159], v[172:175], v[28:31]
	v_mfma_f32_16x16x32_f16 v[16:19], v[148:151], v[164:167], v[16:19]
	v_mfma_f32_16x16x32_f16 v[12:15], v[156:159], v[164:167], v[12:15]
	v_mfma_f32_16x16x32_f16 v[64:67], v[152:155], v[192:195], v[64:67]
	v_mfma_f32_16x16x32_f16 v[60:63], v[160:163], v[192:195], v[60:63]
	v_mfma_f32_16x16x32_f16 v[48:51], v[152:155], v[184:187], v[48:51]
	v_mfma_f32_16x16x32_f16 v[44:47], v[160:163], v[184:187], v[44:47]
	v_mfma_f32_16x16x32_f16 v[32:35], v[152:155], v[176:179], v[32:35]
	v_mfma_f32_16x16x32_f16 v[28:31], v[160:163], v[176:179], v[28:31]
	v_mfma_f32_16x16x32_f16 v[16:19], v[152:155], v[168:171], v[16:19]
	v_mfma_f32_16x16x32_f16 v[12:15], v[160:163], v[168:171], v[12:15]
	s_setprio 0
	s_setprio 1
	v_mfma_f32_16x16x32_f16 v[56:59], v[132:135], v[188:191], v[56:59]
	v_mfma_f32_16x16x32_f16 v[52:55], v[140:143], v[188:191], v[52:55]
	v_mfma_f32_16x16x32_f16 v[40:43], v[132:135], v[180:183], v[40:43]
	v_mfma_f32_16x16x32_f16 v[36:39], v[140:143], v[180:183], v[36:39]
	v_mfma_f32_16x16x32_f16 v[24:27], v[132:135], v[172:175], v[24:27]
	v_mfma_f32_16x16x32_f16 v[20:23], v[140:143], v[172:175], v[20:23]
	v_mfma_f32_16x16x32_f16 v[8:11], v[132:135], v[164:167], v[8:11]
	v_mfma_f32_16x16x32_f16 v[4:7], v[140:143], v[164:167], v[4:7]
	v_mfma_f32_16x16x32_f16 v[56:59], v[136:139], v[192:195], v[56:59]
	v_mfma_f32_16x16x32_f16 v[52:55], v[144:147], v[192:195], v[52:55]
	v_mfma_f32_16x16x32_f16 v[40:43], v[136:139], v[184:187], v[40:43]
	v_mfma_f32_16x16x32_f16 v[36:39], v[144:147], v[184:187], v[36:39]
	v_mfma_f32_16x16x32_f16 v[24:27], v[136:139], v[176:179], v[24:27]
	v_mfma_f32_16x16x32_f16 v[20:23], v[144:147], v[176:179], v[20:23]
	v_mfma_f32_16x16x32_f16 v[8:11], v[136:139], v[168:171], v[8:11]
	v_mfma_f32_16x16x32_f16 v[4:7], v[144:147], v[168:171], v[4:7]
	s_setprio 0
; #define PG8_STAGE(bufoff, gbase, voff) do { _Pragma("unroll") for (int _i = 0; _i < 2; ++_i) \
;         __builtin_amdgcn_global_load_lds((const unsigned*)((const char*)(gbase) + (voff)[_i]), (LAS unsigned*)(lds + (bufoff) + ldsw + _i * 8192), 16, 0, 0); } while (0)
; #define PG8_LDA(dst, b, h) do { _Pragma("unroll") for (int m = 0; m < 4; ++m) _Pragma("unroll") for (int k = 0; k < 2; ++k) dst[m][k] = *(const LAS f16x8*)(lds + PG8_SA(b, h) + aoff + m * 2048 + k * 1024); } while (0)
; #define PG8_LDB(dst, b, h) do { _Pragma("unroll") for (int n = 0; n < 2; ++n) _Pragma("unroll") for (int k = 0; k < 2; ++k) dst[n][k] = *(const LAS f16x8*)(lds + PG8_SB(b, h) + boff + n * 2048 + k * 1024); } while (0)
; #define PG8_MMA(ai, bj, At, Bt) do { __builtin_amdgcn_s_setprio(1); _Pragma("unroll") for (int m = 0; m < 4; ++m) _Pragma("unroll") for (int n = 0; n < 2; ++n) _Pragma("unroll") for (int k = 0; k < 2; ++k) \
;         acc[ai][bj][m][n] = mma16_<Epi::BF16>(Bt[n][k], At[m][k], acc[ai][bj][m][n]); __builtin_amdgcn_s_setprio(0); } while (0)
; #define PG8_WAIT_V(n) asm volatile("s_waitcnt vmcnt(" #n ")" ::: "memory")
; #define PG8_WAIT_L(n) asm volatile("s_waitcnt lgkmcnt(" #n ")" ::: "memory")
; #define PG8_BAR __builtin_amdgcn_s_barrier()
; #define PG8_SCHED __builtin_amdgcn_sched_barrier(0)
;     ...
;             PG8_LDB(B0, 1, 0); PG8_LDB(B1, 1, 1); PG8_SCHED; PG8_LDA(At, 1, 0); PG8_STAGE(PG8_SA(0, 1), a2 + hA, voffA);
;             PG8_WAIT_V(8); PG8_WAIT_L(0); PG8_BAR; PG8_MMA(0, 0, At, B0); PG8_MMA(0, 1, At, B1); PG8_BAR; PG8_SCHED;
;             PG8_LDA(At, 1, 1); PG8_STAGE(PG8_SB(1, 0), b3, voffB); PG8_STAGE(PG8_SB(1, 1), b3 + hB, voffB); PG8_STAGE(PG8_SA(1, 0), a3, voffA);
;             PG8_WAIT_V(8); PG8_WAIT_L(0); PG8_BAR; if (!cur.half) { PG8_MMA(1, 0, At, B0); PG8_MMA(1, 1, At, B1); } PG8_BAR; PG8_SCHED;
.LBB0_760:
	s_barrier
	s_add_i32 s30, 0, 0x18000
	v_add_u32_e32 v0, s30, v233
	s_add_i32 s31, 0, 0x1c000
	ds_read_b128 v[148:151], v0
	ds_read_b128 v[152:155], v0 offset:1024
	ds_read_b128 v[156:159], v0 offset:2048
	ds_read_b128 v[160:163], v0 offset:3072
	v_add_u32_e32 v0, s31, v233
	ds_read_b128 v[132:135], v0
	ds_read_b128 v[136:139], v0 offset:1024
	ds_read_b128 v[140:143], v0 offset:2048
	ds_read_b128 v[144:147], v0 offset:3072
	s_add_u32 s28, s28, 0x1a0000
	s_addc_u32 s29, s29, 0
	s_add_u32 s98, s28, 0xffe60080
	s_addc_u32 s99, s29, -1
	s_mov_b32 m0, s37
	s_waitcnt lgkmcnt(0)
	ds_read_b128 v[164:167], v243 offset:32768
	ds_read_b128 v[168:171], v243 offset:33792
	ds_read_b128 v[172:175], v243 offset:34816
	ds_read_b128 v[176:179], v243 offset:35840
	ds_read_b128 v[180:183], v243 offset:36864
	ds_read_b128 v[184:187], v243 offset:37888
	ds_read_b128 v[188:191], v243 offset:38912
	ds_read_b128 v[192:195], v243 offset:39936
	global_load_lds_dwordx4 v214, s[28:29]
	s_mov_b32 m0, s48
	s_nop 0
	global_load_lds_dwordx4 v218, s[28:29]
	s_waitcnt vmcnt(8) lgkmcnt(0)
	s_barrier
	s_setprio 1
	v_mfma_f32_16x16x32_f16 v[128:131], v[148:151], v[164:167], v[128:131]
	v_mfma_f32_16x16x32_f16 v[124:127], v[156:159], v[164:167], v[124:127]
	v_mfma_f32_16x16x32_f16 v[112:115], v[148:151], v[172:175], v[112:115]
	v_mfma_f32_16x16x32_f16 v[108:111], v[156:159], v[172:175], v[108:111]
	v_mfma_f32_16x16x32_f16 v[96:99], v[148:151], v[180:183], v[96:99]
	v_mfma_f32_16x16x32_f16 v[92:95], v[156:159], v[180:183], v[92:95]
	v_mfma_f32_16x16x32_f16 v[80:83], v[148:151], v[188:191], v[80:83]
	v_mfma_f32_16x16x32_f16 v[76:79], v[156:159], v[188:191], v[76:79]
	v_mfma_f32_16x16x32_f16 v[128:131], v[152:155], v[168:171], v[128:131]
	v_mfma_f32_16x16x32_f16 v[124:127], v[160:163], v[168:171], v[124:127]
	v_mfma_f32_16x16x32_f16 v[112:115], v[152:155], v[176:179], v[112:115]
	v_mfma_f32_16x16x32_f16 v[108:111], v[160:163], v[176:179], v[108:111]
	v_mfma_f32_16x16x32_f16 v[96:99], v[152:155], v[184:187], v[96:99]
	v_mfma_f32_16x16x32_f16 v[92:95], v[160:163], v[184:187], v[92:95]
	v_mfma_f32_16x16x32_f16 v[80:83], v[152:155], v[192:195], v[80:83]
	v_mfma_f32_16x16x32_f16 v[76:79], v[160:163], v[192:195], v[76:79]
	s_setprio 0
	s_setprio 1
	v_mfma_f32_16x16x32_f16 v[120:123], v[132:135], v[164:167], v[120:123]
	v_mfma_f32_16x16x32_f16 v[116:119], v[140:143], v[164:167], v[116:119]
	v_mfma_f32_16x16x32_f16 v[104:107], v[132:135], v[172:175], v[104:107]
	v_mfma_f32_16x16x32_f16 v[100:103], v[140:143], v[172:175], v[100:103]
	v_mfma_f32_16x16x32_f16 v[88:91], v[132:135], v[180:183], v[88:91]
	v_mfma_f32_16x16x32_f16 v[84:87], v[140:143], v[180:183], v[84:87]
	v_mfma_f32_16x16x32_f16 v[72:75], v[132:135], v[188:191], v[72:75]
	v_mfma_f32_16x16x32_f16 v[68:71], v[140:143], v[188:191], v[68:71]
	v_mfma_f32_16x16x32_f16 v[120:123], v[136:139], v[168:171], v[120:123]
	v_mfma_f32_16x16x32_f16 v[116:119], v[144:147], v[168:171], v[116:119]
	v_mfma_f32_16x16x32_f16 v[104:107], v[136:139], v[176:179], v[104:107]
	v_mfma_f32_16x16x32_f16 v[100:103], v[144:147], v[176:179], v[100:103]
	v_mfma_f32_16x16x32_f16 v[88:91], v[136:139], v[184:187], v[88:91]
	v_mfma_f32_16x16x32_f16 v[84:87], v[144:147], v[184:187], v[84:87]
	v_mfma_f32_16x16x32_f16 v[72:75], v[136:139], v[192:195], v[72:75]
	v_mfma_f32_16x16x32_f16 v[68:71], v[144:147], v[192:195], v[68:71]
	s_setprio 0
	s_barrier
	s_add_i32 s28, s30, s35
	s_add_u32 s26, s26, 0x80
	s_addc_u32 s27, s27, 0
	s_mov_b32 m0, s28
	ds_read_b128 v[188:191], v243 offset:49152
	ds_read_b128 v[192:195], v243 offset:50176
	ds_read_b128 v[180:183], v243 offset:51200
	ds_read_b128 v[184:187], v243 offset:52224
	ds_read_b128 v[172:175], v243 offset:53248
	ds_read_b128 v[176:179], v243 offset:54272
	ds_read_b128 v[164:167], v243 offset:55296
	ds_read_b128 v[168:171], v243 offset:56320
	global_load_lds_dwordx4 v216, s[26:27]
	s_add_i32 m0, s28, 0x2000
	s_add_i32 s28, s31, s35
	global_load_lds_dwordx4 v220, s[26:27]
	s_add_u32 s26, s26, 0x40000
	s_addc_u32 s27, s27, 0
	s_mov_b32 m0, s28
	s_and_b64 vcc, exec, s[40:41]
	global_load_lds_dwordx4 v216, s[26:27]
	s_add_i32 m0, s28, 0x2000
	s_nop 0
	global_load_lds_dwordx4 v220, s[26:27]
	s_mov_b32 m0, s49
	s_nop 0
	global_load_lds_dwordx4 v214, s[98:99]
	s_mov_b32 m0, s50
	s_nop 0
	global_load_lds_dwordx4 v218, s[98:99]
	s_waitcnt vmcnt(8) lgkmcnt(0)
	s_barrier
	s_cbranch_vccnz .LBB0_757
	s_setprio 1
	v_mfma_f32_16x16x32_f16 v[64:67], v[148:151], v[188:191], v[64:67]
	v_mfma_f32_16x16x32_f16 v[60:63], v[156:159], v[188:191], v[60:63]
	v_mfma_f32_16x16x32_f16 v[48:51], v[148:151], v[180:183], v[48:51]
	v_mfma_f32_16x16x32_f16 v[44:47], v[156:159], v[180:183], v[44:47]
	v_mfma_f32_16x16x32_f16 v[32:35], v[148:151], v[172:175], v[32:35]
	v_mfma_f32_16x16x32_f16 v[28:31], v[156:159], v[172:175], v[28:31]
	v_mfma_f32_16x16x32_f16 v[16:19], v[148:151], v[164:167], v[16:19]
	v_mfma_f32_16x16x32_f16 v[12:15], v[156:159], v[164:167], v[12:15]
	v_mfma_f32_16x16x32_f16 v[64:67], v[152:155], v[192:195], v[64:67]
	v_mfma_f32_16x16x32_f16 v[60:63], v[160:163], v[192:195], v[60:63]
	v_mfma_f32_16x16x32_f16 v[48:51], v[152:155], v[184:187], v[48:51]
	v_mfma_f32_16x16x32_f16 v[44:47], v[160:163], v[184:187], v[44:47]
	v_mfma_f32_16x16x32_f16 v[32:35], v[152:155], v[176:179], v[32:35]
	v_mfma_f32_16x16x32_f16 v[28:31], v[160:163], v[176:179], v[28:31]
	v_mfma_f32_16x16x32_f16 v[16:19], v[152:155], v[168:171], v[16:19]
	v_mfma_f32_16x16x32_f16 v[12:15], v[160:163], v[168:171], v[12:15]
	s_setprio 0
	s_setprio 1
	v_mfma_f32_16x16x32_f16 v[56:59], v[132:135], v[188:191], v[56:59]
	v_mfma_f32_16x16x32_f16 v[52:55], v[140:143], v[188:191], v[52:55]
	v_mfma_f32_16x16x32_f16 v[40:43], v[132:135], v[180:183], v[40:43]
	v_mfma_f32_16x16x32_f16 v[36:39], v[140:143], v[180:183], v[36:39]
	v_mfma_f32_16x16x32_f16 v[24:27], v[132:135], v[172:175], v[24:27]
	v_mfma_f32_16x16x32_f16 v[20:23], v[140:143], v[172:175], v[20:23]
	v_mfma_f32_16x16x32_f16 v[8:11], v[132:135], v[164:167], v[8:11]
	v_mfma_f32_16x16x32_f16 v[2:5], v[140:143], v[164:167], v[4:7]
	v_mfma_f32_16x16x32_f16 v[56:59], v[136:139], v[192:195], v[56:59]
	v_mfma_f32_16x16x32_f16 v[52:55], v[144:147], v[192:195], v[52:55]
	v_mfma_f32_16x16x32_f16 v[40:43], v[136:139], v[184:187], v[40:43]
	v_mfma_f32_16x16x32_f16 v[36:39], v[144:147], v[184:187], v[36:39]
	v_mfma_f32_16x16x32_f16 v[24:27], v[136:139], v[176:179], v[24:27]
	v_mfma_f32_16x16x32_f16 v[20:23], v[144:147], v[176:179], v[20:23]
	v_mfma_f32_16x16x32_f16 v[8:11], v[136:139], v[168:171], v[8:11]
	v_mfma_f32_16x16x32_f16 v[4:7], v[144:147], v[168:171], v[2:5]
	s_setprio 0
	s_branch .LBB0_757

; #define PG8_STAGE(bufoff, gbase, voff) do { _Pragma("unroll") for (int _i = 0; _i < 2; ++_i) \
;         __builtin_amdgcn_global_load_lds((const unsigned*)((const char*)(gbase) + (voff)[_i]), (LAS unsigned*)(lds + (bufoff) + ldsw + _i * 8192), 16, 0, 0); } while (0)
; #define PG8_LDA(dst, b, h) do { _Pragma("unroll") for (int m = 0; m < 4; ++m) _Pragma("unroll") for (int k = 0; k < 2; ++k) dst[m][k] = *(const LAS f16x8*)(lds + PG8_SA(b, h) + aoff + m * 2048 + k * 1024); } while (0)
; #define PG8_LDB(dst, b, h) do { _Pragma("unroll") for (int n = 0; n < 2; ++n) _Pragma("unroll") for (int k = 0; k < 2; ++k) dst[n][k] = *(const LAS f16x8*)(lds + PG8_SB(b, h) + boff + n * 2048 + k * 1024); } while (0)
; #define PG8_MMA(ai, bj, At, Bt) do { __builtin_amdgcn_s_setprio(1); _Pragma("unroll") for (int m = 0; m < 4; ++m) _Pragma("unroll") for (int n = 0; n < 2; ++n) _Pragma("unroll") for (int k = 0; k < 2; ++k) \
;         acc[ai][bj][m][n] = mma16_<Epi::BF16>(Bt[n][k], At[m][k], acc[ai][bj][m][n]); __builtin_amdgcn_s_setprio(0); } while (0)
; #define PG8_WAIT_V(n) asm volatile("s_waitcnt vmcnt(" #n ")" ::: "memory")
; #define PG8_WAIT_L(n) asm volatile("s_waitcnt lgkmcnt(" #n ")" ::: "memory")
; #define PG8_BAR __builtin_amdgcn_s_barrier()
; #define PG8_SCHED __builtin_amdgcn_sched_barrier(0)
;     ...
;             const char* a1 = cA + (size_t)(t + 1) * kstep;
;             const char* a2 = last ? nA : cA + (size_t)(t + 2) * kstep; const char* b2 = last ? nB : cB + (size_t)(t + 2) * kstep;
;             const char* a3 = a2 + kstep; const char* b3 = b2 + kstep;
;             if constexpr (SP2) {
;             PG8_LDB(B0, 0, 0); PG8_LDB(B1, 0, 1); PG8_SCHED; PG8_LDA(At, 0, 0); PG8_STAGE(PG8_SA(1, 1), a1 + hA, voffA);
;             PG8_WAIT_V(8); PG8_WAIT_L(0); PG8_BAR; PG8_MMA(0, 0, At, B0); PG8_MMA(0, 1, At, B1); PG8_BAR; PG8_SCHED;
;             PG8_LDA(At, 0, 1); PG8_STAGE(PG8_SB(0, 0), b2, voffB); PG8_STAGE(PG8_SB(0, 1), b2 + hB, voffB); PG8_STAGE(PG8_SA(0, 0), a2, voffA);
;             PG8_WAIT_V(8); PG8_WAIT_L(0); PG8_BAR; if (!cur.half) { PG8_MMA(1, 0, At, B0); PG8_MMA(1, 1, At, B1); } PG8_BAR; PG8_SCHED;
.LBB0_798:
	s_mov_b64 s[24:25], s[10:11]
	s_add_u32 s10, s24, 0x100
	s_addc_u32 s11, s25, 0
	s_add_i32 s40, 0, 0x10000
	s_cmp_eq_u32 s59, 12
	s_cselect_b32 s23, s51, s11
	s_cselect_b32 s22, s50, s10
	v_add_u32_e32 v0, s40, v233
	s_cselect_b32 s21, s2, s58
	s_cselect_b32 s20, s3, s49
	s_add_i32 s41, 0, 0x14000
	ds_read_b128 v[148:151], v0
	ds_read_b128 v[152:155], v0 offset:1024
	ds_read_b128 v[156:159], v0 offset:2048
	ds_read_b128 v[160:163], v0 offset:3072
	v_add_u32_e32 v0, s41, v233
	ds_read_b128 v[132:135], v0
	ds_read_b128 v[136:139], v0 offset:1024
	ds_read_b128 v[140:143], v0 offset:2048
	ds_read_b128 v[144:147], v0 offset:3072
	s_add_i32 m0, s9, 0xc000
	s_waitcnt lgkmcnt(0)
	ds_read_b128 v[164:167], v243
	ds_read_b128 v[168:171], v243 offset:1024
	ds_read_b128 v[172:175], v243 offset:2048
	ds_read_b128 v[176:179], v243 offset:3072
	ds_read_b128 v[180:183], v243 offset:4096
	ds_read_b128 v[184:187], v243 offset:5120
	ds_read_b128 v[188:191], v243 offset:6144
	ds_read_b128 v[192:195], v243 offset:7168
	global_load_lds_dwordx4 v222, s[24:25]
	s_add_i32 m0, s9, 0xe000
	s_nop 0
	global_load_lds_dwordx4 v224, s[24:25]
	s_waitcnt vmcnt(8) lgkmcnt(0)
	s_barrier
	s_setprio 1
	v_mfma_f32_16x16x32_f16 v[128:131], v[148:151], v[164:167], v[128:131]
	v_mfma_f32_16x16x32_f16 v[124:127], v[156:159], v[164:167], v[124:127]
	v_mfma_f32_16x16x32_f16 v[112:115], v[148:151], v[172:175], v[112:115]
	v_mfma_f32_16x16x32_f16 v[108:111], v[156:159], v[172:175], v[108:111]
	v_mfma_f32_16x16x32_f16 v[96:99], v[148:151], v[180:183], v[96:99]
	v_mfma_f32_16x16x32_f16 v[92:95], v[156:159], v[180:183], v[92:95]
	v_mfma_f32_16x16x32_f16 v[80:83], v[148:151], v[188:191], v[80:83]
	v_mfma_f32_16x16x32_f16 v[76:79], v[156:159], v[188:191], v[76:79]
	v_mfma_f32_16x16x32_f16 v[128:131], v[152:155], v[168:171], v[128:131]
	v_mfma_f32_16x16x32_f16 v[124:127], v[160:163], v[168:171], v[124:127]
	v_mfma_f32_16x16x32_f16 v[112:115], v[152:155], v[176:179], v[112:115]
	v_mfma_f32_16x16x32_f16 v[108:111], v[160:163], v[176:179], v[108:111]
	v_mfma_f32_16x16x32_f16 v[96:99], v[152:155], v[184:187], v[96:99]
	v_mfma_f32_16x16x32_f16 v[92:95], v[160:163], v[184:187], v[92:95]
	v_mfma_f32_16x16x32_f16 v[80:83], v[152:155], v[192:195], v[80:83]
	v_mfma_f32_16x16x32_f16 v[76:79], v[160:163], v[192:195], v[76:79]
	s_setprio 0
	s_setprio 1
	v_mfma_f32_16x16x32_f16 v[120:123], v[132:135], v[164:167], v[120:123]
	v_mfma_f32_16x16x32_f16 v[116:119], v[140:143], v[164:167], v[116:119]
	v_mfma_f32_16x16x32_f16 v[104:107], v[132:135], v[172:175], v[104:107]
	v_mfma_f32_16x16x32_f16 v[100:103], v[140:143], v[172:175], v[100:103]
	v_mfma_f32_16x16x32_f16 v[88:91], v[132:135], v[180:183], v[88:91]
	v_mfma_f32_16x16x32_f16 v[84:87], v[140:143], v[180:183], v[84:87]
	v_mfma_f32_16x16x32_f16 v[72:75], v[132:135], v[188:191], v[72:75]
	v_mfma_f32_16x16x32_f16 v[68:71], v[140:143], v[188:191], v[68:71]
	v_mfma_f32_16x16x32_f16 v[120:123], v[136:139], v[168:171], v[120:123]
	v_mfma_f32_16x16x32_f16 v[116:119], v[144:147], v[168:171], v[116:119]
	v_mfma_f32_16x16x32_f16 v[104:107], v[136:139], v[176:179], v[104:107]
	v_mfma_f32_16x16x32_f16 v[100:103], v[144:147], v[176:179], v[100:103]
	v_mfma_f32_16x16x32_f16 v[88:91], v[136:139], v[184:187], v[88:91]
	v_mfma_f32_16x16x32_f16 v[84:87], v[144:147], v[184:187], v[84:87]
	v_mfma_f32_16x16x32_f16 v[72:75], v[136:139], v[192:195], v[72:75]
	v_mfma_f32_16x16x32_f16 v[68:71], v[144:147], v[192:195], v[68:71]
	s_setprio 0
	s_barrier
	s_add_i32 s24, s40, s27
	s_mov_b32 m0, s24
	ds_read_b128 v[188:191], v243 offset:16384
	ds_read_b128 v[192:195], v243 offset:17408
	ds_read_b128 v[180:183], v243 offset:18432
	ds_read_b128 v[184:187], v243 offset:19456
	ds_read_b128 v[172:175], v243 offset:20480
	ds_read_b128 v[176:179], v243 offset:21504
	ds_read_b128 v[164:167], v243 offset:22528
	ds_read_b128 v[168:171], v243 offset:23552
	global_load_lds_dwordx4 v216, s[20:21]
	s_add_i32 m0, s24, 0x2000
	s_add_u32 s24, s20, 0x40000
	s_addc_u32 s25, s21, 0
	s_add_i32 s40, s41, s27
	global_load_lds_dwordx4 v220, s[20:21]
	s_mov_b32 m0, s40
	s_nop 0
	global_load_lds_dwordx4 v216, s[24:25]
	s_add_i32 m0, s40, 0x2000
	s_nop 0
	global_load_lds_dwordx4 v220, s[24:25]
	s_mov_b32 m0, s9
	v_cndmask_b32_e64 v0, 0, 1, s[18:19]
	global_load_lds_dwordx4 v214, s[22:23]
	s_mov_b32 m0, s28
	v_cmp_ne_u32_e64 s[40:41], 1, v0
	global_load_lds_dwordx4 v218, s[22:23]
	s_waitcnt vmcnt(8) lgkmcnt(0)
	s_andn2_b64 vcc, exec, s[18:19]
	s_barrier
	s_cbranch_vccnz .LBB0_800
	s_setprio 1
	v_mfma_f32_16x16x32_f16 v[64:67], v[148:151], v[188:191], v[64:67]
	v_mfma_f32_16x16x32_f16 v[60:63], v[156:159], v[188:191], v[60:63]
	v_mfma_f32_16x16x32_f16 v[48:51], v[148:151], v[180:183], v[48:51]
	v_mfma_f32_16x16x32_f16 v[44:47], v[156:159], v[180:183], v[44:47]
	v_mfma_f32_16x16x32_f16 v[32:35], v[148:151], v[172:175], v[32:35]
	v_mfma_f32_16x16x32_f16 v[28:31], v[156:159], v[172:175], v[28:31]
	v_mfma_f32_16x16x32_f16 v[16:19], v[148:151], v[164:167], v[16:19]
	v_mfma_f32_16x16x32_f16 v[12:15], v[156:159], v[164:167], v[12:15]
	v_mfma_f32_16x16x32_f16 v[64:67], v[152:155], v[192:195], v[64:67]
	v_mfma_f32_16x16x32_f16 v[60:63], v[160:163], v[192:195], v[60:63]
	v_mfma_f32_16x16x32_f16 v[48:51], v[152:155], v[184:187], v[48:51]
	v_mfma_f32_16x16x32_f16 v[44:47], v[160:163], v[184:187], v[44:47]
	v_mfma_f32_16x16x32_f16 v[32:35], v[152:155], v[176:179], v[32:35]
	v_mfma_f32_16x16x32_f16 v[28:31], v[160:163], v[176:179], v[28:31]
	v_mfma_f32_16x16x32_f16 v[16:19], v[152:155], v[168:171], v[16:19]
	v_mfma_f32_16x16x32_f16 v[12:15], v[160:163], v[168:171], v[12:15]
	s_setprio 0
	s_setprio 1
	v_mfma_f32_16x16x32_f16 v[56:59], v[132:135], v[188:191], v[56:59]
	v_mfma_f32_16x16x32_f16 v[52:55], v[140:143], v[188:191], v[52:55]
	v_mfma_f32_16x16x32_f16 v[40:43], v[132:135], v[180:183], v[40:43]
	v_mfma_f32_16x16x32_f16 v[36:39], v[140:143], v[180:183], v[36:39]
	v_mfma_f32_16x16x32_f16 v[24:27], v[132:135], v[172:175], v[24:27]
	v_mfma_f32_16x16x32_f16 v[20:23], v[140:143], v[172:175], v[20:23]
	v_mfma_f32_16x16x32_f16 v[8:11], v[132:135], v[164:167], v[8:11]
	v_mfma_f32_16x16x32_f16 v[4:7], v[140:143], v[164:167], v[4:7]
	v_mfma_f32_16x16x32_f16 v[56:59], v[136:139], v[192:195], v[56:59]
	v_mfma_f32_16x16x32_f16 v[52:55], v[144:147], v[192:195], v[52:55]
	v_mfma_f32_16x16x32_f16 v[40:43], v[136:139], v[184:187], v[40:43]
	v_mfma_f32_16x16x32_f16 v[36:39], v[144:147], v[184:187], v[36:39]
	v_mfma_f32_16x16x32_f16 v[24:27], v[136:139], v[176:179], v[24:27]
	v_mfma_f32_16x16x32_f16 v[20:23], v[144:147], v[176:179], v[20:23]
	v_mfma_f32_16x16x32_f16 v[8:11], v[136:139], v[168:171], v[8:11]
	v_mfma_f32_16x16x32_f16 v[4:7], v[144:147], v[168:171], v[4:7]
	s_setprio 0
; #define PG8_STAGE(bufoff, gbase, voff) do { _Pragma("unroll") for (int _i = 0; _i < 2; ++_i) \
;         __builtin_amdgcn_global_load_lds((const unsigned*)((const char*)(gbase) + (voff)[_i]), (LAS unsigned*)(lds + (bufoff) + ldsw + _i * 8192), 16, 0, 0); } while (0)
; #define PG8_LDA(dst, b, h) do { _Pragma("unroll") for (int m = 0; m < 4; ++m) _Pragma("unroll") for (int k = 0; k < 2; ++k) dst[m][k] = *(const LAS f16x8*)(lds + PG8_SA(b, h) + aoff + m * 2048 + k * 1024); } while (0)
; #define PG8_LDB(dst, b, h) do { _Pragma("unroll") for (int n = 0; n < 2; ++n) _Pragma("unroll") for (int k = 0; k < 2; ++k) dst[n][k] = *(const LAS f16x8*)(lds + PG8_SB(b, h) + boff + n * 2048 + k * 1024); } while (0)
; #define PG8_MMA(ai, bj, At, Bt) do { __builtin_amdgcn_s_setprio(1); _Pragma("unroll") for (int m = 0; m < 4; ++m) _Pragma("unroll") for (int n = 0; n < 2; ++n) _Pragma("unroll") for (int k = 0; k < 2; ++k) \
;         acc[ai][bj][m][n] = mma16_<Epi::BF16>(Bt[n][k], At[m][k], acc[ai][bj][m][n]); __builtin_amdgcn_s_setprio(0); } while (0)
; #define PG8_WAIT_V(n) asm volatile("s_waitcnt vmcnt(" #n ")" ::: "memory")
; #define PG8_WAIT_L(n) asm volatile("s_waitcnt lgkmcnt(" #n ")" ::: "memory")
; #define PG8_BAR __builtin_amdgcn_s_barrier()
; #define PG8_SCHED __builtin_amdgcn_sched_barrier(0)
;     ...
;             PG8_LDB(B0, 1, 0); PG8_LDB(B1, 1, 1); PG8_SCHED; PG8_LDA(At, 1, 0); PG8_STAGE(PG8_SA(0, 1), a2 + hA, voffA);
;             PG8_WAIT_V(8); PG8_WAIT_L(0); PG8_BAR; PG8_MMA(0, 0, At, B0); PG8_MMA(0, 1, At, B1); PG8_BAR; PG8_SCHED;
;             PG8_LDA(At, 1, 1); PG8_STAGE(PG8_SB(1, 0), b3, voffB); PG8_STAGE(PG8_SB(1, 1), b3 + hB, voffB); PG8_STAGE(PG8_SA(1, 0), a3, voffA);
;             PG8_WAIT_V(8); PG8_WAIT_L(0); PG8_BAR; if (!cur.half) { PG8_MMA(1, 0, At, B0); PG8_MMA(1, 1, At, B1); } PG8_BAR; PG8_SCHED;
.LBB0_800:
	s_barrier
	s_add_i32 s24, 0, 0x18000
	v_add_u32_e32 v0, s24, v233
	s_add_i32 s25, 0, 0x1c000
	ds_read_b128 v[148:151], v0
	ds_read_b128 v[152:155], v0 offset:1024
	ds_read_b128 v[156:159], v0 offset:2048
	ds_read_b128 v[160:163], v0 offset:3072
	v_add_u32_e32 v0, s25, v233
	ds_read_b128 v[132:135], v0
	ds_read_b128 v[136:139], v0 offset:1024
	ds_read_b128 v[140:143], v0 offset:2048
	ds_read_b128 v[144:147], v0 offset:3072
	s_add_u32 s22, s22, 0x1a0000
	s_addc_u32 s23, s23, 0
	s_add_u32 s98, s22, 0xffe60080
	s_addc_u32 s99, s23, -1
	s_mov_b32 m0, s29
	s_waitcnt lgkmcnt(0)
	ds_read_b128 v[164:167], v243 offset:32768
	ds_read_b128 v[168:171], v243 offset:33792
	ds_read_b128 v[172:175], v243 offset:34816
	ds_read_b128 v[176:179], v243 offset:35840
	ds_read_b128 v[180:183], v243 offset:36864
	ds_read_b128 v[184:187], v243 offset:37888
	ds_read_b128 v[188:191], v243 offset:38912
	ds_read_b128 v[192:195], v243 offset:39936
	global_load_lds_dwordx4 v214, s[22:23]
	s_mov_b32 m0, s30
	s_nop 0
	global_load_lds_dwordx4 v218, s[22:23]
	s_waitcnt vmcnt(8) lgkmcnt(0)
	s_barrier
	s_setprio 1
	v_mfma_f32_16x16x32_f16 v[128:131], v[148:151], v[164:167], v[128:131]
	v_mfma_f32_16x16x32_f16 v[124:127], v[156:159], v[164:167], v[124:127]
	v_mfma_f32_16x16x32_f16 v[112:115], v[148:151], v[172:175], v[112:115]
	v_mfma_f32_16x16x32_f16 v[108:111], v[156:159], v[172:175], v[108:111]
	v_mfma_f32_16x16x32_f16 v[96:99], v[148:151], v[180:183], v[96:99]
	v_mfma_f32_16x16x32_f16 v[92:95], v[156:159], v[180:183], v[92:95]
	v_mfma_f32_16x16x32_f16 v[80:83], v[148:151], v[188:191], v[80:83]
	v_mfma_f32_16x16x32_f16 v[76:79], v[156:159], v[188:191], v[76:79]
	v_mfma_f32_16x16x32_f16 v[128:131], v[152:155], v[168:171], v[128:131]
	v_mfma_f32_16x16x32_f16 v[124:127], v[160:163], v[168:171], v[124:127]
	v_mfma_f32_16x16x32_f16 v[112:115], v[152:155], v[176:179], v[112:115]
	v_mfma_f32_16x16x32_f16 v[108:111], v[160:163], v[176:179], v[108:111]
	v_mfma_f32_16x16x32_f16 v[96:99], v[152:155], v[184:187], v[96:99]
	v_mfma_f32_16x16x32_f16 v[92:95], v[160:163], v[184:187], v[92:95]
	v_mfma_f32_16x16x32_f16 v[80:83], v[152:155], v[192:195], v[80:83]
	v_mfma_f32_16x16x32_f16 v[76:79], v[160:163], v[192:195], v[76:79]
	s_setprio 0
	s_setprio 1
	v_mfma_f32_16x16x32_f16 v[120:123], v[132:135], v[164:167], v[120:123]
	v_mfma_f32_16x16x32_f16 v[116:119], v[140:143], v[164:167], v[116:119]
	v_mfma_f32_16x16x32_f16 v[104:107], v[132:135], v[172:175], v[104:107]
	v_mfma_f32_16x16x32_f16 v[100:103], v[140:143], v[172:175], v[100:103]
	v_mfma_f32_16x16x32_f16 v[88:91], v[132:135], v[180:183], v[88:91]
	v_mfma_f32_16x16x32_f16 v[84:87], v[140:143], v[180:183], v[84:87]
	v_mfma_f32_16x16x32_f16 v[72:75], v[132:135], v[188:191], v[72:75]
	v_mfma_f32_16x16x32_f16 v[68:71], v[140:143], v[188:191], v[68:71]
	v_mfma_f32_16x16x32_f16 v[120:123], v[136:139], v[168:171], v[120:123]
	v_mfma_f32_16x16x32_f16 v[116:119], v[144:147], v[168:171], v[116:119]
	v_mfma_f32_16x16x32_f16 v[104:107], v[136:139], v[176:179], v[104:107]
	v_mfma_f32_16x16x32_f16 v[100:103], v[144:147], v[176:179], v[100:103]
	v_mfma_f32_16x16x32_f16 v[88:91], v[136:139], v[184:187], v[88:91]
	v_mfma_f32_16x16x32_f16 v[84:87], v[144:147], v[184:187], v[84:87]
	v_mfma_f32_16x16x32_f16 v[72:75], v[136:139], v[192:195], v[72:75]
	v_mfma_f32_16x16x32_f16 v[68:71], v[144:147], v[192:195], v[68:71]
	s_setprio 0
	s_barrier
	s_add_i32 s22, s24, s27
	s_add_u32 s20, s20, 0x80
	s_addc_u32 s21, s21, 0
	s_mov_b32 m0, s22
	ds_read_b128 v[188:191], v243 offset:49152
	ds_read_b128 v[192:195], v243 offset:50176
	ds_read_b128 v[180:183], v243 offset:51200
	ds_read_b128 v[184:187], v243 offset:52224
	ds_read_b128 v[172:175], v243 offset:53248
	ds_read_b128 v[176:179], v243 offset:54272
	ds_read_b128 v[164:167], v243 offset:55296
	ds_read_b128 v[168:171], v243 offset:56320
	global_load_lds_dwordx4 v216, s[20:21]
	s_add_i32 m0, s22, 0x2000
	s_add_i32 s22, s25, s27
	global_load_lds_dwordx4 v220, s[20:21]
	s_add_u32 s20, s20, 0x40000
	s_addc_u32 s21, s21, 0
	s_mov_b32 m0, s22
	s_and_b64 vcc, exec, s[40:41]
	global_load_lds_dwordx4 v216, s[20:21]
	s_add_i32 m0, s22, 0x2000
	s_nop 0
	global_load_lds_dwordx4 v220, s[20:21]
	s_mov_b32 m0, s31
	s_nop 0
	global_load_lds_dwordx4 v214, s[98:99]
	s_mov_b32 m0, s34
	s_nop 0
	global_load_lds_dwordx4 v218, s[98:99]
	s_waitcnt vmcnt(8) lgkmcnt(0)
	s_barrier
	s_cbranch_vccnz .LBB0_797
	s_setprio 1
	v_mfma_f32_16x16x32_f16 v[64:67], v[148:151], v[188:191], v[64:67]
	v_mfma_f32_16x16x32_f16 v[60:63], v[156:159], v[188:191], v[60:63]
	v_mfma_f32_16x16x32_f16 v[48:51], v[148:151], v[180:183], v[48:51]
	v_mfma_f32_16x16x32_f16 v[44:47], v[156:159], v[180:183], v[44:47]
	v_mfma_f32_16x16x32_f16 v[32:35], v[148:151], v[172:175], v[32:35]
	v_mfma_f32_16x16x32_f16 v[28:31], v[156:159], v[172:175], v[28:31]
	v_mfma_f32_16x16x32_f16 v[16:19], v[148:151], v[164:167], v[16:19]
	v_mfma_f32_16x16x32_f16 v[12:15], v[156:159], v[164:167], v[12:15]
	v_mfma_f32_16x16x32_f16 v[64:67], v[152:155], v[192:195], v[64:67]
	v_mfma_f32_16x16x32_f16 v[60:63], v[160:163], v[192:195], v[60:63]
	v_mfma_f32_16x16x32_f16 v[48:51], v[152:155], v[184:187], v[48:51]
	v_mfma_f32_16x16x32_f16 v[44:47], v[160:163], v[184:187], v[44:47]
	v_mfma_f32_16x16x32_f16 v[32:35], v[152:155], v[176:179], v[32:35]
	v_mfma_f32_16x16x32_f16 v[28:31], v[160:163], v[176:179], v[28:31]
	v_mfma_f32_16x16x32_f16 v[16:19], v[152:155], v[168:171], v[16:19]
	v_mfma_f32_16x16x32_f16 v[12:15], v[160:163], v[168:171], v[12:15]
	s_setprio 0
	s_setprio 1
	v_mfma_f32_16x16x32_f16 v[56:59], v[132:135], v[188:191], v[56:59]
	v_mfma_f32_16x16x32_f16 v[52:55], v[140:143], v[188:191], v[52:55]
	v_mfma_f32_16x16x32_f16 v[40:43], v[132:135], v[180:183], v[40:43]
	v_mfma_f32_16x16x32_f16 v[36:39], v[140:143], v[180:183], v[36:39]
	v_mfma_f32_16x16x32_f16 v[24:27], v[132:135], v[172:175], v[24:27]
	v_mfma_f32_16x16x32_f16 v[20:23], v[140:143], v[172:175], v[20:23]
	v_mfma_f32_16x16x32_f16 v[8:11], v[132:135], v[164:167], v[8:11]
	v_mfma_f32_16x16x32_f16 v[2:5], v[140:143], v[164:167], v[4:7]
	v_mfma_f32_16x16x32_f16 v[56:59], v[136:139], v[192:195], v[56:59]
	v_mfma_f32_16x16x32_f16 v[52:55], v[144:147], v[192:195], v[52:55]
	v_mfma_f32_16x16x32_f16 v[40:43], v[136:139], v[184:187], v[40:43]
	v_mfma_f32_16x16x32_f16 v[36:39], v[144:147], v[184:187], v[36:39]
	v_mfma_f32_16x16x32_f16 v[24:27], v[136:139], v[176:179], v[24:27]
	v_mfma_f32_16x16x32_f16 v[20:23], v[144:147], v[176:179], v[20:23]
	v_mfma_f32_16x16x32_f16 v[8:11], v[136:139], v[168:171], v[8:11]
	v_mfma_f32_16x16x32_f16 v[4:7], v[144:147], v[168:171], v[2:5]
	s_setprio 0
	s_branch .LBB0_797

; #define PG8_STAGE(bufoff, gbase, voff) do { _Pragma("unroll") for (int _i = 0; _i < 2; ++_i) \
;         __builtin_amdgcn_global_load_lds((const unsigned*)((const char*)(gbase) + (voff)[_i]), (LAS unsigned*)(lds + (bufoff) + ldsw + _i * 8192), 16, 0, 0); } while (0)
; #define PG8_LDA(dst, b, h) do { _Pragma("unroll") for (int m = 0; m < 4; ++m) _Pragma("unroll") for (int k = 0; k < 2; ++k) dst[m][k] = *(const LAS f16x8*)(lds + PG8_SA(b, h) + aoff + m * 2048 + k * 1024); } while (0)
; #define PG8_LDB(dst, b, h) do { _Pragma("unroll") for (int n = 0; n < 2; ++n) _Pragma("unroll") for (int k = 0; k < 2; ++k) dst[n][k] = *(const LAS f16x8*)(lds + PG8_SB(b, h) + boff + n * 2048 + k * 1024); } while (0)
; #define PG8_MMA(ai, bj, At, Bt) do { __builtin_amdgcn_s_setprio(1); _Pragma("unroll") for (int m = 0; m < 4; ++m) _Pragma("unroll") for (int n = 0; n < 2; ++n) _Pragma("unroll") for (int k = 0; k < 2; ++k) \
;         acc[ai][bj][m][n] = mma16_<Epi::BF16>(Bt[n][k], At[m][k], acc[ai][bj][m][n]); __builtin_amdgcn_s_setprio(0); } while (0)
; #define PG8_WAIT_V(n) asm volatile("s_waitcnt vmcnt(" #n ")" ::: "memory")
; #define PG8_WAIT_L(n) asm volatile("s_waitcnt lgkmcnt(" #n ")" ::: "memory")
; #define PG8_BAR __builtin_amdgcn_s_barrier()
; #define PG8_SCHED __builtin_amdgcn_sched_barrier(0)
;     ...
;             const bool last = (t == nt - 2);
;             const char* a1 = cA + (size_t)(t + 1) * kstep;
;             const char* a2 = last ? nA : cA + (size_t)(t + 2) * kstep; const char* b2 = last ? nB : cB + (size_t)(t + 2) * kstep;
;             const char* a3 = a2 + kstep; const char* b3 = b2 + kstep;
;             if constexpr (SP2) {
;             PG8_LDB(B0, 0, 0); PG8_LDB(B1, 0, 1); PG8_SCHED; PG8_LDA(At, 0, 0); PG8_STAGE(PG8_SA(1, 1), a1 + hA, voffA);
;             PG8_WAIT_V(8); PG8_WAIT_L(0); PG8_BAR; PG8_MMA(0, 0, At, B0); PG8_MMA(0, 1, At, B1); PG8_BAR; PG8_SCHED;
;             PG8_LDA(At, 0, 1); PG8_STAGE(PG8_SB(0, 0), b2, voffB); PG8_STAGE(PG8_SB(0, 1), b2 + hB, voffB); PG8_STAGE(PG8_SA(0, 0), a2, voffA);
;             PG8_WAIT_V(8); PG8_WAIT_L(0); PG8_BAR; if (!cur.half) { PG8_MMA(1, 0, At, B0); PG8_MMA(1, 1, At, B1); } PG8_BAR; PG8_SCHED;
.LBB0_886:
	s_add_u32 s25, s36, 0xfffc0080
	s_addc_u32 s27, s37, -1
	s_add_i32 s40, 0, 0x10000
	s_cmp_eq_u32 s14, 12
	s_cselect_b32 s45, s29, s27
	s_cselect_b32 s44, s28, s25
	s_waitcnt lgkmcnt(0)
	v_add_u32_e32 v106, s40, v244
	s_cselect_b32 s43, s2, s11
	s_cselect_b32 s42, s3, s9
	s_add_i32 s25, 0, 0x14000
	ds_read_b128 v[154:157], v106
	ds_read_b128 v[158:161], v106 offset:1024
	ds_read_b128 v[162:165], v106 offset:2048
	ds_read_b128 v[166:169], v106 offset:3072
	v_add_u32_e32 v106, s25, v244
	ds_read_b128 v[138:141], v106
	ds_read_b128 v[142:145], v106 offset:1024
	ds_read_b128 v[146:149], v106 offset:2048
	ds_read_b128 v[150:153], v106 offset:3072
	s_add_i32 m0, s51, 0xc000
	ds_read_b128 v[170:173], v245
	ds_read_b128 v[174:177], v245 offset:1024
	ds_read_b128 v[178:181], v245 offset:2048
	ds_read_b128 v[182:185], v245 offset:3072
	ds_read_b128 v[186:189], v245 offset:4096
	ds_read_b128 v[190:193], v245 offset:5120
	ds_read_b128 v[226:229], v245 offset:6144
	ds_read_b128 v[230:233], v245 offset:7168
	global_load_lds_dwordx4 v222, s[36:37]
	s_add_i32 m0, s51, 0xe000
	s_nop 0
	global_load_lds_dwordx4 v224, s[36:37]
	s_waitcnt vmcnt(8) lgkmcnt(0)
	s_barrier
	s_setprio 1
	v_mfma_f32_16x16x32_bf16 v[106:109], v[154:157], v[170:173], v[134:137]
	v_mfma_f32_16x16x32_bf16 v[110:113], v[162:165], v[170:173], v[130:133]
	v_mfma_f32_16x16x32_bf16 v[126:129], v[154:157], v[178:181], v[126:129]
	v_mfma_f32_16x16x32_bf16 v[122:125], v[162:165], v[178:181], v[122:125]
	v_mfma_f32_16x16x32_bf16 v[118:121], v[154:157], v[186:189], v[118:121]
	v_mfma_f32_16x16x32_bf16 v[114:117], v[162:165], v[186:189], v[114:117]
	v_mfma_f32_16x16x32_bf16 v[102:105], v[154:157], v[226:229], v[102:105]
	v_mfma_f32_16x16x32_bf16 v[98:101], v[162:165], v[226:229], v[98:101]
	v_mfma_f32_16x16x32_bf16 v[106:109], v[158:161], v[174:177], v[106:109]
	v_mfma_f32_16x16x32_bf16 v[110:113], v[166:169], v[174:177], v[110:113]
	v_mfma_f32_16x16x32_bf16 v[126:129], v[158:161], v[182:185], v[126:129]
	v_mfma_f32_16x16x32_bf16 v[122:125], v[166:169], v[182:185], v[122:125]
	v_mfma_f32_16x16x32_bf16 v[118:121], v[158:161], v[190:193], v[118:121]
	v_mfma_f32_16x16x32_bf16 v[114:117], v[166:169], v[190:193], v[114:117]
	v_mfma_f32_16x16x32_bf16 v[102:105], v[158:161], v[230:233], v[102:105]
	v_mfma_f32_16x16x32_bf16 v[98:101], v[166:169], v[230:233], v[98:101]
	s_setprio 0
	s_setprio 1
	v_mfma_f32_16x16x32_bf16 v[70:73], v[138:141], v[170:173], v[70:73]
	v_mfma_f32_16x16x32_bf16 v[66:69], v[146:149], v[170:173], v[66:69]
	v_mfma_f32_16x16x32_bf16 v[58:61], v[138:141], v[178:181], v[58:61]
	v_mfma_f32_16x16x32_bf16 v[50:53], v[146:149], v[178:181], v[50:53]
	v_mfma_f32_16x16x32_bf16 v[46:49], v[138:141], v[186:189], v[46:49]
	v_mfma_f32_16x16x32_bf16 v[42:45], v[146:149], v[186:189], v[42:45]
	v_mfma_f32_16x16x32_bf16 v[38:41], v[138:141], v[226:229], v[38:41]
	v_mfma_f32_16x16x32_bf16 v[34:37], v[146:149], v[226:229], v[34:37]
	v_mfma_f32_16x16x32_bf16 v[70:73], v[142:145], v[174:177], v[70:73]
	v_mfma_f32_16x16x32_bf16 v[66:69], v[150:153], v[174:177], v[66:69]
	v_mfma_f32_16x16x32_bf16 v[58:61], v[142:145], v[182:185], v[58:61]
	v_mfma_f32_16x16x32_bf16 v[50:53], v[150:153], v[182:185], v[50:53]
	v_mfma_f32_16x16x32_bf16 v[46:49], v[142:145], v[190:193], v[46:49]
	v_mfma_f32_16x16x32_bf16 v[42:45], v[150:153], v[190:193], v[42:45]
	v_mfma_f32_16x16x32_bf16 v[38:41], v[142:145], v[230:233], v[38:41]
	v_mfma_f32_16x16x32_bf16 v[34:37], v[150:153], v[230:233], v[34:37]
	s_setprio 0
	s_barrier
	s_add_i32 s27, s40, s50
	s_mov_b32 m0, s27
	ds_read_b128 v[186:189], v245 offset:16384
	ds_read_b128 v[190:193], v245 offset:17408
	ds_read_b128 v[178:181], v245 offset:18432
	ds_read_b128 v[182:185], v245 offset:19456
	ds_read_b128 v[170:173], v245 offset:20480
	ds_read_b128 v[174:177], v245 offset:21504
	ds_read_b128 v[130:133], v245 offset:22528
	ds_read_b128 v[134:137], v245 offset:23552
	global_load_lds_dwordx4 v214, s[42:43]
	s_add_i32 m0, s27, 0x2000
	s_add_u32 s40, s42, 0x40000
	s_addc_u32 s41, s43, 0
	s_add_i32 s25, s25, s50
	global_load_lds_dwordx4 v218, s[42:43]
	s_mov_b32 m0, s25
	s_nop 0
	global_load_lds_dwordx4 v214, s[40:41]
	s_add_i32 m0, s25, 0x2000
	s_nop 0
	global_load_lds_dwordx4 v218, s[40:41]
	s_mov_b32 m0, s51
	v_cndmask_b32_e64 v200, 0, 1, s[34:35]
	global_load_lds_dwordx4 v194, s[44:45]
	s_mov_b32 m0, s52
	v_cmp_ne_u32_e64 s[40:41], 1, v200
	global_load_lds_dwordx4 v216, s[44:45]
	s_waitcnt vmcnt(8) lgkmcnt(0)
	s_andn2_b64 vcc, exec, s[34:35]
	s_barrier
	s_cbranch_vccnz .LBB0_888
	s_setprio 1
	v_mfma_f32_16x16x32_bf16 v[94:97], v[154:157], v[186:189], v[94:97]
	v_mfma_f32_16x16x32_bf16 v[90:93], v[162:165], v[186:189], v[90:93]
	v_mfma_f32_16x16x32_bf16 v[86:89], v[154:157], v[178:181], v[86:89]
	v_mfma_f32_16x16x32_bf16 v[82:85], v[162:165], v[178:181], v[82:85]
	v_mfma_f32_16x16x32_bf16 v[78:81], v[154:157], v[170:173], v[78:81]
	v_mfma_f32_16x16x32_bf16 v[74:77], v[162:165], v[170:173], v[74:77]
	v_mfma_f32_16x16x32_bf16 v[62:65], v[154:157], v[130:133], v[62:65]
	v_mfma_f32_16x16x32_bf16 v[54:57], v[162:165], v[130:133], v[54:57]
	v_mfma_f32_16x16x32_bf16 v[94:97], v[158:161], v[190:193], v[94:97]
	v_mfma_f32_16x16x32_bf16 v[90:93], v[166:169], v[190:193], v[90:93]
	v_mfma_f32_16x16x32_bf16 v[86:89], v[158:161], v[182:185], v[86:89]
	v_mfma_f32_16x16x32_bf16 v[82:85], v[166:169], v[182:185], v[82:85]
	v_mfma_f32_16x16x32_bf16 v[78:81], v[158:161], v[174:177], v[78:81]
	v_mfma_f32_16x16x32_bf16 v[74:77], v[166:169], v[174:177], v[74:77]
	v_mfma_f32_16x16x32_bf16 v[62:65], v[158:161], v[134:137], v[62:65]
	v_mfma_f32_16x16x32_bf16 v[54:57], v[166:169], v[134:137], v[54:57]
	s_setprio 0
	s_setprio 1
	v_mfma_f32_16x16x32_bf16 v[30:33], v[138:141], v[186:189], v[30:33]
	v_mfma_f32_16x16x32_bf16 v[26:29], v[146:149], v[186:189], v[26:29]
	v_mfma_f32_16x16x32_bf16 v[22:25], v[138:141], v[178:181], v[22:25]
	v_mfma_f32_16x16x32_bf16 v[18:21], v[146:149], v[178:181], v[18:21]
	v_mfma_f32_16x16x32_bf16 v[14:17], v[138:141], v[170:173], v[14:17]
	v_mfma_f32_16x16x32_bf16 v[10:13], v[146:149], v[170:173], v[10:13]
	v_mfma_f32_16x16x32_bf16 v[6:9], v[138:141], v[130:133], v[6:9]
	v_mfma_f32_16x16x32_bf16 v[2:5], v[146:149], v[130:133], v[2:5]
	v_mfma_f32_16x16x32_bf16 v[30:33], v[142:145], v[190:193], v[30:33]
	v_mfma_f32_16x16x32_bf16 v[26:29], v[150:153], v[190:193], v[26:29]
	v_mfma_f32_16x16x32_bf16 v[22:25], v[142:145], v[182:185], v[22:25]
	v_mfma_f32_16x16x32_bf16 v[18:21], v[150:153], v[182:185], v[18:21]
	v_mfma_f32_16x16x32_bf16 v[14:17], v[142:145], v[174:177], v[14:17]
	v_mfma_f32_16x16x32_bf16 v[10:13], v[150:153], v[174:177], v[10:13]
	v_mfma_f32_16x16x32_bf16 v[6:9], v[142:145], v[134:137], v[6:9]
	v_mfma_f32_16x16x32_bf16 v[2:5], v[150:153], v[134:137], v[2:5]
	s_setprio 0
; #define PG8_STAGE(bufoff, gbase, voff) do { _Pragma("unroll") for (int _i = 0; _i < 2; ++_i) \
;         __builtin_amdgcn_global_load_lds((const unsigned*)((const char*)(gbase) + (voff)[_i]), (LAS unsigned*)(lds + (bufoff) + ldsw + _i * 8192), 16, 0, 0); } while (0)
; #define PG8_LDA(dst, b, h) do { _Pragma("unroll") for (int m = 0; m < 4; ++m) _Pragma("unroll") for (int k = 0; k < 2; ++k) dst[m][k] = *(const LAS f16x8*)(lds + PG8_SA(b, h) + aoff + m * 2048 + k * 1024); } while (0)
; #define PG8_LDB(dst, b, h) do { _Pragma("unroll") for (int n = 0; n < 2; ++n) _Pragma("unroll") for (int k = 0; k < 2; ++k) dst[n][k] = *(const LAS f16x8*)(lds + PG8_SB(b, h) + boff + n * 2048 + k * 1024); } while (0)
; #define PG8_MMA(ai, bj, At, Bt) do { __builtin_amdgcn_s_setprio(1); _Pragma("unroll") for (int m = 0; m < 4; ++m) _Pragma("unroll") for (int n = 0; n < 2; ++n) _Pragma("unroll") for (int k = 0; k < 2; ++k) \
;         acc[ai][bj][m][n] = mma16_<Epi::BF16>(Bt[n][k], At[m][k], acc[ai][bj][m][n]); __builtin_amdgcn_s_setprio(0); } while (0)
; #define PG8_WAIT_V(n) asm volatile("s_waitcnt vmcnt(" #n ")" ::: "memory")
; #define PG8_WAIT_L(n) asm volatile("s_waitcnt lgkmcnt(" #n ")" ::: "memory")
; #define PG8_BAR __builtin_amdgcn_s_barrier()
; #define PG8_SCHED __builtin_amdgcn_sched_barrier(0)
;     ...
;             PG8_LDB(B0, 1, 0); PG8_LDB(B1, 1, 1); PG8_SCHED; PG8_LDA(At, 1, 0); PG8_STAGE(PG8_SA(0, 1), a2 + hA, voffA);
;             PG8_WAIT_V(8); PG8_WAIT_L(0); PG8_BAR; PG8_MMA(0, 0, At, B0); PG8_MMA(0, 1, At, B1); PG8_BAR; PG8_SCHED;
;             PG8_LDA(At, 1, 1); PG8_STAGE(PG8_SB(1, 0), b3, voffB); PG8_STAGE(PG8_SB(1, 1), b3 + hB, voffB); PG8_STAGE(PG8_SA(1, 0), a3, voffA);
;             PG8_WAIT_V(8); PG8_WAIT_L(0); PG8_BAR; if (!cur.half) { PG8_MMA(1, 0, At, B0); PG8_MMA(1, 1, At, B1); } PG8_BAR; PG8_SCHED;
.LBB0_888:
	s_barrier
	s_add_i32 s25, 0, 0x18000
	s_waitcnt lgkmcnt(0)
	v_add_u32_e32 v130, s25, v244
	s_add_i32 s27, 0, 0x1c000
	ds_read_b128 v[154:157], v130
	ds_read_b128 v[158:161], v130 offset:1024
	ds_read_b128 v[162:165], v130 offset:2048
	ds_read_b128 v[166:169], v130 offset:3072
	v_add_u32_e32 v130, s27, v244
	ds_read_b128 v[138:141], v130
	ds_read_b128 v[142:145], v130 offset:1024
	ds_read_b128 v[146:149], v130 offset:2048
	ds_read_b128 v[150:153], v130 offset:3072
	s_add_u32 s44, s44, 0x40000
	s_addc_u32 s45, s45, 0
	s_add_u32 s98, s44, 0xfffc0080
	s_addc_u32 s99, s45, -1
	s_mov_b32 m0, s53
	ds_read_b128 v[170:173], v245 offset:32768
	ds_read_b128 v[174:177], v245 offset:33792
	ds_read_b128 v[178:181], v245 offset:34816
	ds_read_b128 v[182:185], v245 offset:35840
	ds_read_b128 v[186:189], v245 offset:36864
	ds_read_b128 v[190:193], v245 offset:37888
	ds_read_b128 v[246:249], v245 offset:38912
	ds_read_b128 v[200:203], v245 offset:39936
	global_load_lds_dwordx4 v194, s[44:45]
	s_mov_b32 m0, s54
	s_nop 0
	global_load_lds_dwordx4 v216, s[44:45]
	s_waitcnt vmcnt(8) lgkmcnt(0)
	s_barrier
	s_setprio 1
	v_mfma_f32_16x16x32_bf16 v[106:109], v[154:157], v[170:173], v[106:109]
	v_mfma_f32_16x16x32_bf16 v[134:137], v[158:161], v[174:177], v[106:109]
	v_mfma_f32_16x16x32_bf16 v[106:109], v[162:165], v[170:173], v[110:113]
	v_mfma_f32_16x16x32_bf16 v[130:133], v[166:169], v[174:177], v[106:109]
	v_mfma_f32_16x16x32_bf16 v[106:109], v[154:157], v[178:181], v[126:129]
	v_mfma_f32_16x16x32_bf16 v[126:129], v[158:161], v[182:185], v[106:109]
	v_mfma_f32_16x16x32_bf16 v[106:109], v[162:165], v[178:181], v[122:125]
	v_mfma_f32_16x16x32_bf16 v[122:125], v[166:169], v[182:185], v[106:109]
	v_mfma_f32_16x16x32_bf16 v[106:109], v[154:157], v[186:189], v[118:121]
	v_mfma_f32_16x16x32_bf16 v[118:121], v[158:161], v[190:193], v[106:109]
	v_mfma_f32_16x16x32_bf16 v[106:109], v[162:165], v[186:189], v[114:117]
	v_mfma_f32_16x16x32_bf16 v[102:105], v[154:157], v[246:249], v[102:105]
	v_mfma_f32_16x16x32_bf16 v[98:101], v[162:165], v[246:249], v[98:101]
	v_mfma_f32_16x16x32_bf16 v[114:117], v[166:169], v[190:193], v[106:109]
	v_mfma_f32_16x16x32_bf16 v[102:105], v[158:161], v[200:203], v[102:105]
	v_mfma_f32_16x16x32_bf16 v[98:101], v[166:169], v[200:203], v[98:101]
	s_setprio 0
	s_setprio 1
	v_mfma_f32_16x16x32_bf16 v[70:73], v[138:141], v[170:173], v[70:73]
	v_mfma_f32_16x16x32_bf16 v[66:69], v[146:149], v[170:173], v[66:69]
	v_mfma_f32_16x16x32_bf16 v[58:61], v[138:141], v[178:181], v[58:61]
	v_mfma_f32_16x16x32_bf16 v[50:53], v[146:149], v[178:181], v[50:53]
	v_mfma_f32_16x16x32_bf16 v[46:49], v[138:141], v[186:189], v[46:49]
	v_mfma_f32_16x16x32_bf16 v[42:45], v[146:149], v[186:189], v[42:45]
	v_mfma_f32_16x16x32_bf16 v[38:41], v[138:141], v[246:249], v[38:41]
	v_mfma_f32_16x16x32_bf16 v[34:37], v[146:149], v[246:249], v[34:37]
	v_mfma_f32_16x16x32_bf16 v[70:73], v[142:145], v[174:177], v[70:73]
	v_mfma_f32_16x16x32_bf16 v[66:69], v[150:153], v[174:177], v[66:69]
	v_mfma_f32_16x16x32_bf16 v[58:61], v[142:145], v[182:185], v[58:61]
	v_mfma_f32_16x16x32_bf16 v[50:53], v[150:153], v[182:185], v[50:53]
	v_mfma_f32_16x16x32_bf16 v[46:49], v[142:145], v[190:193], v[46:49]
	v_mfma_f32_16x16x32_bf16 v[42:45], v[150:153], v[190:193], v[42:45]
	v_mfma_f32_16x16x32_bf16 v[38:41], v[142:145], v[200:203], v[38:41]
	v_mfma_f32_16x16x32_bf16 v[34:37], v[150:153], v[200:203], v[34:37]
	s_setprio 0
	s_barrier
	s_add_i32 s25, s25, s50
	s_add_u32 s42, s42, 0x80
	s_addc_u32 s43, s43, 0
	s_mov_b32 m0, s25
	ds_read_b128 v[186:189], v245 offset:49152
	ds_read_b128 v[190:193], v245 offset:50176
	ds_read_b128 v[178:181], v245 offset:51200
	ds_read_b128 v[182:185], v245 offset:52224
	ds_read_b128 v[170:173], v245 offset:53248
	ds_read_b128 v[174:177], v245 offset:54272
	ds_read_b128 v[106:109], v245 offset:55296
	ds_read_b128 v[110:113], v245 offset:56320
	global_load_lds_dwordx4 v214, s[42:43]
	s_add_i32 m0, s25, 0x2000
	s_add_i32 s25, s27, s50
	global_load_lds_dwordx4 v218, s[42:43]
	s_add_u32 s42, s42, 0x40000
	s_addc_u32 s43, s43, 0
	s_mov_b32 m0, s25
	s_and_b64 vcc, exec, s[40:41]
	global_load_lds_dwordx4 v214, s[42:43]
	s_add_i32 m0, s25, 0x2000
	s_nop 0
	global_load_lds_dwordx4 v218, s[42:43]
	s_mov_b32 m0, s57
	s_nop 0
	global_load_lds_dwordx4 v194, s[98:99]
	s_mov_b32 m0, s58
	s_nop 0
	global_load_lds_dwordx4 v216, s[98:99]
	s_waitcnt vmcnt(8) lgkmcnt(0)
	s_barrier
	s_cbranch_vccnz .LBB0_885
	s_setprio 1
	v_mfma_f32_16x16x32_bf16 v[94:97], v[154:157], v[186:189], v[94:97]
	v_mfma_f32_16x16x32_bf16 v[90:93], v[162:165], v[186:189], v[90:93]
	v_mfma_f32_16x16x32_bf16 v[86:89], v[154:157], v[178:181], v[86:89]
	v_mfma_f32_16x16x32_bf16 v[82:85], v[162:165], v[178:181], v[82:85]
	v_mfma_f32_16x16x32_bf16 v[78:81], v[154:157], v[170:173], v[78:81]
	v_mfma_f32_16x16x32_bf16 v[74:77], v[162:165], v[170:173], v[74:77]
	v_mfma_f32_16x16x32_bf16 v[62:65], v[154:157], v[106:109], v[62:65]
	v_mfma_f32_16x16x32_bf16 v[54:57], v[162:165], v[106:109], v[54:57]
	v_mfma_f32_16x16x32_bf16 v[94:97], v[158:161], v[190:193], v[94:97]
	v_mfma_f32_16x16x32_bf16 v[90:93], v[166:169], v[190:193], v[90:93]
	v_mfma_f32_16x16x32_bf16 v[86:89], v[158:161], v[182:185], v[86:89]
	v_mfma_f32_16x16x32_bf16 v[82:85], v[166:169], v[182:185], v[82:85]
	v_mfma_f32_16x16x32_bf16 v[78:81], v[158:161], v[174:177], v[78:81]
	v_mfma_f32_16x16x32_bf16 v[74:77], v[166:169], v[174:177], v[74:77]
	v_mfma_f32_16x16x32_bf16 v[62:65], v[158:161], v[110:113], v[62:65]
	v_mfma_f32_16x16x32_bf16 v[54:57], v[166:169], v[110:113], v[54:57]
	s_setprio 0
	s_setprio 1
	v_mfma_f32_16x16x32_bf16 v[30:33], v[138:141], v[186:189], v[30:33]
	v_mfma_f32_16x16x32_bf16 v[26:29], v[146:149], v[186:189], v[26:29]
	v_mfma_f32_16x16x32_bf16 v[22:25], v[138:141], v[178:181], v[22:25]
	v_mfma_f32_16x16x32_bf16 v[18:21], v[146:149], v[178:181], v[18:21]
	v_mfma_f32_16x16x32_bf16 v[14:17], v[138:141], v[170:173], v[14:17]
	v_mfma_f32_16x16x32_bf16 v[10:13], v[146:149], v[170:173], v[10:13]
	v_mfma_f32_16x16x32_bf16 v[6:9], v[138:141], v[106:109], v[6:9]
	v_mfma_f32_16x16x32_bf16 v[2:5], v[146:149], v[106:109], v[2:5]
	v_mfma_f32_16x16x32_bf16 v[30:33], v[142:145], v[190:193], v[30:33]
	v_mfma_f32_16x16x32_bf16 v[26:29], v[150:153], v[190:193], v[26:29]
	v_mfma_f32_16x16x32_bf16 v[22:25], v[142:145], v[182:185], v[22:25]
	v_mfma_f32_16x16x32_bf16 v[18:21], v[150:153], v[182:185], v[18:21]
	v_mfma_f32_16x16x32_bf16 v[14:17], v[142:145], v[174:177], v[14:17]
	v_mfma_f32_16x16x32_bf16 v[10:13], v[150:153], v[174:177], v[10:13]
	v_mfma_f32_16x16x32_bf16 v[6:9], v[142:145], v[110:113], v[6:9]
	v_mfma_f32_16x16x32_bf16 v[2:5], v[150:153], v[110:113], v[2:5]
	s_setprio 0
	s_branch .LBB0_885

; #define PG8_STAGE(bufoff, gbase, voff) do { _Pragma("unroll") for (int _i = 0; _i < 2; ++_i) \
;         __builtin_amdgcn_global_load_lds((const unsigned*)((const char*)(gbase) + (voff)[_i]), (LAS unsigned*)(lds + (bufoff) + ldsw + _i * 8192), 16, 0, 0); } while (0)
; #define PG8_LDA(dst, b, h) do { _Pragma("unroll") for (int m = 0; m < 4; ++m) _Pragma("unroll") for (int k = 0; k < 2; ++k) dst[m][k] = *(const LAS f16x8*)(lds + PG8_SA(b, h) + aoff + m * 2048 + k * 1024); } while (0)
; #define PG8_LDB(dst, b, h) do { _Pragma("unroll") for (int n = 0; n < 2; ++n) _Pragma("unroll") for (int k = 0; k < 2; ++k) dst[n][k] = *(const LAS f16x8*)(lds + PG8_SB(b, h) + boff + n * 2048 + k * 1024); } while (0)
; #define PG8_MMA(ai, bj, At, Bt) do { __builtin_amdgcn_s_setprio(1); _Pragma("unroll") for (int m = 0; m < 4; ++m) _Pragma("unroll") for (int n = 0; n < 2; ++n) _Pragma("unroll") for (int k = 0; k < 2; ++k) \
;         acc[ai][bj][m][n] = mma16_<Epi::BF16>(Bt[n][k], At[m][k], acc[ai][bj][m][n]); __builtin_amdgcn_s_setprio(0); } while (0)
; #define PG8_WAIT_V(n) asm volatile("s_waitcnt vmcnt(" #n ")" ::: "memory")
; #define PG8_WAIT_L(n) asm volatile("s_waitcnt lgkmcnt(" #n ")" ::: "memory")
; #define PG8_BAR __builtin_amdgcn_s_barrier()
;     ...
;             const bool last = (t == nt - 2);
;             const char* a1 = cA + (size_t)(t + 1) * kstep;
;             const char* a2 = last ? nA : cA + (size_t)(t + 2) * kstep; const char* b2 = last ? nB : cB + (size_t)(t + 2) * kstep;
;             const char* a3 = a2 + kstep; const char* b3 = b2 + kstep;
;             if constexpr (SP2) {
;             PG8_LDB(B0, 0, 0); PG8_LDB(B1, 0, 1); PG8_SCHED; PG8_LDA(At, 0, 0); PG8_STAGE(PG8_SA(1, 1), a1 + hA, voffA);
;             PG8_WAIT_V(8); PG8_WAIT_L(0); PG8_BAR; PG8_MMA(0, 0, At, B0); PG8_MMA(0, 1, At, B1); PG8_BAR; PG8_SCHED;
;             PG8_LDA(At, 0, 1); PG8_STAGE(PG8_SB(0, 0), b2, voffB); PG8_STAGE(PG8_SB(0, 1), b2 + hB, voffB); PG8_STAGE(PG8_SA(0, 0), a2, voffA);
;             PG8_WAIT_V(8); PG8_WAIT_L(0); PG8_BAR; if (!cur.half) { PG8_MMA(1, 0, At, B0); PG8_MMA(1, 1, At, B1); } PG8_BAR; PG8_SCHED;
;             PG8_LDB(B0, 1, 0); PG8_LDB(B1, 1, 1); PG8_SCHED; PG8_LDA(At, 1, 0); PG8_STAGE(PG8_SA(0, 1), a2 + hA, voffA);
;             PG8_WAIT_V(8); PG8_WAIT_L(0); PG8_BAR; PG8_MMA(0, 0, At, B0); PG8_MMA(0, 1, At, B1); PG8_BAR; PG8_SCHED;
.LBB0_1018:
	s_add_u32 s34, s30, 0xfffc0080
	s_addc_u32 s35, s31, -1
	s_add_i32 s54, 0, 0x10000
	s_cmp_eq_u32 s53, 12
	s_cselect_b32 s37, s2, s35
	s_cselect_b32 s36, s3, s34
	s_cselect_b32 s35, s19, s52
	s_cselect_b32 s34, s21, s51
	s_add_i32 s56, 0, 0x14000
	v_add_u32_e32 v156, s54, v141
	v_add_u32_e32 v172, s56, v141
	ds_read_b128 v[144:147], v156
	ds_read_b128 v[148:151], v156 offset:1024
	ds_read_b128 v[152:155], v156 offset:2048
	ds_read_b128 v[156:159], v156 offset:3072
	ds_read_b128 v[160:163], v172
	ds_read_b128 v[164:167], v172 offset:1024
	ds_read_b128 v[168:171], v172 offset:2048
	ds_read_b128 v[172:175], v172 offset:3072
	s_add_i32 m0, s27, 0xc000
	ds_read_b128 v[176:179], v143
	ds_read_b128 v[180:183], v143 offset:1024
	ds_read_b128 v[184:187], v143 offset:2048
	ds_read_b128 v[188:191], v143 offset:3072
	ds_read_b128 v[192:195], v143 offset:4096
	ds_read_b128 v[200:203], v143 offset:5120
	ds_read_b128 v[214:217], v143 offset:6144
	ds_read_b128 v[218:221], v143 offset:7168
	global_load_lds_dwordx4 v136, s[30:31]
	s_add_i32 m0, s27, 0xe000
	s_nop 0
	global_load_lds_dwordx4 v138, s[30:31]
	s_waitcnt vmcnt(8) lgkmcnt(0)
	s_barrier
	s_setprio 1
	v_mfma_f32_16x16x32_bf16 v[126:129], v[144:147], v[176:179], v[126:129]
	v_mfma_f32_16x16x32_bf16 v[118:121], v[152:155], v[176:179], v[118:121]
	v_mfma_f32_16x16x32_bf16 v[110:113], v[144:147], v[184:187], v[110:113]
	v_mfma_f32_16x16x32_bf16 v[102:105], v[152:155], v[184:187], v[102:105]
	v_mfma_f32_16x16x32_bf16 v[94:97], v[144:147], v[192:195], v[94:97]
	v_mfma_f32_16x16x32_bf16 v[86:89], v[152:155], v[192:195], v[86:89]
	v_mfma_f32_16x16x32_bf16 v[78:81], v[144:147], v[214:217], v[78:81]
	v_mfma_f32_16x16x32_bf16 v[70:73], v[152:155], v[214:217], v[70:73]
	v_mfma_f32_16x16x32_bf16 v[126:129], v[148:151], v[180:183], v[126:129]
	v_mfma_f32_16x16x32_bf16 v[118:121], v[156:159], v[180:183], v[118:121]
	v_mfma_f32_16x16x32_bf16 v[110:113], v[148:151], v[188:191], v[110:113]
	v_mfma_f32_16x16x32_bf16 v[102:105], v[156:159], v[188:191], v[102:105]
	v_mfma_f32_16x16x32_bf16 v[94:97], v[148:151], v[200:203], v[94:97]
	v_mfma_f32_16x16x32_bf16 v[86:89], v[156:159], v[200:203], v[86:89]
	v_mfma_f32_16x16x32_bf16 v[78:81], v[148:151], v[218:221], v[78:81]
	v_mfma_f32_16x16x32_bf16 v[70:73], v[156:159], v[218:221], v[70:73]
	s_setprio 0
	s_setprio 1
	v_mfma_f32_16x16x32_bf16 v[122:125], v[160:163], v[176:179], v[122:125]
	v_mfma_f32_16x16x32_bf16 v[114:117], v[168:171], v[176:179], v[114:117]
	v_mfma_f32_16x16x32_bf16 v[106:109], v[160:163], v[184:187], v[106:109]
	v_mfma_f32_16x16x32_bf16 v[98:101], v[168:171], v[184:187], v[98:101]
	v_mfma_f32_16x16x32_bf16 v[90:93], v[160:163], v[192:195], v[90:93]
	v_mfma_f32_16x16x32_bf16 v[82:85], v[168:171], v[192:195], v[82:85]
	v_mfma_f32_16x16x32_bf16 v[74:77], v[160:163], v[214:217], v[74:77]
	v_mfma_f32_16x16x32_bf16 v[66:69], v[168:171], v[214:217], v[66:69]
	v_mfma_f32_16x16x32_bf16 v[122:125], v[164:167], v[180:183], v[122:125]
	v_mfma_f32_16x16x32_bf16 v[114:117], v[172:175], v[180:183], v[114:117]
	v_mfma_f32_16x16x32_bf16 v[106:109], v[164:167], v[188:191], v[106:109]
	v_mfma_f32_16x16x32_bf16 v[98:101], v[172:175], v[188:191], v[98:101]
	v_mfma_f32_16x16x32_bf16 v[90:93], v[164:167], v[200:203], v[90:93]
	v_mfma_f32_16x16x32_bf16 v[82:85], v[172:175], v[200:203], v[82:85]
	v_mfma_f32_16x16x32_bf16 v[74:77], v[164:167], v[218:221], v[74:77]
	v_mfma_f32_16x16x32_bf16 v[66:69], v[172:175], v[218:221], v[66:69]
	s_setprio 0
	s_barrier
	s_add_i32 s54, s54, s40
	s_mov_b32 m0, s54
	ds_read_b128 v[176:179], v143 offset:16384
	ds_read_b128 v[180:183], v143 offset:17408
	ds_read_b128 v[184:187], v143 offset:18432
	ds_read_b128 v[188:191], v143 offset:19456
	ds_read_b128 v[192:195], v143 offset:20480
	ds_read_b128 v[200:203], v143 offset:21504
	ds_read_b128 v[214:217], v143 offset:22528
	ds_read_b128 v[218:221], v143 offset:23552
	global_load_lds_dwordx4 v0, s[34:35]
	s_add_i32 m0, s54, 0x2000
	s_add_u32 s54, s34, 0x40000
	s_addc_u32 s55, s35, 0
	s_add_i32 s56, s56, s40
	global_load_lds_dwordx4 v130, s[34:35]
	s_mov_b32 m0, s56
	s_nop 0
	global_load_lds_dwordx4 v0, s[54:55]
	s_add_i32 m0, s56, 0x2000
	s_nop 0
	global_load_lds_dwordx4 v130, s[54:55]
	s_mov_b32 m0, s27
	s_nop 0
	global_load_lds_dwordx4 v134, s[36:37]
	s_mov_b32 m0, s29
	s_nop 0
	global_load_lds_dwordx4 v132, s[36:37]
	s_waitcnt vmcnt(8) lgkmcnt(0)
	s_barrier
	s_setprio 1
	v_mfma_f32_16x16x32_bf16 v[62:65], v[144:147], v[176:179], v[62:65]
	v_mfma_f32_16x16x32_bf16 v[54:57], v[152:155], v[176:179], v[54:57]
	v_mfma_f32_16x16x32_bf16 v[46:49], v[144:147], v[184:187], v[46:49]
	v_mfma_f32_16x16x32_bf16 v[38:41], v[152:155], v[184:187], v[38:41]
	v_mfma_f32_16x16x32_bf16 v[30:33], v[144:147], v[192:195], v[30:33]
	v_mfma_f32_16x16x32_bf16 v[22:25], v[152:155], v[192:195], v[22:25]
	v_mfma_f32_16x16x32_bf16 v[14:17], v[144:147], v[214:217], v[14:17]
	v_mfma_f32_16x16x32_bf16 v[6:9], v[152:155], v[214:217], v[6:9]
	v_mfma_f32_16x16x32_bf16 v[62:65], v[148:151], v[180:183], v[62:65]
	v_mfma_f32_16x16x32_bf16 v[54:57], v[156:159], v[180:183], v[54:57]
	v_mfma_f32_16x16x32_bf16 v[46:49], v[148:151], v[188:191], v[46:49]
	v_mfma_f32_16x16x32_bf16 v[38:41], v[156:159], v[188:191], v[38:41]
	v_mfma_f32_16x16x32_bf16 v[30:33], v[148:151], v[200:203], v[30:33]
	v_mfma_f32_16x16x32_bf16 v[22:25], v[156:159], v[200:203], v[22:25]
	v_mfma_f32_16x16x32_bf16 v[14:17], v[148:151], v[218:221], v[14:17]
	v_mfma_f32_16x16x32_bf16 v[6:9], v[156:159], v[218:221], v[6:9]
	s_setprio 0
	s_setprio 1
	v_mfma_f32_16x16x32_bf16 v[58:61], v[160:163], v[176:179], v[58:61]
	v_mfma_f32_16x16x32_bf16 v[50:53], v[168:171], v[176:179], v[50:53]
	v_mfma_f32_16x16x32_bf16 v[42:45], v[160:163], v[184:187], v[42:45]
	v_mfma_f32_16x16x32_bf16 v[34:37], v[168:171], v[184:187], v[34:37]
	v_mfma_f32_16x16x32_bf16 v[26:29], v[160:163], v[192:195], v[26:29]
	v_mfma_f32_16x16x32_bf16 v[18:21], v[168:171], v[192:195], v[18:21]
	v_mfma_f32_16x16x32_bf16 v[10:13], v[160:163], v[214:217], v[10:13]
	v_mfma_f32_16x16x32_bf16 v[2:5], v[168:171], v[214:217], v[2:5]
	v_mfma_f32_16x16x32_bf16 v[58:61], v[164:167], v[180:183], v[58:61]
	v_mfma_f32_16x16x32_bf16 v[50:53], v[172:175], v[180:183], v[50:53]
	v_mfma_f32_16x16x32_bf16 v[42:45], v[164:167], v[188:191], v[42:45]
	v_mfma_f32_16x16x32_bf16 v[34:37], v[172:175], v[188:191], v[34:37]
	v_mfma_f32_16x16x32_bf16 v[26:29], v[164:167], v[200:203], v[26:29]
	v_mfma_f32_16x16x32_bf16 v[18:21], v[172:175], v[200:203], v[18:21]
	v_mfma_f32_16x16x32_bf16 v[10:13], v[164:167], v[218:221], v[10:13]
	v_mfma_f32_16x16x32_bf16 v[2:5], v[172:175], v[218:221], v[2:5]
	s_setprio 0
	s_barrier
; #define PG8_STAGE(bufoff, gbase, voff) do { _Pragma("unroll") for (int _i = 0; _i < 2; ++_i) \
;         __builtin_amdgcn_global_load_lds((const unsigned*)((const char*)(gbase) + (voff)[_i]), (LAS unsigned*)(lds + (bufoff) + ldsw + _i * 8192), 16, 0, 0); } while (0)
; #define PG8_LDA(dst, b, h) do { _Pragma("unroll") for (int m = 0; m < 4; ++m) _Pragma("unroll") for (int k = 0; k < 2; ++k) dst[m][k] = *(const LAS f16x8*)(lds + PG8_SA(b, h) + aoff + m * 2048 + k * 1024); } while (0)
; #define PG8_LDB(dst, b, h) do { _Pragma("unroll") for (int n = 0; n < 2; ++n) _Pragma("unroll") for (int k = 0; k < 2; ++k) dst[n][k] = *(const LAS f16x8*)(lds + PG8_SB(b, h) + boff + n * 2048 + k * 1024); } while (0)
; #define PG8_MMA(ai, bj, At, Bt) do { __builtin_amdgcn_s_setprio(1); _Pragma("unroll") for (int m = 0; m < 4; ++m) _Pragma("unroll") for (int n = 0; n < 2; ++n) _Pragma("unroll") for (int k = 0; k < 2; ++k) \
;         acc[ai][bj][m][n] = mma16_<Epi::BF16>(Bt[n][k], At[m][k], acc[ai][bj][m][n]); __builtin_amdgcn_s_setprio(0); } while (0)
; #define PG8_WAIT_V(n) asm volatile("s_waitcnt vmcnt(" #n ")" ::: "memory")
; #define PG8_WAIT_L(n) asm volatile("s_waitcnt lgkmcnt(" #n ")" ::: "memory")
; #define PG8_BAR __builtin_amdgcn_s_barrier()
; #define PG8_SCHED __builtin_amdgcn_sched_barrier(0)
;     ...
;             PG8_LDB(B0, 1, 0); PG8_LDB(B1, 1, 1); PG8_SCHED; PG8_LDA(At, 1, 0); PG8_STAGE(PG8_SA(0, 1), a2 + hA, voffA);
;             PG8_WAIT_V(8); PG8_WAIT_L(0); PG8_BAR; PG8_MMA(0, 0, At, B0); PG8_MMA(0, 1, At, B1); PG8_BAR; PG8_SCHED;
;             PG8_LDA(At, 1, 1); PG8_STAGE(PG8_SB(1, 0), b3, voffB); PG8_STAGE(PG8_SB(1, 1), b3 + hB, voffB); PG8_STAGE(PG8_SA(1, 0), a3, voffA);
;             PG8_WAIT_V(8); PG8_WAIT_L(0); PG8_BAR; if (!cur.half) { PG8_MMA(1, 0, At, B0); PG8_MMA(1, 1, At, B1); } PG8_BAR; PG8_SCHED;
	s_add_i32 s54, 0, 0x18000
	s_add_i32 s55, 0, 0x1c000
	v_add_u32_e32 v156, s54, v141
	v_add_u32_e32 v172, s55, v141
	ds_read_b128 v[144:147], v156
	ds_read_b128 v[148:151], v156 offset:1024
	ds_read_b128 v[152:155], v156 offset:2048
	ds_read_b128 v[156:159], v156 offset:3072
	ds_read_b128 v[160:163], v172
	ds_read_b128 v[164:167], v172 offset:1024
	ds_read_b128 v[168:171], v172 offset:2048
	ds_read_b128 v[172:175], v172 offset:3072
	s_add_u32 s36, s36, 0x40000
	s_addc_u32 s37, s37, 0
	s_add_u32 s98, s36, 0xfffc0080
	s_addc_u32 s99, s37, -1
	s_mov_b32 m0, s43
	ds_read_b128 v[176:179], v143 offset:32768
	ds_read_b128 v[180:183], v143 offset:33792
	ds_read_b128 v[184:187], v143 offset:34816
	ds_read_b128 v[188:191], v143 offset:35840
	ds_read_b128 v[192:195], v143 offset:36864
	ds_read_b128 v[200:203], v143 offset:37888
	ds_read_b128 v[214:217], v143 offset:38912
	ds_read_b128 v[218:221], v143 offset:39936
	global_load_lds_dwordx4 v134, s[36:37]
	s_mov_b32 m0, s44
	s_nop 0
	global_load_lds_dwordx4 v132, s[36:37]
	s_waitcnt vmcnt(8) lgkmcnt(0)
	s_barrier
	s_setprio 1
	v_mfma_f32_16x16x32_bf16 v[126:129], v[144:147], v[176:179], v[126:129]
	v_mfma_f32_16x16x32_bf16 v[118:121], v[152:155], v[176:179], v[118:121]
	v_mfma_f32_16x16x32_bf16 v[110:113], v[144:147], v[184:187], v[110:113]
	v_mfma_f32_16x16x32_bf16 v[102:105], v[152:155], v[184:187], v[102:105]
	v_mfma_f32_16x16x32_bf16 v[94:97], v[144:147], v[192:195], v[94:97]
	v_mfma_f32_16x16x32_bf16 v[86:89], v[152:155], v[192:195], v[86:89]
	v_mfma_f32_16x16x32_bf16 v[78:81], v[144:147], v[214:217], v[78:81]
	v_mfma_f32_16x16x32_bf16 v[70:73], v[152:155], v[214:217], v[70:73]
	v_mfma_f32_16x16x32_bf16 v[126:129], v[148:151], v[180:183], v[126:129]
	v_mfma_f32_16x16x32_bf16 v[118:121], v[156:159], v[180:183], v[118:121]
	v_mfma_f32_16x16x32_bf16 v[110:113], v[148:151], v[188:191], v[110:113]
	v_mfma_f32_16x16x32_bf16 v[102:105], v[156:159], v[188:191], v[102:105]
	v_mfma_f32_16x16x32_bf16 v[94:97], v[148:151], v[200:203], v[94:97]
	v_mfma_f32_16x16x32_bf16 v[86:89], v[156:159], v[200:203], v[86:89]
	v_mfma_f32_16x16x32_bf16 v[78:81], v[148:151], v[218:221], v[78:81]
	v_mfma_f32_16x16x32_bf16 v[70:73], v[156:159], v[218:221], v[70:73]
	s_setprio 0
	s_setprio 1
	v_mfma_f32_16x16x32_bf16 v[122:125], v[160:163], v[176:179], v[122:125]
	v_mfma_f32_16x16x32_bf16 v[114:117], v[168:171], v[176:179], v[114:117]
	v_mfma_f32_16x16x32_bf16 v[106:109], v[160:163], v[184:187], v[106:109]
	v_mfma_f32_16x16x32_bf16 v[98:101], v[168:171], v[184:187], v[98:101]
	v_mfma_f32_16x16x32_bf16 v[90:93], v[160:163], v[192:195], v[90:93]
	v_mfma_f32_16x16x32_bf16 v[82:85], v[168:171], v[192:195], v[82:85]
	v_mfma_f32_16x16x32_bf16 v[74:77], v[160:163], v[214:217], v[74:77]
	v_mfma_f32_16x16x32_bf16 v[66:69], v[168:171], v[214:217], v[66:69]
	v_mfma_f32_16x16x32_bf16 v[122:125], v[164:167], v[180:183], v[122:125]
	v_mfma_f32_16x16x32_bf16 v[114:117], v[172:175], v[180:183], v[114:117]
	v_mfma_f32_16x16x32_bf16 v[106:109], v[164:167], v[188:191], v[106:109]
	v_mfma_f32_16x16x32_bf16 v[98:101], v[172:175], v[188:191], v[98:101]
	v_mfma_f32_16x16x32_bf16 v[90:93], v[164:167], v[200:203], v[90:93]
	v_mfma_f32_16x16x32_bf16 v[82:85], v[172:175], v[200:203], v[82:85]
	v_mfma_f32_16x16x32_bf16 v[74:77], v[164:167], v[218:221], v[74:77]
	v_mfma_f32_16x16x32_bf16 v[66:69], v[172:175], v[218:221], v[66:69]
	s_setprio 0
	s_barrier
	s_add_i32 s36, s54, s40
	s_add_u32 s34, s34, 0x80
	s_addc_u32 s35, s35, 0
	s_mov_b32 m0, s36
	ds_read_b128 v[176:179], v143 offset:49152
	ds_read_b128 v[180:183], v143 offset:50176
	ds_read_b128 v[184:187], v143 offset:51200
	ds_read_b128 v[188:191], v143 offset:52224
	ds_read_b128 v[192:195], v143 offset:53248
	ds_read_b128 v[200:203], v143 offset:54272
	ds_read_b128 v[214:217], v143 offset:55296
	ds_read_b128 v[218:221], v143 offset:56320
	global_load_lds_dwordx4 v0, s[34:35]
	s_add_i32 m0, s36, 0x2000
	s_add_i32 s36, s55, s40
	global_load_lds_dwordx4 v130, s[34:35]
	s_add_u32 s34, s34, 0x40000
	s_addc_u32 s35, s35, 0
	s_mov_b32 m0, s36
	s_nop 0
	global_load_lds_dwordx4 v0, s[34:35]
	s_add_i32 m0, s36, 0x2000
	s_nop 0
	global_load_lds_dwordx4 v130, s[34:35]
	s_mov_b32 m0, s45
	s_nop 0
	global_load_lds_dwordx4 v134, s[98:99]
	s_mov_b32 m0, s47
	s_nop 0
	global_load_lds_dwordx4 v132, s[98:99]
	s_waitcnt vmcnt(8) lgkmcnt(0)
	s_barrier
	s_setprio 1
	v_mfma_f32_16x16x32_bf16 v[62:65], v[144:147], v[176:179], v[62:65]
	v_mfma_f32_16x16x32_bf16 v[54:57], v[152:155], v[176:179], v[54:57]
	v_mfma_f32_16x16x32_bf16 v[46:49], v[144:147], v[184:187], v[46:49]
	v_mfma_f32_16x16x32_bf16 v[38:41], v[152:155], v[184:187], v[38:41]
	v_mfma_f32_16x16x32_bf16 v[30:33], v[144:147], v[192:195], v[30:33]
	v_mfma_f32_16x16x32_bf16 v[22:25], v[152:155], v[192:195], v[22:25]
	v_mfma_f32_16x16x32_bf16 v[14:17], v[144:147], v[214:217], v[14:17]
	v_mfma_f32_16x16x32_bf16 v[6:9], v[152:155], v[214:217], v[6:9]
	v_mfma_f32_16x16x32_bf16 v[62:65], v[148:151], v[180:183], v[62:65]
	v_mfma_f32_16x16x32_bf16 v[54:57], v[156:159], v[180:183], v[54:57]
	v_mfma_f32_16x16x32_bf16 v[46:49], v[148:151], v[188:191], v[46:49]
	v_mfma_f32_16x16x32_bf16 v[38:41], v[156:159], v[188:191], v[38:41]
	v_mfma_f32_16x16x32_bf16 v[30:33], v[148:151], v[200:203], v[30:33]
	v_mfma_f32_16x16x32_bf16 v[22:25], v[156:159], v[200:203], v[22:25]
	v_mfma_f32_16x16x32_bf16 v[14:17], v[148:151], v[218:221], v[14:17]
	v_mfma_f32_16x16x32_bf16 v[6:9], v[156:159], v[218:221], v[6:9]
	s_setprio 0
	s_setprio 1
	v_mfma_f32_16x16x32_bf16 v[58:61], v[160:163], v[176:179], v[58:61]
	v_mfma_f32_16x16x32_bf16 v[50:53], v[168:171], v[176:179], v[50:53]
	v_mfma_f32_16x16x32_bf16 v[42:45], v[160:163], v[184:187], v[42:45]
	v_mfma_f32_16x16x32_bf16 v[34:37], v[168:171], v[184:187], v[34:37]
	v_mfma_f32_16x16x32_bf16 v[26:29], v[160:163], v[192:195], v[26:29]
	v_mfma_f32_16x16x32_bf16 v[18:21], v[168:171], v[192:195], v[18:21]
	v_mfma_f32_16x16x32_bf16 v[10:13], v[160:163], v[214:217], v[10:13]
	v_mfma_f32_16x16x32_bf16 v[2:5], v[168:171], v[214:217], v[2:5]
	v_mfma_f32_16x16x32_bf16 v[58:61], v[164:167], v[180:183], v[58:61]
	v_mfma_f32_16x16x32_bf16 v[50:53], v[172:175], v[180:183], v[50:53]
	v_mfma_f32_16x16x32_bf16 v[42:45], v[164:167], v[188:191], v[42:45]
	v_mfma_f32_16x16x32_bf16 v[34:37], v[172:175], v[188:191], v[34:37]
	v_mfma_f32_16x16x32_bf16 v[26:29], v[164:167], v[200:203], v[26:29]
	v_mfma_f32_16x16x32_bf16 v[18:21], v[172:175], v[200:203], v[18:21]
	v_mfma_f32_16x16x32_bf16 v[10:13], v[164:167], v[218:221], v[10:13]
	v_mfma_f32_16x16x32_bf16 v[2:5], v[172:175], v[218:221], v[2:5]
	s_setprio 0
	s_barrier
	s_add_i32 s53, s53, 2
	s_add_u32 s30, s30, 0x100
	s_addc_u32 s31, s31, 0
	s_add_u32 s51, s51, 0x100
	s_addc_u32 s52, s52, 0
	s_cmp_gt_u32 s53, 13
	s_cbranch_scc0 .LBB0_1018
	s_and_b64 vcc, exec, s[10:11]
	s_cbranch_vccz .LBB0_1021
	s_barrier

; #define PG8_STAGE(bufoff, gbase, voff) do { _Pragma("unroll") for (int _i = 0; _i < 2; ++_i) \
;         __builtin_amdgcn_global_load_lds((const unsigned*)((const char*)(gbase) + (voff)[_i]), (LAS unsigned*)(lds + (bufoff) + ldsw + _i * 8192), 16, 0, 0); } while (0)
; #define PG8_LDA(dst, b, h) do { _Pragma("unroll") for (int m = 0; m < 4; ++m) _Pragma("unroll") for (int k = 0; k < 2; ++k) dst[m][k] = *(const LAS f16x8*)(lds + PG8_SA(b, h) + aoff + m * 2048 + k * 1024); } while (0)
; #define PG8_LDB(dst, b, h) do { _Pragma("unroll") for (int n = 0; n < 2; ++n) _Pragma("unroll") for (int k = 0; k < 2; ++k) dst[n][k] = *(const LAS f16x8*)(lds + PG8_SB(b, h) + boff + n * 2048 + k * 1024); } while (0)
; #define PG8_MMA(ai, bj, At, Bt) do { __builtin_amdgcn_s_setprio(1); _Pragma("unroll") for (int m = 0; m < 4; ++m) _Pragma("unroll") for (int n = 0; n < 2; ++n) _Pragma("unroll") for (int k = 0; k < 2; ++k) \
;         acc[ai][bj][m][n] = mma16_<Epi::BF16>(Bt[n][k], At[m][k], acc[ai][bj][m][n]); __builtin_amdgcn_s_setprio(0); } while (0)
; #define PG8_WAIT_V(n) asm volatile("s_waitcnt vmcnt(" #n ")" ::: "memory")
; #define PG8_WAIT_L(n) asm volatile("s_waitcnt lgkmcnt(" #n ")" ::: "memory")
; #define PG8_BAR __builtin_amdgcn_s_barrier()
; #define PG8_SCHED __builtin_amdgcn_sched_barrier(0)
;     ...
;             const bool last = (t == nt - 2);
;             const char* a1 = cA + (size_t)(t + 1) * kstep;
;             const char* a2 = last ? nA : cA + (size_t)(t + 2) * kstep; const char* b2 = last ? nB : cB + (size_t)(t + 2) * kstep;
;             const char* a3 = a2 + kstep; const char* b3 = b2 + kstep;
;             if constexpr (SP2) {
;             PG8_LDB(B0, 0, 0); PG8_LDB(B1, 0, 1); PG8_SCHED; PG8_LDA(At, 0, 0); PG8_STAGE(PG8_SA(1, 1), a1 + hA, voffA);
;             PG8_WAIT_V(8); PG8_WAIT_L(0); PG8_BAR; PG8_MMA(0, 0, At, B0); PG8_MMA(0, 1, At, B1); PG8_BAR; PG8_SCHED;
;             PG8_LDA(At, 0, 1); PG8_STAGE(PG8_SB(0, 0), b2, voffB); PG8_STAGE(PG8_SB(0, 1), b2 + hB, voffB); PG8_STAGE(PG8_SA(0, 0), a2, voffA);
;             PG8_WAIT_V(8); PG8_WAIT_L(0); PG8_BAR; if (!cur.half) { PG8_MMA(1, 0, At, B0); PG8_MMA(1, 1, At, B1); } PG8_BAR; PG8_SCHED;
.LBB0_1103:
	s_mov_b64 s[42:43], s[30:31]
	s_add_u32 s30, s42, 0x100
	s_addc_u32 s31, s43, 0
	s_add_i32 s29, 0, 0x10000
	s_cmp_eq_u32 s14, 40
	s_cselect_b32 s45, s25, s31
	s_cselect_b32 s44, s24, s30
	s_cselect_b32 s37, s27, s3
	s_cselect_b32 s36, s26, s2
	s_add_i32 s69, 0, 0x14000
	v_add_u32_e32 v130, s29, v243
	v_add_u32_e32 v142, s69, v243
	ds_read_b128 v[146:149], v130
	ds_read_b128 v[150:153], v130 offset:1024
	ds_read_b128 v[154:157], v130 offset:2048
	ds_read_b128 v[158:161], v130 offset:3072
	ds_read_b128 v[130:133], v142
	ds_read_b128 v[134:137], v142 offset:1024
	ds_read_b128 v[138:141], v142 offset:2048
	ds_read_b128 v[142:145], v142 offset:3072
	s_add_i32 m0, s53, 0xc000
	s_waitcnt lgkmcnt(0)
	ds_read_b128 v[162:165], v244
	ds_read_b128 v[166:169], v244 offset:1024
	ds_read_b128 v[170:173], v244 offset:2048
	ds_read_b128 v[174:177], v244 offset:3072
	ds_read_b128 v[178:181], v244 offset:4096
	ds_read_b128 v[182:185], v244 offset:5120
	ds_read_b128 v[186:189], v244 offset:6144
	ds_read_b128 v[190:193], v244 offset:7168
	global_load_lds_dwordx4 v222, s[42:43]
	s_add_i32 m0, s53, 0xe000
	s_nop 0
	global_load_lds_dwordx4 v224, s[42:43]
	s_waitcnt vmcnt(8) lgkmcnt(0)
	s_barrier
	s_setprio 1
	v_mfma_f32_16x16x32_bf16 v[126:129], v[146:149], v[162:165], v[126:129]
	v_mfma_f32_16x16x32_bf16 v[122:125], v[154:157], v[162:165], v[122:125]
	v_mfma_f32_16x16x32_bf16 v[118:121], v[146:149], v[170:173], v[118:121]
	v_mfma_f32_16x16x32_bf16 v[114:117], v[154:157], v[170:173], v[114:117]
	v_mfma_f32_16x16x32_bf16 v[110:113], v[146:149], v[178:181], v[110:113]
	v_mfma_f32_16x16x32_bf16 v[106:109], v[154:157], v[178:181], v[106:109]
	v_mfma_f32_16x16x32_bf16 v[102:105], v[146:149], v[186:189], v[102:105]
	v_mfma_f32_16x16x32_bf16 v[98:101], v[154:157], v[186:189], v[98:101]
	v_mfma_f32_16x16x32_bf16 v[126:129], v[150:153], v[166:169], v[126:129]
	v_mfma_f32_16x16x32_bf16 v[122:125], v[158:161], v[166:169], v[122:125]
	v_mfma_f32_16x16x32_bf16 v[118:121], v[150:153], v[174:177], v[118:121]
	v_mfma_f32_16x16x32_bf16 v[114:117], v[158:161], v[174:177], v[114:117]
	v_mfma_f32_16x16x32_bf16 v[110:113], v[150:153], v[182:185], v[110:113]
	v_mfma_f32_16x16x32_bf16 v[106:109], v[158:161], v[182:185], v[106:109]
	v_mfma_f32_16x16x32_bf16 v[102:105], v[150:153], v[190:193], v[102:105]
	v_mfma_f32_16x16x32_bf16 v[98:101], v[158:161], v[190:193], v[98:101]
	s_setprio 0
	s_setprio 1
	v_mfma_f32_16x16x32_bf16 v[78:81], v[130:133], v[162:165], v[78:81]
	v_mfma_f32_16x16x32_bf16 v[74:77], v[138:141], v[162:165], v[74:77]
	v_mfma_f32_16x16x32_bf16 v[62:65], v[130:133], v[170:173], v[62:65]
	v_mfma_f32_16x16x32_bf16 v[58:61], v[138:141], v[170:173], v[58:61]
	v_mfma_f32_16x16x32_bf16 v[46:49], v[130:133], v[178:181], v[46:49]
	v_mfma_f32_16x16x32_bf16 v[42:45], v[138:141], v[178:181], v[42:45]
	v_mfma_f32_16x16x32_bf16 v[38:41], v[130:133], v[186:189], v[38:41]
	v_mfma_f32_16x16x32_bf16 v[34:37], v[138:141], v[186:189], v[34:37]
	v_mfma_f32_16x16x32_bf16 v[78:81], v[134:137], v[166:169], v[78:81]
	v_mfma_f32_16x16x32_bf16 v[74:77], v[142:145], v[166:169], v[74:77]
	v_mfma_f32_16x16x32_bf16 v[62:65], v[134:137], v[174:177], v[62:65]
	v_mfma_f32_16x16x32_bf16 v[58:61], v[142:145], v[174:177], v[58:61]
	v_mfma_f32_16x16x32_bf16 v[46:49], v[134:137], v[182:185], v[46:49]
	v_mfma_f32_16x16x32_bf16 v[42:45], v[142:145], v[182:185], v[42:45]
	v_mfma_f32_16x16x32_bf16 v[38:41], v[134:137], v[190:193], v[38:41]
	v_mfma_f32_16x16x32_bf16 v[34:37], v[142:145], v[190:193], v[34:37]
	s_setprio 0
	s_barrier
	s_add_i32 s29, s29, s52
	s_mov_b32 m0, s29
	ds_read_b128 v[186:189], v244 offset:16384
	ds_read_b128 v[190:193], v244 offset:17408
	ds_read_b128 v[178:181], v244 offset:18432
	ds_read_b128 v[182:185], v244 offset:19456
	ds_read_b128 v[170:173], v244 offset:20480
	ds_read_b128 v[174:177], v244 offset:21504
	ds_read_b128 v[162:165], v244 offset:22528
	ds_read_b128 v[166:169], v244 offset:23552
	global_load_lds_dwordx4 v214, s[36:37]
	s_add_i32 m0, s29, 0x2000
	s_add_u32 s42, s36, 0xb0000
	s_addc_u32 s43, s37, 0
	s_add_i32 s29, s69, s52
	global_load_lds_dwordx4 v218, s[36:37]
	s_mov_b32 m0, s29
	s_nop 0
	global_load_lds_dwordx4 v214, s[42:43]
	s_add_i32 m0, s29, 0x2000
	s_nop 0
	global_load_lds_dwordx4 v218, s[42:43]
	s_mov_b32 m0, s53
	v_cndmask_b32_e64 v200, 0, 1, s[34:35]
	global_load_lds_dwordx4 v194, s[44:45]
	s_mov_b32 m0, s54
	v_cmp_ne_u32_e64 s[42:43], 1, v200
	global_load_lds_dwordx4 v216, s[44:45]
	s_waitcnt vmcnt(8) lgkmcnt(0)
	s_andn2_b64 vcc, exec, s[34:35]
	s_barrier
	s_cbranch_vccnz .LBB0_1105
	s_setprio 1
	v_mfma_f32_16x16x32_bf16 v[94:97], v[146:149], v[186:189], v[94:97]
	v_mfma_f32_16x16x32_bf16 v[90:93], v[154:157], v[186:189], v[90:93]
	v_mfma_f32_16x16x32_bf16 v[86:89], v[146:149], v[178:181], v[86:89]
	v_mfma_f32_16x16x32_bf16 v[82:85], v[154:157], v[178:181], v[82:85]
	v_mfma_f32_16x16x32_bf16 v[70:73], v[146:149], v[170:173], v[70:73]
	v_mfma_f32_16x16x32_bf16 v[66:69], v[154:157], v[170:173], v[66:69]
	v_mfma_f32_16x16x32_bf16 v[54:57], v[146:149], v[162:165], v[54:57]
	v_mfma_f32_16x16x32_bf16 v[50:53], v[154:157], v[162:165], v[50:53]
	v_mfma_f32_16x16x32_bf16 v[94:97], v[150:153], v[190:193], v[94:97]
	v_mfma_f32_16x16x32_bf16 v[90:93], v[158:161], v[190:193], v[90:93]
	v_mfma_f32_16x16x32_bf16 v[86:89], v[150:153], v[182:185], v[86:89]
	v_mfma_f32_16x16x32_bf16 v[82:85], v[158:161], v[182:185], v[82:85]
	v_mfma_f32_16x16x32_bf16 v[70:73], v[150:153], v[174:177], v[70:73]
	v_mfma_f32_16x16x32_bf16 v[66:69], v[158:161], v[174:177], v[66:69]
	v_mfma_f32_16x16x32_bf16 v[54:57], v[150:153], v[166:169], v[54:57]
	v_mfma_f32_16x16x32_bf16 v[50:53], v[158:161], v[166:169], v[50:53]
	s_setprio 0
	s_setprio 1
	v_mfma_f32_16x16x32_bf16 v[30:33], v[130:133], v[186:189], v[30:33]
	v_mfma_f32_16x16x32_bf16 v[26:29], v[138:141], v[186:189], v[26:29]
	v_mfma_f32_16x16x32_bf16 v[22:25], v[130:133], v[178:181], v[22:25]
	v_mfma_f32_16x16x32_bf16 v[18:21], v[138:141], v[178:181], v[18:21]
	v_mfma_f32_16x16x32_bf16 v[14:17], v[130:133], v[170:173], v[14:17]
	v_mfma_f32_16x16x32_bf16 v[10:13], v[138:141], v[170:173], v[10:13]
	v_mfma_f32_16x16x32_bf16 v[6:9], v[130:133], v[162:165], v[6:9]
	v_mfma_f32_16x16x32_bf16 v[2:5], v[138:141], v[162:165], v[2:5]
	v_mfma_f32_16x16x32_bf16 v[30:33], v[134:137], v[190:193], v[30:33]
	v_mfma_f32_16x16x32_bf16 v[26:29], v[142:145], v[190:193], v[26:29]
	v_mfma_f32_16x16x32_bf16 v[22:25], v[134:137], v[182:185], v[22:25]
	v_mfma_f32_16x16x32_bf16 v[18:21], v[142:145], v[182:185], v[18:21]
	v_mfma_f32_16x16x32_bf16 v[14:17], v[134:137], v[174:177], v[14:17]
	v_mfma_f32_16x16x32_bf16 v[10:13], v[142:145], v[174:177], v[10:13]
	v_mfma_f32_16x16x32_bf16 v[6:9], v[134:137], v[166:169], v[6:9]
	v_mfma_f32_16x16x32_bf16 v[2:5], v[142:145], v[166:169], v[2:5]
	s_setprio 0
; #define PG8_STAGE(bufoff, gbase, voff) do { _Pragma("unroll") for (int _i = 0; _i < 2; ++_i) \
;         __builtin_amdgcn_global_load_lds((const unsigned*)((const char*)(gbase) + (voff)[_i]), (LAS unsigned*)(lds + (bufoff) + ldsw + _i * 8192), 16, 0, 0); } while (0)
; #define PG8_LDA(dst, b, h) do { _Pragma("unroll") for (int m = 0; m < 4; ++m) _Pragma("unroll") for (int k = 0; k < 2; ++k) dst[m][k] = *(const LAS f16x8*)(lds + PG8_SA(b, h) + aoff + m * 2048 + k * 1024); } while (0)
; #define PG8_LDB(dst, b, h) do { _Pragma("unroll") for (int n = 0; n < 2; ++n) _Pragma("unroll") for (int k = 0; k < 2; ++k) dst[n][k] = *(const LAS f16x8*)(lds + PG8_SB(b, h) + boff + n * 2048 + k * 1024); } while (0)
; #define PG8_MMA(ai, bj, At, Bt) do { __builtin_amdgcn_s_setprio(1); _Pragma("unroll") for (int m = 0; m < 4; ++m) _Pragma("unroll") for (int n = 0; n < 2; ++n) _Pragma("unroll") for (int k = 0; k < 2; ++k) \
;         acc[ai][bj][m][n] = mma16_<Epi::BF16>(Bt[n][k], At[m][k], acc[ai][bj][m][n]); __builtin_amdgcn_s_setprio(0); } while (0)
; #define PG8_WAIT_V(n) asm volatile("s_waitcnt vmcnt(" #n ")" ::: "memory")
; #define PG8_WAIT_L(n) asm volatile("s_waitcnt lgkmcnt(" #n ")" ::: "memory")
; #define PG8_BAR __builtin_amdgcn_s_barrier()
; #define PG8_SCHED __builtin_amdgcn_sched_barrier(0)
;     ...
;             PG8_LDB(B0, 1, 0); PG8_LDB(B1, 1, 1); PG8_SCHED; PG8_LDA(At, 1, 0); PG8_STAGE(PG8_SA(0, 1), a2 + hA, voffA);
;             PG8_WAIT_V(8); PG8_WAIT_L(0); PG8_BAR; PG8_MMA(0, 0, At, B0); PG8_MMA(0, 1, At, B1); PG8_BAR; PG8_SCHED;
;             PG8_LDA(At, 1, 1); PG8_STAGE(PG8_SB(1, 0), b3, voffB); PG8_STAGE(PG8_SB(1, 1), b3 + hB, voffB); PG8_STAGE(PG8_SA(1, 0), a3, voffA);
;             PG8_WAIT_V(8); PG8_WAIT_L(0); PG8_BAR; if (!cur.half) { PG8_MMA(1, 0, At, B0); PG8_MMA(1, 1, At, B1); } PG8_BAR; PG8_SCHED;
.LBB0_1105:
	s_barrier
	s_add_i32 s29, 0, 0x18000
	s_add_i32 s69, 0, 0x1c000
	v_add_u32_e32 v130, s29, v243
	v_add_u32_e32 v142, s69, v243
	ds_read_b128 v[146:149], v130
	ds_read_b128 v[150:153], v130 offset:1024
	ds_read_b128 v[154:157], v130 offset:2048
	ds_read_b128 v[158:161], v130 offset:3072
	ds_read_b128 v[130:133], v142
	ds_read_b128 v[134:137], v142 offset:1024
	ds_read_b128 v[138:141], v142 offset:2048
	ds_read_b128 v[142:145], v142 offset:3072
	s_add_u32 s44, s44, 0xb0000
	s_addc_u32 s45, s45, 0
	s_add_u32 s98, s44, 0xfff50080
	s_addc_u32 s99, s45, -1
	s_mov_b32 m0, s55
	s_waitcnt lgkmcnt(0)
	ds_read_b128 v[162:165], v244 offset:32768
	ds_read_b128 v[166:169], v244 offset:33792
	ds_read_b128 v[170:173], v244 offset:34816
	ds_read_b128 v[174:177], v244 offset:35840
	ds_read_b128 v[178:181], v244 offset:36864
	ds_read_b128 v[182:185], v244 offset:37888
	ds_read_b128 v[186:189], v244 offset:38912
	ds_read_b128 v[190:193], v244 offset:39936
	global_load_lds_dwordx4 v194, s[44:45]
	s_mov_b32 m0, s56
	s_nop 0
	global_load_lds_dwordx4 v216, s[44:45]
	s_waitcnt vmcnt(8) lgkmcnt(0)
	s_barrier
	s_setprio 1
	v_mfma_f32_16x16x32_bf16 v[126:129], v[146:149], v[162:165], v[126:129]
	v_mfma_f32_16x16x32_bf16 v[122:125], v[154:157], v[162:165], v[122:125]
	v_mfma_f32_16x16x32_bf16 v[118:121], v[146:149], v[170:173], v[118:121]
	v_mfma_f32_16x16x32_bf16 v[114:117], v[154:157], v[170:173], v[114:117]
	v_mfma_f32_16x16x32_bf16 v[110:113], v[146:149], v[178:181], v[110:113]
	v_mfma_f32_16x16x32_bf16 v[106:109], v[154:157], v[178:181], v[106:109]
	v_mfma_f32_16x16x32_bf16 v[102:105], v[146:149], v[186:189], v[102:105]
	v_mfma_f32_16x16x32_bf16 v[98:101], v[154:157], v[186:189], v[98:101]
	v_mfma_f32_16x16x32_bf16 v[126:129], v[150:153], v[166:169], v[126:129]
	v_mfma_f32_16x16x32_bf16 v[122:125], v[158:161], v[166:169], v[122:125]
	v_mfma_f32_16x16x32_bf16 v[118:121], v[150:153], v[174:177], v[118:121]
	v_mfma_f32_16x16x32_bf16 v[114:117], v[158:161], v[174:177], v[114:117]
	v_mfma_f32_16x16x32_bf16 v[110:113], v[150:153], v[182:185], v[110:113]
	v_mfma_f32_16x16x32_bf16 v[106:109], v[158:161], v[182:185], v[106:109]
	v_mfma_f32_16x16x32_bf16 v[102:105], v[150:153], v[190:193], v[102:105]
	v_mfma_f32_16x16x32_bf16 v[98:101], v[158:161], v[190:193], v[98:101]
	s_setprio 0
	s_setprio 1
	v_mfma_f32_16x16x32_bf16 v[78:81], v[130:133], v[162:165], v[78:81]
	v_mfma_f32_16x16x32_bf16 v[74:77], v[138:141], v[162:165], v[74:77]
	v_mfma_f32_16x16x32_bf16 v[62:65], v[130:133], v[170:173], v[62:65]
	v_mfma_f32_16x16x32_bf16 v[58:61], v[138:141], v[170:173], v[58:61]
	v_mfma_f32_16x16x32_bf16 v[46:49], v[130:133], v[178:181], v[46:49]
	v_mfma_f32_16x16x32_bf16 v[42:45], v[138:141], v[178:181], v[42:45]
	v_mfma_f32_16x16x32_bf16 v[38:41], v[130:133], v[186:189], v[38:41]
	v_mfma_f32_16x16x32_bf16 v[34:37], v[138:141], v[186:189], v[34:37]
	v_mfma_f32_16x16x32_bf16 v[78:81], v[134:137], v[166:169], v[78:81]
	v_mfma_f32_16x16x32_bf16 v[74:77], v[142:145], v[166:169], v[74:77]
	v_mfma_f32_16x16x32_bf16 v[62:65], v[134:137], v[174:177], v[62:65]
	v_mfma_f32_16x16x32_bf16 v[58:61], v[142:145], v[174:177], v[58:61]
	v_mfma_f32_16x16x32_bf16 v[46:49], v[134:137], v[182:185], v[46:49]
	v_mfma_f32_16x16x32_bf16 v[42:45], v[142:145], v[182:185], v[42:45]
	v_mfma_f32_16x16x32_bf16 v[38:41], v[134:137], v[190:193], v[38:41]
	v_mfma_f32_16x16x32_bf16 v[34:37], v[142:145], v[190:193], v[34:37]
	s_setprio 0
	s_barrier
	s_add_i32 s29, s29, s52
	s_add_u32 s36, s36, 0x80
	s_addc_u32 s37, s37, 0
	s_mov_b32 m0, s29
	ds_read_b128 v[186:189], v244 offset:49152
	ds_read_b128 v[190:193], v244 offset:50176
	ds_read_b128 v[178:181], v244 offset:51200
	ds_read_b128 v[182:185], v244 offset:52224
	ds_read_b128 v[170:173], v244 offset:53248
	ds_read_b128 v[174:177], v244 offset:54272
	ds_read_b128 v[162:165], v244 offset:55296
	ds_read_b128 v[166:169], v244 offset:56320
	global_load_lds_dwordx4 v214, s[36:37]
	s_add_i32 m0, s29, 0x2000
	s_add_i32 s29, s69, s52
	global_load_lds_dwordx4 v218, s[36:37]
	s_add_u32 s36, s36, 0xb0000
	s_addc_u32 s37, s37, 0
	s_mov_b32 m0, s29
	s_and_b64 vcc, exec, s[42:43]
	global_load_lds_dwordx4 v214, s[36:37]
	s_add_i32 m0, s29, 0x2000
	s_nop 0
	global_load_lds_dwordx4 v218, s[36:37]
	s_mov_b32 m0, s59
	s_nop 0
	global_load_lds_dwordx4 v194, s[98:99]
	s_mov_b32 m0, s60
	s_nop 0
	global_load_lds_dwordx4 v216, s[98:99]
	s_waitcnt vmcnt(8) lgkmcnt(0)
	s_barrier
	s_cbranch_vccnz .LBB0_1102
	s_setprio 1
	v_mfma_f32_16x16x32_bf16 v[94:97], v[146:149], v[186:189], v[94:97]
	v_mfma_f32_16x16x32_bf16 v[90:93], v[154:157], v[186:189], v[90:93]
	v_mfma_f32_16x16x32_bf16 v[86:89], v[146:149], v[178:181], v[86:89]
	v_mfma_f32_16x16x32_bf16 v[82:85], v[154:157], v[178:181], v[82:85]
	v_mfma_f32_16x16x32_bf16 v[70:73], v[146:149], v[170:173], v[70:73]
	v_mfma_f32_16x16x32_bf16 v[66:69], v[154:157], v[170:173], v[66:69]
	v_mfma_f32_16x16x32_bf16 v[54:57], v[146:149], v[162:165], v[54:57]
	v_mfma_f32_16x16x32_bf16 v[50:53], v[154:157], v[162:165], v[50:53]
	v_mfma_f32_16x16x32_bf16 v[94:97], v[150:153], v[190:193], v[94:97]
	v_mfma_f32_16x16x32_bf16 v[90:93], v[158:161], v[190:193], v[90:93]
	v_mfma_f32_16x16x32_bf16 v[86:89], v[150:153], v[182:185], v[86:89]
	v_mfma_f32_16x16x32_bf16 v[82:85], v[158:161], v[182:185], v[82:85]
	v_mfma_f32_16x16x32_bf16 v[70:73], v[150:153], v[174:177], v[70:73]
	v_mfma_f32_16x16x32_bf16 v[66:69], v[158:161], v[174:177], v[66:69]
	v_mfma_f32_16x16x32_bf16 v[54:57], v[150:153], v[166:169], v[54:57]
	v_mfma_f32_16x16x32_bf16 v[50:53], v[158:161], v[166:169], v[50:53]
	s_setprio 0
	s_setprio 1
	v_mfma_f32_16x16x32_bf16 v[30:33], v[130:133], v[186:189], v[30:33]
	v_mfma_f32_16x16x32_bf16 v[26:29], v[138:141], v[186:189], v[26:29]
	v_mfma_f32_16x16x32_bf16 v[22:25], v[130:133], v[178:181], v[22:25]
	v_mfma_f32_16x16x32_bf16 v[18:21], v[138:141], v[178:181], v[18:21]
	v_mfma_f32_16x16x32_bf16 v[14:17], v[130:133], v[170:173], v[14:17]
	v_mfma_f32_16x16x32_bf16 v[10:13], v[138:141], v[170:173], v[10:13]
	v_mfma_f32_16x16x32_bf16 v[6:9], v[130:133], v[162:165], v[6:9]
	v_mfma_f32_16x16x32_bf16 v[2:5], v[138:141], v[162:165], v[2:5]
	v_mfma_f32_16x16x32_bf16 v[30:33], v[134:137], v[190:193], v[30:33]
	v_mfma_f32_16x16x32_bf16 v[26:29], v[142:145], v[190:193], v[26:29]
	v_mfma_f32_16x16x32_bf16 v[22:25], v[134:137], v[182:185], v[22:25]
	v_mfma_f32_16x16x32_bf16 v[18:21], v[142:145], v[182:185], v[18:21]
	v_mfma_f32_16x16x32_bf16 v[14:17], v[134:137], v[174:177], v[14:17]
	v_mfma_f32_16x16x32_bf16 v[10:13], v[142:145], v[174:177], v[10:13]
	v_mfma_f32_16x16x32_bf16 v[6:9], v[134:137], v[166:169], v[6:9]
	v_mfma_f32_16x16x32_bf16 v[2:5], v[142:145], v[166:169], v[2:5]
	s_setprio 0
	s_branch .LBB0_1102
